# v108 + nt hint on the hand LayerNorm residual-row loads (single-reader, last use before far reuse)
# speedup vs baseline: 1.0054x; 1.0020x over previous
.LBB0_359:
	s_or_b64 exec, exec, s[38:39]
	v_readlane_b32 s2, v250, 53
	s_cmp_lg_u32 s2, 3
	s_cselect_b64 s[44:45], -1, 0
	s_cmp_eq_u32 s2, 3
	s_mov_b64 s[38:39], -1
	s_waitcnt lgkmcnt(0)
	s_barrier
	s_cbranch_scc1 .LBB0_383
	v_and_b32_e32 v0, 63, v222
	v_readfirstlane_b32 s46, v222
	v_lshlrev_b32_e32 v1, 5, v0
	v_lshlrev_b32_e32 v2, 4, v0
	s_lshl_b32 s2, s42, 2
	v_readlane_b32 s48, v252, 22
	v_readlane_b32 s49, v252, 23
	v_readlane_b32 s50, v252, 24
	v_readlane_b32 s51, v252, 25
	s_nop 3
	s_lshr_b32 s46, s46, 6
	s_add_u32 s46, s46, s95
	s_add_u32 s48, s48, s2
	s_addc_u32 s49, s49, 0
	s_add_u32 s50, s50, s2
	s_addc_u32 s51, s51, 0
	global_load_dwordx4 v[4:7], v1, s[48:49]
	global_load_dwordx4 v[20:23], v1, s[50:51]
	global_load_dwordx4 v[8:11], v1, s[48:49] offset:16
	global_load_dwordx4 v[24:27], v1, s[50:51] offset:16
	global_load_dwordx4 v[12:15], v1, s[48:49] offset:2048
	global_load_dwordx4 v[28:31], v1, s[50:51] offset:2048
	global_load_dwordx4 v[16:19], v1, s[48:49] offset:2064
	global_load_dwordx4 v[32:35], v1, s[50:51] offset:2064
	s_add_u32 s36, s46, 0x0
	v_lshl_add_u32 v128, s36, 12, v1
	s_add_u32 s37, s46, 0x1000
	v_lshl_add_u32 v129, s37, 12, v1
	s_add_u32 s38, s46, 0x2000
	v_lshl_add_u32 v130, s38, 12, v1
	s_add_u32 s39, s46, 0x3000
	v_lshl_add_u32 v131, s39, 12, v1
	global_load_dwordx4 v[36:39], v128, s[64:65] nt
	global_load_dwordx4 v[40:43], v128, s[64:65] offset:16 nt
	global_load_dwordx4 v[44:47], v128, s[64:65] offset:2048 nt
	global_load_dwordx4 v[48:51], v128, s[64:65] offset:2064 nt
	global_load_dwordx4 v[52:55], v129, s[64:65] nt
	global_load_dwordx4 v[56:59], v129, s[64:65] offset:16 nt
	global_load_dwordx4 v[60:63], v129, s[64:65] offset:2048 nt
	global_load_dwordx4 v[64:67], v129, s[64:65] offset:2064 nt
	global_load_dwordx4 v[68:71], v130, s[64:65] nt
	global_load_dwordx4 v[72:75], v130, s[64:65] offset:16 nt
	global_load_dwordx4 v[76:79], v130, s[64:65] offset:2048 nt
	global_load_dwordx4 v[80:83], v130, s[64:65] offset:2064 nt
	global_load_dwordx4 v[84:87], v131, s[64:65] nt
	global_load_dwordx4 v[88:91], v131, s[64:65] offset:16 nt
	global_load_dwordx4 v[92:95], v131, s[64:65] offset:2048 nt
	global_load_dwordx4 v[96:99], v131, s[64:65] offset:2064 nt
	s_add_u32 s40, s46, 0x4000
	v_lshl_add_u32 v132, s40, 12, v1
	s_add_u32 s41, s46, 0x5000
	v_lshl_add_u32 v133, s41, 12, v1
	s_add_u32 s42, s46, 0x6000
	v_lshl_add_u32 v134, s42, 12, v1
	s_add_u32 s43, s46, 0x7000
	v_lshl_add_u32 v135, s43, 12, v1
	global_load_dwordx4 v[156:159], v132, s[64:65] nt
	global_load_dwordx4 v[160:163], v132, s[64:65] offset:16 nt
	global_load_dwordx4 v[164:167], v132, s[64:65] offset:2048 nt
	global_load_dwordx4 v[168:171], v132, s[64:65] offset:2064 nt
	global_load_dwordx4 v[172:175], v133, s[64:65] nt
	global_load_dwordx4 v[176:179], v133, s[64:65] offset:16 nt
	global_load_dwordx4 v[180:183], v133, s[64:65] offset:2048 nt
	global_load_dwordx4 v[184:187], v133, s[64:65] offset:2064 nt
	global_load_dwordx4 v[188:191], v134, s[64:65] nt
	global_load_dwordx4 v[192:195], v134, s[64:65] offset:16 nt
	global_load_dwordx4 v[196:199], v134, s[64:65] offset:2048 nt
	global_load_dwordx4 v[200:203], v134, s[64:65] offset:2064 nt
	global_load_dwordx4 v[204:207], v135, s[64:65] nt
	global_load_dwordx4 v[208:211], v135, s[64:65] offset:16 nt
	global_load_dwordx4 v[212:215], v135, s[64:65] offset:2048 nt
	global_load_dwordx4 v[216:219], v135, s[64:65] offset:2064 nt
	s_waitcnt vmcnt(16)
	v_pk_add_f32 v[108:109], v[36:37], v[38:39]
	v_pk_add_f32 v[110:111], v[40:41], v[42:43]
	v_pk_add_f32 v[112:113], v[44:45], v[46:47]
	v_pk_add_f32 v[114:115], v[48:49], v[50:51]
	v_pk_mul_f32 v[116:117], v[36:37], v[36:37]
	v_pk_fma_f32 v[116:117], v[38:39], v[38:39], v[116:117]
	v_pk_fma_f32 v[116:117], v[40:41], v[40:41], v[116:117]
	v_pk_fma_f32 v[116:117], v[42:43], v[42:43], v[116:117]
	v_pk_fma_f32 v[116:117], v[44:45], v[44:45], v[116:117]
	v_pk_fma_f32 v[116:117], v[46:47], v[46:47], v[116:117]
	v_pk_fma_f32 v[116:117], v[48:49], v[48:49], v[116:117]
	v_pk_fma_f32 v[116:117], v[50:51], v[50:51], v[116:117]
	v_pk_add_f32 v[108:109], v[108:109], v[110:111]
	v_pk_add_f32 v[112:113], v[112:113], v[114:115]
	v_pk_add_f32 v[108:109], v[108:109], v[112:113]
	v_add_f32_e32 v100, v108, v109
	v_add_f32_e32 v101, v116, v117
	v_pk_add_f32 v[108:109], v[52:53], v[54:55]
	v_pk_add_f32 v[110:111], v[56:57], v[58:59]
	v_pk_add_f32 v[112:113], v[60:61], v[62:63]
	v_pk_add_f32 v[114:115], v[64:65], v[66:67]
	v_pk_mul_f32 v[116:117], v[52:53], v[52:53]
	v_pk_fma_f32 v[116:117], v[54:55], v[54:55], v[116:117]
	v_pk_fma_f32 v[116:117], v[56:57], v[56:57], v[116:117]
	v_pk_fma_f32 v[116:117], v[58:59], v[58:59], v[116:117]
	v_pk_fma_f32 v[116:117], v[60:61], v[60:61], v[116:117]
	v_pk_fma_f32 v[116:117], v[62:63], v[62:63], v[116:117]
	v_pk_fma_f32 v[116:117], v[64:65], v[64:65], v[116:117]
	v_pk_fma_f32 v[116:117], v[66:67], v[66:67], v[116:117]
	v_pk_add_f32 v[108:109], v[108:109], v[110:111]
	v_pk_add_f32 v[112:113], v[112:113], v[114:115]
	v_pk_add_f32 v[108:109], v[108:109], v[112:113]
	v_add_f32_e32 v102, v108, v109
	v_add_f32_e32 v103, v116, v117
	v_pk_add_f32 v[108:109], v[68:69], v[70:71]
	v_pk_add_f32 v[110:111], v[72:73], v[74:75]
	v_pk_add_f32 v[112:113], v[76:77], v[78:79]
	v_pk_add_f32 v[114:115], v[80:81], v[82:83]
	v_pk_mul_f32 v[116:117], v[68:69], v[68:69]
	v_pk_fma_f32 v[116:117], v[70:71], v[70:71], v[116:117]
	v_pk_fma_f32 v[116:117], v[72:73], v[72:73], v[116:117]
	v_pk_fma_f32 v[116:117], v[74:75], v[74:75], v[116:117]
	v_pk_fma_f32 v[116:117], v[76:77], v[76:77], v[116:117]
	v_pk_fma_f32 v[116:117], v[78:79], v[78:79], v[116:117]
	v_pk_fma_f32 v[116:117], v[80:81], v[80:81], v[116:117]
	v_pk_fma_f32 v[116:117], v[82:83], v[82:83], v[116:117]
	v_pk_add_f32 v[108:109], v[108:109], v[110:111]
	v_pk_add_f32 v[112:113], v[112:113], v[114:115]
	v_pk_add_f32 v[108:109], v[108:109], v[112:113]
	v_add_f32_e32 v104, v108, v109
	v_add_f32_e32 v105, v116, v117
	v_pk_add_f32 v[108:109], v[84:85], v[86:87]
	v_pk_add_f32 v[110:111], v[88:89], v[90:91]
	v_pk_add_f32 v[112:113], v[92:93], v[94:95]
	v_pk_add_f32 v[114:115], v[96:97], v[98:99]
	v_pk_mul_f32 v[116:117], v[84:85], v[84:85]
	v_pk_fma_f32 v[116:117], v[86:87], v[86:87], v[116:117]
	v_pk_fma_f32 v[116:117], v[88:89], v[88:89], v[116:117]
	v_pk_fma_f32 v[116:117], v[90:91], v[90:91], v[116:117]
	v_pk_fma_f32 v[116:117], v[92:93], v[92:93], v[116:117]
	v_pk_fma_f32 v[116:117], v[94:95], v[94:95], v[116:117]
	v_pk_fma_f32 v[116:117], v[96:97], v[96:97], v[116:117]
	v_pk_fma_f32 v[116:117], v[98:99], v[98:99], v[116:117]
	v_pk_add_f32 v[108:109], v[108:109], v[110:111]
	v_pk_add_f32 v[112:113], v[112:113], v[114:115]
	v_pk_add_f32 v[108:109], v[108:109], v[112:113]
	v_add_f32_e32 v106, v108, v109
	v_add_f32_e32 v107, v116, v117
	v_add_f32_dpp v100, v100, v100 quad_perm:[1,0,3,2] row_mask:0xf bank_mask:0xf
	v_add_f32_dpp v101, v101, v101 quad_perm:[1,0,3,2] row_mask:0xf bank_mask:0xf
	v_add_f32_dpp v102, v102, v102 quad_perm:[1,0,3,2] row_mask:0xf bank_mask:0xf
	v_add_f32_dpp v103, v103, v103 quad_perm:[1,0,3,2] row_mask:0xf bank_mask:0xf
	v_add_f32_dpp v104, v104, v104 quad_perm:[1,0,3,2] row_mask:0xf bank_mask:0xf
	v_add_f32_dpp v105, v105, v105 quad_perm:[1,0,3,2] row_mask:0xf bank_mask:0xf
	v_add_f32_dpp v106, v106, v106 quad_perm:[1,0,3,2] row_mask:0xf bank_mask:0xf
	v_add_f32_dpp v107, v107, v107 quad_perm:[1,0,3,2] row_mask:0xf bank_mask:0xf
	v_add_f32_dpp v100, v100, v100 quad_perm:[2,3,0,1] row_mask:0xf bank_mask:0xf
	v_add_f32_dpp v101, v101, v101 quad_perm:[2,3,0,1] row_mask:0xf bank_mask:0xf
	v_add_f32_dpp v102, v102, v102 quad_perm:[2,3,0,1] row_mask:0xf bank_mask:0xf
	v_add_f32_dpp v103, v103, v103 quad_perm:[2,3,0,1] row_mask:0xf bank_mask:0xf
	v_add_f32_dpp v104, v104, v104 quad_perm:[2,3,0,1] row_mask:0xf bank_mask:0xf
	v_add_f32_dpp v105, v105, v105 quad_perm:[2,3,0,1] row_mask:0xf bank_mask:0xf
	v_add_f32_dpp v106, v106, v106 quad_perm:[2,3,0,1] row_mask:0xf bank_mask:0xf
	v_add_f32_dpp v107, v107, v107 quad_perm:[2,3,0,1] row_mask:0xf bank_mask:0xf
	v_add_f32_dpp v100, v100, v100 row_half_mirror row_mask:0xf bank_mask:0xf
	v_add_f32_dpp v101, v101, v101 row_half_mirror row_mask:0xf bank_mask:0xf
	v_add_f32_dpp v102, v102, v102 row_half_mirror row_mask:0xf bank_mask:0xf
	v_add_f32_dpp v103, v103, v103 row_half_mirror row_mask:0xf bank_mask:0xf
	v_add_f32_dpp v104, v104, v104 row_half_mirror row_mask:0xf bank_mask:0xf
	v_add_f32_dpp v105, v105, v105 row_half_mirror row_mask:0xf bank_mask:0xf
	v_add_f32_dpp v106, v106, v106 row_half_mirror row_mask:0xf bank_mask:0xf
	v_add_f32_dpp v107, v107, v107 row_half_mirror row_mask:0xf bank_mask:0xf
	v_add_f32_dpp v100, v100, v100 row_mirror row_mask:0xf bank_mask:0xf
	v_add_f32_dpp v101, v101, v101 row_mirror row_mask:0xf bank_mask:0xf
	v_add_f32_dpp v102, v102, v102 row_mirror row_mask:0xf bank_mask:0xf
	v_add_f32_dpp v103, v103, v103 row_mirror row_mask:0xf bank_mask:0xf
	v_add_f32_dpp v104, v104, v104 row_mirror row_mask:0xf bank_mask:0xf
	v_add_f32_dpp v105, v105, v105 row_mirror row_mask:0xf bank_mask:0xf
	v_add_f32_dpp v106, v106, v106 row_mirror row_mask:0xf bank_mask:0xf
	v_add_f32_dpp v107, v107, v107 row_mirror row_mask:0xf bank_mask:0xf
	v_mov_b32_e32 v108, v100
	v_mov_b32_e32 v109, v101
	v_mov_b32_e32 v110, v102
	v_mov_b32_e32 v111, v103
	v_mov_b32_e32 v112, v104
	v_mov_b32_e32 v113, v105
	v_mov_b32_e32 v114, v106
	v_mov_b32_e32 v115, v107
	s_nop 1
	v_permlane16_swap_b32_e32 v108, v100
	v_permlane16_swap_b32_e32 v109, v101
	v_permlane16_swap_b32_e32 v110, v102
	v_permlane16_swap_b32_e32 v111, v103
	v_permlane16_swap_b32_e32 v112, v104
	v_permlane16_swap_b32_e32 v113, v105
	v_permlane16_swap_b32_e32 v114, v106
	v_permlane16_swap_b32_e32 v115, v107
	v_add_f32_e32 v100, v100, v108
	v_add_f32_e32 v101, v101, v109
	v_add_f32_e32 v102, v102, v110
	v_add_f32_e32 v103, v103, v111
	v_add_f32_e32 v104, v104, v112
	v_add_f32_e32 v105, v105, v113
	v_add_f32_e32 v106, v106, v114
	v_add_f32_e32 v107, v107, v115
	v_mov_b32_e32 v108, v100
	v_mov_b32_e32 v109, v101
	v_mov_b32_e32 v110, v102
	v_mov_b32_e32 v111, v103
	v_mov_b32_e32 v112, v104
	v_mov_b32_e32 v113, v105
	v_mov_b32_e32 v114, v106
	v_mov_b32_e32 v115, v107
	s_nop 1
	v_permlane32_swap_b32_e32 v108, v100
	v_permlane32_swap_b32_e32 v109, v101
	v_permlane32_swap_b32_e32 v110, v102
	v_permlane32_swap_b32_e32 v111, v103
	v_permlane32_swap_b32_e32 v112, v104
	v_permlane32_swap_b32_e32 v113, v105
	v_permlane32_swap_b32_e32 v114, v106
	v_permlane32_swap_b32_e32 v115, v107
	v_add_f32_e32 v100, v100, v108
	v_add_f32_e32 v101, v101, v109
	v_add_f32_e32 v102, v102, v110
	v_add_f32_e32 v103, v103, v111
	v_add_f32_e32 v104, v104, v112
	v_add_f32_e32 v105, v105, v113
	v_add_f32_e32 v106, v106, v114
	v_add_f32_e32 v107, v107, v115
	v_mul_f32_e32 v230, 0x3a800000, v100
	v_mul_f32_e32 v116, 0x3a800000, v101
	v_fma_f32 v116, -v230, v230, v116
	v_max_f32_e32 v116, 0, v116
	v_add_f32_e32 v116, 0x3727c5ac, v116
	v_mul_f32_e32 v232, 0x3a800000, v102
	v_mul_f32_e32 v118, 0x3a800000, v103
	v_fma_f32 v118, -v232, v232, v118
	v_max_f32_e32 v118, 0, v118
	v_add_f32_e32 v118, 0x3727c5ac, v118
	v_mul_f32_e32 v234, 0x3a800000, v104
	v_mul_f32_e32 v120, 0x3a800000, v105
	v_fma_f32 v120, -v234, v234, v120
	v_max_f32_e32 v120, 0, v120
	v_add_f32_e32 v120, 0x3727c5ac, v120
	v_mul_f32_e32 v236, 0x3a800000, v106
	v_mul_f32_e32 v122, 0x3a800000, v107
	v_fma_f32 v122, -v236, v236, v122
	v_max_f32_e32 v122, 0, v122
	v_add_f32_e32 v122, 0x3727c5ac, v122
	v_rsq_f32_e32 v117, v116
	v_rsq_f32_e32 v119, v118
	v_rsq_f32_e32 v121, v120
	v_rsq_f32_e32 v123, v122
	s_nop 0
	v_mul_f32_e32 v124, v116, v117
	v_mul_f32_e32 v124, v124, v117
	v_fmaak_f32 v124, -0.5, v124, 0x3fc00000
	v_mul_f32_e32 v231, v117, v124
	v_mul_f32_e32 v125, v118, v119
	v_mul_f32_e32 v125, v125, v119
	v_fmaak_f32 v125, -0.5, v125, 0x3fc00000
	v_mul_f32_e32 v233, v119, v125
	v_mul_f32_e32 v126, v120, v121
	v_mul_f32_e32 v126, v126, v121
	v_fmaak_f32 v126, -0.5, v126, 0x3fc00000
	v_mul_f32_e32 v235, v121, v126
	v_mul_f32_e32 v127, v122, v123
	v_mul_f32_e32 v127, v127, v123
	v_fmaak_f32 v127, -0.5, v127, 0x3fc00000
	v_mul_f32_e32 v237, v123, v127
	v_pk_add_f32 v[36:37], v[36:37], v[230:231] op_sel_hi:[1,0] neg_lo:[0,1] neg_hi:[0,1]
	v_pk_add_f32 v[38:39], v[38:39], v[230:231] op_sel_hi:[1,0] neg_lo:[0,1] neg_hi:[0,1]
	v_pk_add_f32 v[40:41], v[40:41], v[230:231] op_sel_hi:[1,0] neg_lo:[0,1] neg_hi:[0,1]
	v_pk_add_f32 v[42:43], v[42:43], v[230:231] op_sel_hi:[1,0] neg_lo:[0,1] neg_hi:[0,1]
	v_pk_add_f32 v[44:45], v[44:45], v[230:231] op_sel_hi:[1,0] neg_lo:[0,1] neg_hi:[0,1]
	v_pk_add_f32 v[46:47], v[46:47], v[230:231] op_sel_hi:[1,0] neg_lo:[0,1] neg_hi:[0,1]
	v_pk_add_f32 v[48:49], v[48:49], v[230:231] op_sel_hi:[1,0] neg_lo:[0,1] neg_hi:[0,1]
	v_pk_add_f32 v[50:51], v[50:51], v[230:231] op_sel_hi:[1,0] neg_lo:[0,1] neg_hi:[0,1]
	v_pk_mul_f32 v[36:37], v[36:37], v[230:231] op_sel:[0,1] op_sel_hi:[1,1]
	v_pk_mul_f32 v[38:39], v[38:39], v[230:231] op_sel:[0,1] op_sel_hi:[1,1]
	v_pk_mul_f32 v[40:41], v[40:41], v[230:231] op_sel:[0,1] op_sel_hi:[1,1]
	v_pk_mul_f32 v[42:43], v[42:43], v[230:231] op_sel:[0,1] op_sel_hi:[1,1]
	v_pk_mul_f32 v[44:45], v[44:45], v[230:231] op_sel:[0,1] op_sel_hi:[1,1]
	v_pk_mul_f32 v[46:47], v[46:47], v[230:231] op_sel:[0,1] op_sel_hi:[1,1]
	v_pk_mul_f32 v[48:49], v[48:49], v[230:231] op_sel:[0,1] op_sel_hi:[1,1]
	v_pk_mul_f32 v[50:51], v[50:51], v[230:231] op_sel:[0,1] op_sel_hi:[1,1]
	v_pk_fma_f32 v[36:37], v[4:5], v[36:37], v[20:21]
	v_pk_fma_f32 v[38:39], v[6:7], v[38:39], v[22:23]
	v_pk_fma_f32 v[40:41], v[8:9], v[40:41], v[24:25]
	v_pk_fma_f32 v[42:43], v[10:11], v[42:43], v[26:27]
	v_pk_fma_f32 v[44:45], v[12:13], v[44:45], v[28:29]
	v_pk_fma_f32 v[46:47], v[14:15], v[46:47], v[30:31]
	v_pk_fma_f32 v[48:49], v[16:17], v[48:49], v[32:33]
	v_pk_fma_f32 v[50:51], v[18:19], v[50:51], v[34:35]
	v_cvt_pk_bf16_f32 v36, v36, v37
	v_cvt_pk_bf16_f32 v37, v38, v39
	v_cvt_pk_bf16_f32 v38, v40, v41
	v_cvt_pk_bf16_f32 v39, v42, v43
	v_cvt_pk_bf16_f32 v44, v44, v45
	v_cvt_pk_bf16_f32 v45, v46, v47
	v_cvt_pk_bf16_f32 v46, v48, v49
	v_cvt_pk_bf16_f32 v47, v50, v51
	v_lshl_add_u32 v3, s36, 11, v2
	global_store_dwordx4 v3, v[36:39], s[96:97] sc1
	global_store_dwordx4 v3, v[44:47], s[96:97] offset:1024 sc1
	v_pk_add_f32 v[52:53], v[52:53], v[232:233] op_sel_hi:[1,0] neg_lo:[0,1] neg_hi:[0,1]
	v_pk_add_f32 v[54:55], v[54:55], v[232:233] op_sel_hi:[1,0] neg_lo:[0,1] neg_hi:[0,1]
	v_pk_add_f32 v[56:57], v[56:57], v[232:233] op_sel_hi:[1,0] neg_lo:[0,1] neg_hi:[0,1]
	v_pk_add_f32 v[58:59], v[58:59], v[232:233] op_sel_hi:[1,0] neg_lo:[0,1] neg_hi:[0,1]
	v_pk_add_f32 v[60:61], v[60:61], v[232:233] op_sel_hi:[1,0] neg_lo:[0,1] neg_hi:[0,1]
	v_pk_add_f32 v[62:63], v[62:63], v[232:233] op_sel_hi:[1,0] neg_lo:[0,1] neg_hi:[0,1]
	v_pk_add_f32 v[64:65], v[64:65], v[232:233] op_sel_hi:[1,0] neg_lo:[0,1] neg_hi:[0,1]
	v_pk_add_f32 v[66:67], v[66:67], v[232:233] op_sel_hi:[1,0] neg_lo:[0,1] neg_hi:[0,1]
	v_pk_mul_f32 v[52:53], v[52:53], v[232:233] op_sel:[0,1] op_sel_hi:[1,1]
	v_pk_mul_f32 v[54:55], v[54:55], v[232:233] op_sel:[0,1] op_sel_hi:[1,1]
	v_pk_mul_f32 v[56:57], v[56:57], v[232:233] op_sel:[0,1] op_sel_hi:[1,1]
	v_pk_mul_f32 v[58:59], v[58:59], v[232:233] op_sel:[0,1] op_sel_hi:[1,1]
	v_pk_mul_f32 v[60:61], v[60:61], v[232:233] op_sel:[0,1] op_sel_hi:[1,1]
	v_pk_mul_f32 v[62:63], v[62:63], v[232:233] op_sel:[0,1] op_sel_hi:[1,1]
	v_pk_mul_f32 v[64:65], v[64:65], v[232:233] op_sel:[0,1] op_sel_hi:[1,1]
	v_pk_mul_f32 v[66:67], v[66:67], v[232:233] op_sel:[0,1] op_sel_hi:[1,1]
	v_pk_fma_f32 v[52:53], v[4:5], v[52:53], v[20:21]
	v_pk_fma_f32 v[54:55], v[6:7], v[54:55], v[22:23]
	v_pk_fma_f32 v[56:57], v[8:9], v[56:57], v[24:25]
	v_pk_fma_f32 v[58:59], v[10:11], v[58:59], v[26:27]
	v_pk_fma_f32 v[60:61], v[12:13], v[60:61], v[28:29]
	v_pk_fma_f32 v[62:63], v[14:15], v[62:63], v[30:31]
	v_pk_fma_f32 v[64:65], v[16:17], v[64:65], v[32:33]
	v_pk_fma_f32 v[66:67], v[18:19], v[66:67], v[34:35]
	v_cvt_pk_bf16_f32 v52, v52, v53
	v_cvt_pk_bf16_f32 v53, v54, v55
	v_cvt_pk_bf16_f32 v54, v56, v57
	v_cvt_pk_bf16_f32 v55, v58, v59
	v_cvt_pk_bf16_f32 v60, v60, v61
	v_cvt_pk_bf16_f32 v61, v62, v63
	v_cvt_pk_bf16_f32 v62, v64, v65
	v_cvt_pk_bf16_f32 v63, v66, v67
	v_lshl_add_u32 v3, s37, 11, v2
	global_store_dwordx4 v3, v[52:55], s[96:97] sc1
	global_store_dwordx4 v3, v[60:63], s[96:97] offset:1024 sc1
	v_pk_add_f32 v[68:69], v[68:69], v[234:235] op_sel_hi:[1,0] neg_lo:[0,1] neg_hi:[0,1]
	v_pk_add_f32 v[70:71], v[70:71], v[234:235] op_sel_hi:[1,0] neg_lo:[0,1] neg_hi:[0,1]
	v_pk_add_f32 v[72:73], v[72:73], v[234:235] op_sel_hi:[1,0] neg_lo:[0,1] neg_hi:[0,1]
	v_pk_add_f32 v[74:75], v[74:75], v[234:235] op_sel_hi:[1,0] neg_lo:[0,1] neg_hi:[0,1]
	v_pk_add_f32 v[76:77], v[76:77], v[234:235] op_sel_hi:[1,0] neg_lo:[0,1] neg_hi:[0,1]
	v_pk_add_f32 v[78:79], v[78:79], v[234:235] op_sel_hi:[1,0] neg_lo:[0,1] neg_hi:[0,1]
	v_pk_add_f32 v[80:81], v[80:81], v[234:235] op_sel_hi:[1,0] neg_lo:[0,1] neg_hi:[0,1]
	v_pk_add_f32 v[82:83], v[82:83], v[234:235] op_sel_hi:[1,0] neg_lo:[0,1] neg_hi:[0,1]
	v_pk_mul_f32 v[68:69], v[68:69], v[234:235] op_sel:[0,1] op_sel_hi:[1,1]
	v_pk_mul_f32 v[70:71], v[70:71], v[234:235] op_sel:[0,1] op_sel_hi:[1,1]
	v_pk_mul_f32 v[72:73], v[72:73], v[234:235] op_sel:[0,1] op_sel_hi:[1,1]
	v_pk_mul_f32 v[74:75], v[74:75], v[234:235] op_sel:[0,1] op_sel_hi:[1,1]
	v_pk_mul_f32 v[76:77], v[76:77], v[234:235] op_sel:[0,1] op_sel_hi:[1,1]
	v_pk_mul_f32 v[78:79], v[78:79], v[234:235] op_sel:[0,1] op_sel_hi:[1,1]
	v_pk_mul_f32 v[80:81], v[80:81], v[234:235] op_sel:[0,1] op_sel_hi:[1,1]
	v_pk_mul_f32 v[82:83], v[82:83], v[234:235] op_sel:[0,1] op_sel_hi:[1,1]
	v_pk_fma_f32 v[68:69], v[4:5], v[68:69], v[20:21]
	v_pk_fma_f32 v[70:71], v[6:7], v[70:71], v[22:23]
	v_pk_fma_f32 v[72:73], v[8:9], v[72:73], v[24:25]
	v_pk_fma_f32 v[74:75], v[10:11], v[74:75], v[26:27]
	v_pk_fma_f32 v[76:77], v[12:13], v[76:77], v[28:29]
	v_pk_fma_f32 v[78:79], v[14:15], v[78:79], v[30:31]
	v_pk_fma_f32 v[80:81], v[16:17], v[80:81], v[32:33]
	v_pk_fma_f32 v[82:83], v[18:19], v[82:83], v[34:35]
	v_cvt_pk_bf16_f32 v68, v68, v69
	v_cvt_pk_bf16_f32 v69, v70, v71
	v_cvt_pk_bf16_f32 v70, v72, v73
	v_cvt_pk_bf16_f32 v71, v74, v75
	v_cvt_pk_bf16_f32 v76, v76, v77
	v_cvt_pk_bf16_f32 v77, v78, v79
	v_cvt_pk_bf16_f32 v78, v80, v81
	v_cvt_pk_bf16_f32 v79, v82, v83
	v_lshl_add_u32 v3, s38, 11, v2
	global_store_dwordx4 v3, v[68:71], s[96:97] sc1
	global_store_dwordx4 v3, v[76:79], s[96:97] offset:1024 sc1
	v_pk_add_f32 v[84:85], v[84:85], v[236:237] op_sel_hi:[1,0] neg_lo:[0,1] neg_hi:[0,1]
	v_pk_add_f32 v[86:87], v[86:87], v[236:237] op_sel_hi:[1,0] neg_lo:[0,1] neg_hi:[0,1]
	v_pk_add_f32 v[88:89], v[88:89], v[236:237] op_sel_hi:[1,0] neg_lo:[0,1] neg_hi:[0,1]
	v_pk_add_f32 v[90:91], v[90:91], v[236:237] op_sel_hi:[1,0] neg_lo:[0,1] neg_hi:[0,1]
	v_pk_add_f32 v[92:93], v[92:93], v[236:237] op_sel_hi:[1,0] neg_lo:[0,1] neg_hi:[0,1]
	v_pk_add_f32 v[94:95], v[94:95], v[236:237] op_sel_hi:[1,0] neg_lo:[0,1] neg_hi:[0,1]
	v_pk_add_f32 v[96:97], v[96:97], v[236:237] op_sel_hi:[1,0] neg_lo:[0,1] neg_hi:[0,1]
	v_pk_add_f32 v[98:99], v[98:99], v[236:237] op_sel_hi:[1,0] neg_lo:[0,1] neg_hi:[0,1]
	v_pk_mul_f32 v[84:85], v[84:85], v[236:237] op_sel:[0,1] op_sel_hi:[1,1]
	v_pk_mul_f32 v[86:87], v[86:87], v[236:237] op_sel:[0,1] op_sel_hi:[1,1]
	v_pk_mul_f32 v[88:89], v[88:89], v[236:237] op_sel:[0,1] op_sel_hi:[1,1]
	v_pk_mul_f32 v[90:91], v[90:91], v[236:237] op_sel:[0,1] op_sel_hi:[1,1]
	v_pk_mul_f32 v[92:93], v[92:93], v[236:237] op_sel:[0,1] op_sel_hi:[1,1]
	v_pk_mul_f32 v[94:95], v[94:95], v[236:237] op_sel:[0,1] op_sel_hi:[1,1]
	v_pk_mul_f32 v[96:97], v[96:97], v[236:237] op_sel:[0,1] op_sel_hi:[1,1]
	v_pk_mul_f32 v[98:99], v[98:99], v[236:237] op_sel:[0,1] op_sel_hi:[1,1]
	v_pk_fma_f32 v[84:85], v[4:5], v[84:85], v[20:21]
	v_pk_fma_f32 v[86:87], v[6:7], v[86:87], v[22:23]
	v_pk_fma_f32 v[88:89], v[8:9], v[88:89], v[24:25]
	v_pk_fma_f32 v[90:91], v[10:11], v[90:91], v[26:27]
	v_pk_fma_f32 v[92:93], v[12:13], v[92:93], v[28:29]
	v_pk_fma_f32 v[94:95], v[14:15], v[94:95], v[30:31]
	v_pk_fma_f32 v[96:97], v[16:17], v[96:97], v[32:33]
	v_pk_fma_f32 v[98:99], v[18:19], v[98:99], v[34:35]
	v_cvt_pk_bf16_f32 v84, v84, v85
	v_cvt_pk_bf16_f32 v85, v86, v87
	v_cvt_pk_bf16_f32 v86, v88, v89
	v_cvt_pk_bf16_f32 v87, v90, v91
	v_cvt_pk_bf16_f32 v92, v92, v93
	v_cvt_pk_bf16_f32 v93, v94, v95
	v_cvt_pk_bf16_f32 v94, v96, v97
	v_cvt_pk_bf16_f32 v95, v98, v99
	v_lshl_add_u32 v3, s39, 11, v2
	global_store_dwordx4 v3, v[84:87], s[96:97] sc1
	global_store_dwordx4 v3, v[92:95], s[96:97] offset:1024 sc1
	s_mov_b64 s[52:53], exec
	s_mov_b64 exec, 1
	v_mov_b32_e32 v3, s36
	v_lshlrev_b32_e32 v3, 3, v3
	global_store_dwordx2 v3, v[230:231], s[92:93] sc1
	v_mov_b32_e32 v3, s37
	v_lshlrev_b32_e32 v3, 3, v3
	global_store_dwordx2 v3, v[232:233], s[92:93] sc1
	v_mov_b32_e32 v3, s38
	v_lshlrev_b32_e32 v3, 3, v3
	global_store_dwordx2 v3, v[234:235], s[92:93] sc1
	v_mov_b32_e32 v3, s39
	v_lshlrev_b32_e32 v3, 3, v3
	global_store_dwordx2 v3, v[236:237], s[92:93] sc1
	s_mov_b64 exec, s[52:53]
	s_add_u32 s36, s46, 0x800
	v_lshl_add_u32 v128, s36, 12, v1
	s_add_u32 s37, s46, 0x1800
	v_lshl_add_u32 v129, s37, 12, v1
	s_add_u32 s38, s46, 0x2800
	v_lshl_add_u32 v130, s38, 12, v1
	s_add_u32 s39, s46, 0x3800
	v_lshl_add_u32 v131, s39, 12, v1
	global_load_dwordx4 v[36:39], v128, s[64:65] nt
	global_load_dwordx4 v[40:43], v128, s[64:65] offset:16 nt
	global_load_dwordx4 v[44:47], v128, s[64:65] offset:2048 nt
	global_load_dwordx4 v[48:51], v128, s[64:65] offset:2064 nt
	global_load_dwordx4 v[52:55], v129, s[64:65] nt
	global_load_dwordx4 v[56:59], v129, s[64:65] offset:16 nt
	global_load_dwordx4 v[60:63], v129, s[64:65] offset:2048 nt
	global_load_dwordx4 v[64:67], v129, s[64:65] offset:2064 nt
	global_load_dwordx4 v[68:71], v130, s[64:65] nt
	global_load_dwordx4 v[72:75], v130, s[64:65] offset:16 nt
	global_load_dwordx4 v[76:79], v130, s[64:65] offset:2048 nt
	global_load_dwordx4 v[80:83], v130, s[64:65] offset:2064 nt
	global_load_dwordx4 v[84:87], v131, s[64:65] nt
	global_load_dwordx4 v[88:91], v131, s[64:65] offset:16 nt
	global_load_dwordx4 v[92:95], v131, s[64:65] offset:2048 nt
	global_load_dwordx4 v[96:99], v131, s[64:65] offset:2064 nt
	s_waitcnt vmcnt(28)
	v_pk_add_f32 v[108:109], v[156:157], v[158:159]
	v_pk_add_f32 v[110:111], v[160:161], v[162:163]
	v_pk_add_f32 v[112:113], v[164:165], v[166:167]
	v_pk_add_f32 v[114:115], v[168:169], v[170:171]
	v_pk_mul_f32 v[116:117], v[156:157], v[156:157]
	v_pk_fma_f32 v[116:117], v[158:159], v[158:159], v[116:117]
	v_pk_fma_f32 v[116:117], v[160:161], v[160:161], v[116:117]
	v_pk_fma_f32 v[116:117], v[162:163], v[162:163], v[116:117]
	v_pk_fma_f32 v[116:117], v[164:165], v[164:165], v[116:117]
	v_pk_fma_f32 v[116:117], v[166:167], v[166:167], v[116:117]
	v_pk_fma_f32 v[116:117], v[168:169], v[168:169], v[116:117]
	v_pk_fma_f32 v[116:117], v[170:171], v[170:171], v[116:117]
	v_pk_add_f32 v[108:109], v[108:109], v[110:111]
	v_pk_add_f32 v[112:113], v[112:113], v[114:115]
	v_pk_add_f32 v[108:109], v[108:109], v[112:113]
	v_add_f32_e32 v100, v108, v109
	v_add_f32_e32 v101, v116, v117
	v_pk_add_f32 v[108:109], v[172:173], v[174:175]
	v_pk_add_f32 v[110:111], v[176:177], v[178:179]
	v_pk_add_f32 v[112:113], v[180:181], v[182:183]
	v_pk_add_f32 v[114:115], v[184:185], v[186:187]
	v_pk_mul_f32 v[116:117], v[172:173], v[172:173]
	v_pk_fma_f32 v[116:117], v[174:175], v[174:175], v[116:117]
	v_pk_fma_f32 v[116:117], v[176:177], v[176:177], v[116:117]
	v_pk_fma_f32 v[116:117], v[178:179], v[178:179], v[116:117]
	v_pk_fma_f32 v[116:117], v[180:181], v[180:181], v[116:117]
	v_pk_fma_f32 v[116:117], v[182:183], v[182:183], v[116:117]
	v_pk_fma_f32 v[116:117], v[184:185], v[184:185], v[116:117]
	v_pk_fma_f32 v[116:117], v[186:187], v[186:187], v[116:117]
	v_pk_add_f32 v[108:109], v[108:109], v[110:111]
	v_pk_add_f32 v[112:113], v[112:113], v[114:115]
	v_pk_add_f32 v[108:109], v[108:109], v[112:113]
	v_add_f32_e32 v102, v108, v109
	v_add_f32_e32 v103, v116, v117
	v_pk_add_f32 v[108:109], v[188:189], v[190:191]
	v_pk_add_f32 v[110:111], v[192:193], v[194:195]
	v_pk_add_f32 v[112:113], v[196:197], v[198:199]
	v_pk_add_f32 v[114:115], v[200:201], v[202:203]
	v_pk_mul_f32 v[116:117], v[188:189], v[188:189]
	v_pk_fma_f32 v[116:117], v[190:191], v[190:191], v[116:117]
	v_pk_fma_f32 v[116:117], v[192:193], v[192:193], v[116:117]
	v_pk_fma_f32 v[116:117], v[194:195], v[194:195], v[116:117]
	v_pk_fma_f32 v[116:117], v[196:197], v[196:197], v[116:117]
	v_pk_fma_f32 v[116:117], v[198:199], v[198:199], v[116:117]
	v_pk_fma_f32 v[116:117], v[200:201], v[200:201], v[116:117]
	v_pk_fma_f32 v[116:117], v[202:203], v[202:203], v[116:117]
	v_pk_add_f32 v[108:109], v[108:109], v[110:111]
	v_pk_add_f32 v[112:113], v[112:113], v[114:115]
	v_pk_add_f32 v[108:109], v[108:109], v[112:113]
	v_add_f32_e32 v104, v108, v109
	v_add_f32_e32 v105, v116, v117
	v_pk_add_f32 v[108:109], v[204:205], v[206:207]
	v_pk_add_f32 v[110:111], v[208:209], v[210:211]
	v_pk_add_f32 v[112:113], v[212:213], v[214:215]
	v_pk_add_f32 v[114:115], v[216:217], v[218:219]
	v_pk_mul_f32 v[116:117], v[204:205], v[204:205]
	v_pk_fma_f32 v[116:117], v[206:207], v[206:207], v[116:117]
	v_pk_fma_f32 v[116:117], v[208:209], v[208:209], v[116:117]
	v_pk_fma_f32 v[116:117], v[210:211], v[210:211], v[116:117]
	v_pk_fma_f32 v[116:117], v[212:213], v[212:213], v[116:117]
	v_pk_fma_f32 v[116:117], v[214:215], v[214:215], v[116:117]
	v_pk_fma_f32 v[116:117], v[216:217], v[216:217], v[116:117]
	v_pk_fma_f32 v[116:117], v[218:219], v[218:219], v[116:117]
	v_pk_add_f32 v[108:109], v[108:109], v[110:111]
	v_pk_add_f32 v[112:113], v[112:113], v[114:115]
	v_pk_add_f32 v[108:109], v[108:109], v[112:113]
	v_add_f32_e32 v106, v108, v109
	v_add_f32_e32 v107, v116, v117
	v_add_f32_dpp v100, v100, v100 quad_perm:[1,0,3,2] row_mask:0xf bank_mask:0xf
	v_add_f32_dpp v101, v101, v101 quad_perm:[1,0,3,2] row_mask:0xf bank_mask:0xf
	v_add_f32_dpp v102, v102, v102 quad_perm:[1,0,3,2] row_mask:0xf bank_mask:0xf
	v_add_f32_dpp v103, v103, v103 quad_perm:[1,0,3,2] row_mask:0xf bank_mask:0xf
	v_add_f32_dpp v104, v104, v104 quad_perm:[1,0,3,2] row_mask:0xf bank_mask:0xf
	v_add_f32_dpp v105, v105, v105 quad_perm:[1,0,3,2] row_mask:0xf bank_mask:0xf
	v_add_f32_dpp v106, v106, v106 quad_perm:[1,0,3,2] row_mask:0xf bank_mask:0xf
	v_add_f32_dpp v107, v107, v107 quad_perm:[1,0,3,2] row_mask:0xf bank_mask:0xf
	v_add_f32_dpp v100, v100, v100 quad_perm:[2,3,0,1] row_mask:0xf bank_mask:0xf
	v_add_f32_dpp v101, v101, v101 quad_perm:[2,3,0,1] row_mask:0xf bank_mask:0xf
	v_add_f32_dpp v102, v102, v102 quad_perm:[2,3,0,1] row_mask:0xf bank_mask:0xf
	v_add_f32_dpp v103, v103, v103 quad_perm:[2,3,0,1] row_mask:0xf bank_mask:0xf
	v_add_f32_dpp v104, v104, v104 quad_perm:[2,3,0,1] row_mask:0xf bank_mask:0xf
	v_add_f32_dpp v105, v105, v105 quad_perm:[2,3,0,1] row_mask:0xf bank_mask:0xf
	v_add_f32_dpp v106, v106, v106 quad_perm:[2,3,0,1] row_mask:0xf bank_mask:0xf
	v_add_f32_dpp v107, v107, v107 quad_perm:[2,3,0,1] row_mask:0xf bank_mask:0xf
	v_add_f32_dpp v100, v100, v100 row_half_mirror row_mask:0xf bank_mask:0xf
	v_add_f32_dpp v101, v101, v101 row_half_mirror row_mask:0xf bank_mask:0xf
	v_add_f32_dpp v102, v102, v102 row_half_mirror row_mask:0xf bank_mask:0xf
	v_add_f32_dpp v103, v103, v103 row_half_mirror row_mask:0xf bank_mask:0xf
	v_add_f32_dpp v104, v104, v104 row_half_mirror row_mask:0xf bank_mask:0xf
	v_add_f32_dpp v105, v105, v105 row_half_mirror row_mask:0xf bank_mask:0xf
	v_add_f32_dpp v106, v106, v106 row_half_mirror row_mask:0xf bank_mask:0xf
	v_add_f32_dpp v107, v107, v107 row_half_mirror row_mask:0xf bank_mask:0xf
	v_add_f32_dpp v100, v100, v100 row_mirror row_mask:0xf bank_mask:0xf
	v_add_f32_dpp v101, v101, v101 row_mirror row_mask:0xf bank_mask:0xf
	v_add_f32_dpp v102, v102, v102 row_mirror row_mask:0xf bank_mask:0xf
	v_add_f32_dpp v103, v103, v103 row_mirror row_mask:0xf bank_mask:0xf
	v_add_f32_dpp v104, v104, v104 row_mirror row_mask:0xf bank_mask:0xf
	v_add_f32_dpp v105, v105, v105 row_mirror row_mask:0xf bank_mask:0xf
	v_add_f32_dpp v106, v106, v106 row_mirror row_mask:0xf bank_mask:0xf
	v_add_f32_dpp v107, v107, v107 row_mirror row_mask:0xf bank_mask:0xf
	v_mov_b32_e32 v108, v100
	v_mov_b32_e32 v109, v101
	v_mov_b32_e32 v110, v102
	v_mov_b32_e32 v111, v103
	v_mov_b32_e32 v112, v104
	v_mov_b32_e32 v113, v105
	v_mov_b32_e32 v114, v106
	v_mov_b32_e32 v115, v107
	s_nop 1
	v_permlane16_swap_b32_e32 v108, v100
	v_permlane16_swap_b32_e32 v109, v101
	v_permlane16_swap_b32_e32 v110, v102
	v_permlane16_swap_b32_e32 v111, v103
	v_permlane16_swap_b32_e32 v112, v104
	v_permlane16_swap_b32_e32 v113, v105
	v_permlane16_swap_b32_e32 v114, v106
	v_permlane16_swap_b32_e32 v115, v107
	v_add_f32_e32 v100, v100, v108
	v_add_f32_e32 v101, v101, v109
	v_add_f32_e32 v102, v102, v110
	v_add_f32_e32 v103, v103, v111
	v_add_f32_e32 v104, v104, v112
	v_add_f32_e32 v105, v105, v113
	v_add_f32_e32 v106, v106, v114
	v_add_f32_e32 v107, v107, v115
	v_mov_b32_e32 v108, v100
	v_mov_b32_e32 v109, v101
	v_mov_b32_e32 v110, v102
	v_mov_b32_e32 v111, v103
	v_mov_b32_e32 v112, v104
	v_mov_b32_e32 v113, v105
	v_mov_b32_e32 v114, v106
	v_mov_b32_e32 v115, v107
	s_nop 1
	v_permlane32_swap_b32_e32 v108, v100
	v_permlane32_swap_b32_e32 v109, v101
	v_permlane32_swap_b32_e32 v110, v102
	v_permlane32_swap_b32_e32 v111, v103
	v_permlane32_swap_b32_e32 v112, v104
	v_permlane32_swap_b32_e32 v113, v105
	v_permlane32_swap_b32_e32 v114, v106
	v_permlane32_swap_b32_e32 v115, v107
	v_add_f32_e32 v100, v100, v108
	v_add_f32_e32 v101, v101, v109
	v_add_f32_e32 v102, v102, v110
	v_add_f32_e32 v103, v103, v111
	v_add_f32_e32 v104, v104, v112
	v_add_f32_e32 v105, v105, v113
	v_add_f32_e32 v106, v106, v114
	v_add_f32_e32 v107, v107, v115
	v_mul_f32_e32 v238, 0x3a800000, v100
	v_mul_f32_e32 v116, 0x3a800000, v101
	v_fma_f32 v116, -v238, v238, v116
	v_max_f32_e32 v116, 0, v116
	v_add_f32_e32 v116, 0x3727c5ac, v116
	v_mul_f32_e32 v240, 0x3a800000, v102
	v_mul_f32_e32 v118, 0x3a800000, v103
	v_fma_f32 v118, -v240, v240, v118
	v_max_f32_e32 v118, 0, v118
	v_add_f32_e32 v118, 0x3727c5ac, v118
	v_mul_f32_e32 v242, 0x3a800000, v104
	v_mul_f32_e32 v120, 0x3a800000, v105
	v_fma_f32 v120, -v242, v242, v120
	v_max_f32_e32 v120, 0, v120
	v_add_f32_e32 v120, 0x3727c5ac, v120
	v_mul_f32_e32 v244, 0x3a800000, v106
	v_mul_f32_e32 v122, 0x3a800000, v107
	v_fma_f32 v122, -v244, v244, v122
	v_max_f32_e32 v122, 0, v122
	v_add_f32_e32 v122, 0x3727c5ac, v122
	v_rsq_f32_e32 v117, v116
	v_rsq_f32_e32 v119, v118
	v_rsq_f32_e32 v121, v120
	v_rsq_f32_e32 v123, v122
	s_nop 0
	v_mul_f32_e32 v124, v116, v117
	v_mul_f32_e32 v124, v124, v117
	v_fmaak_f32 v124, -0.5, v124, 0x3fc00000
	v_mul_f32_e32 v239, v117, v124
	v_mul_f32_e32 v125, v118, v119
	v_mul_f32_e32 v125, v125, v119
	v_fmaak_f32 v125, -0.5, v125, 0x3fc00000
	v_mul_f32_e32 v241, v119, v125
	v_mul_f32_e32 v126, v120, v121
	v_mul_f32_e32 v126, v126, v121
	v_fmaak_f32 v126, -0.5, v126, 0x3fc00000
	v_mul_f32_e32 v243, v121, v126
	v_mul_f32_e32 v127, v122, v123
	v_mul_f32_e32 v127, v127, v123
	v_fmaak_f32 v127, -0.5, v127, 0x3fc00000
	v_mul_f32_e32 v245, v123, v127
	v_pk_add_f32 v[156:157], v[156:157], v[238:239] op_sel_hi:[1,0] neg_lo:[0,1] neg_hi:[0,1]
	v_pk_add_f32 v[158:159], v[158:159], v[238:239] op_sel_hi:[1,0] neg_lo:[0,1] neg_hi:[0,1]
	v_pk_add_f32 v[160:161], v[160:161], v[238:239] op_sel_hi:[1,0] neg_lo:[0,1] neg_hi:[0,1]
	v_pk_add_f32 v[162:163], v[162:163], v[238:239] op_sel_hi:[1,0] neg_lo:[0,1] neg_hi:[0,1]
	v_pk_add_f32 v[164:165], v[164:165], v[238:239] op_sel_hi:[1,0] neg_lo:[0,1] neg_hi:[0,1]
	v_pk_add_f32 v[166:167], v[166:167], v[238:239] op_sel_hi:[1,0] neg_lo:[0,1] neg_hi:[0,1]
	v_pk_add_f32 v[168:169], v[168:169], v[238:239] op_sel_hi:[1,0] neg_lo:[0,1] neg_hi:[0,1]
	v_pk_add_f32 v[170:171], v[170:171], v[238:239] op_sel_hi:[1,0] neg_lo:[0,1] neg_hi:[0,1]
	v_pk_mul_f32 v[156:157], v[156:157], v[238:239] op_sel:[0,1] op_sel_hi:[1,1]
	v_pk_mul_f32 v[158:159], v[158:159], v[238:239] op_sel:[0,1] op_sel_hi:[1,1]
	v_pk_mul_f32 v[160:161], v[160:161], v[238:239] op_sel:[0,1] op_sel_hi:[1,1]
	v_pk_mul_f32 v[162:163], v[162:163], v[238:239] op_sel:[0,1] op_sel_hi:[1,1]
	v_pk_mul_f32 v[164:165], v[164:165], v[238:239] op_sel:[0,1] op_sel_hi:[1,1]
	v_pk_mul_f32 v[166:167], v[166:167], v[238:239] op_sel:[0,1] op_sel_hi:[1,1]
	v_pk_mul_f32 v[168:169], v[168:169], v[238:239] op_sel:[0,1] op_sel_hi:[1,1]
	v_pk_mul_f32 v[170:171], v[170:171], v[238:239] op_sel:[0,1] op_sel_hi:[1,1]
	v_pk_fma_f32 v[156:157], v[4:5], v[156:157], v[20:21]
	v_pk_fma_f32 v[158:159], v[6:7], v[158:159], v[22:23]
	v_pk_fma_f32 v[160:161], v[8:9], v[160:161], v[24:25]
	v_pk_fma_f32 v[162:163], v[10:11], v[162:163], v[26:27]
	v_pk_fma_f32 v[164:165], v[12:13], v[164:165], v[28:29]
	v_pk_fma_f32 v[166:167], v[14:15], v[166:167], v[30:31]
	v_pk_fma_f32 v[168:169], v[16:17], v[168:169], v[32:33]
	v_pk_fma_f32 v[170:171], v[18:19], v[170:171], v[34:35]
	v_cvt_pk_bf16_f32 v156, v156, v157
	v_cvt_pk_bf16_f32 v157, v158, v159
	v_cvt_pk_bf16_f32 v158, v160, v161
	v_cvt_pk_bf16_f32 v159, v162, v163
	v_cvt_pk_bf16_f32 v164, v164, v165
	v_cvt_pk_bf16_f32 v165, v166, v167
	v_cvt_pk_bf16_f32 v166, v168, v169
	v_cvt_pk_bf16_f32 v167, v170, v171
	v_lshl_add_u32 v3, s40, 11, v2
	global_store_dwordx4 v3, v[156:159], s[96:97] sc1
	global_store_dwordx4 v3, v[164:167], s[96:97] offset:1024 sc1
	v_pk_add_f32 v[172:173], v[172:173], v[240:241] op_sel_hi:[1,0] neg_lo:[0,1] neg_hi:[0,1]
	v_pk_add_f32 v[174:175], v[174:175], v[240:241] op_sel_hi:[1,0] neg_lo:[0,1] neg_hi:[0,1]
	v_pk_add_f32 v[176:177], v[176:177], v[240:241] op_sel_hi:[1,0] neg_lo:[0,1] neg_hi:[0,1]
	v_pk_add_f32 v[178:179], v[178:179], v[240:241] op_sel_hi:[1,0] neg_lo:[0,1] neg_hi:[0,1]
	v_pk_add_f32 v[180:181], v[180:181], v[240:241] op_sel_hi:[1,0] neg_lo:[0,1] neg_hi:[0,1]
	v_pk_add_f32 v[182:183], v[182:183], v[240:241] op_sel_hi:[1,0] neg_lo:[0,1] neg_hi:[0,1]
	v_pk_add_f32 v[184:185], v[184:185], v[240:241] op_sel_hi:[1,0] neg_lo:[0,1] neg_hi:[0,1]
	v_pk_add_f32 v[186:187], v[186:187], v[240:241] op_sel_hi:[1,0] neg_lo:[0,1] neg_hi:[0,1]
	v_pk_mul_f32 v[172:173], v[172:173], v[240:241] op_sel:[0,1] op_sel_hi:[1,1]
	v_pk_mul_f32 v[174:175], v[174:175], v[240:241] op_sel:[0,1] op_sel_hi:[1,1]
	v_pk_mul_f32 v[176:177], v[176:177], v[240:241] op_sel:[0,1] op_sel_hi:[1,1]
	v_pk_mul_f32 v[178:179], v[178:179], v[240:241] op_sel:[0,1] op_sel_hi:[1,1]
	v_pk_mul_f32 v[180:181], v[180:181], v[240:241] op_sel:[0,1] op_sel_hi:[1,1]
	v_pk_mul_f32 v[182:183], v[182:183], v[240:241] op_sel:[0,1] op_sel_hi:[1,1]
	v_pk_mul_f32 v[184:185], v[184:185], v[240:241] op_sel:[0,1] op_sel_hi:[1,1]
	v_pk_mul_f32 v[186:187], v[186:187], v[240:241] op_sel:[0,1] op_sel_hi:[1,1]
	v_pk_fma_f32 v[172:173], v[4:5], v[172:173], v[20:21]
	v_pk_fma_f32 v[174:175], v[6:7], v[174:175], v[22:23]
	v_pk_fma_f32 v[176:177], v[8:9], v[176:177], v[24:25]
	v_pk_fma_f32 v[178:179], v[10:11], v[178:179], v[26:27]
	v_pk_fma_f32 v[180:181], v[12:13], v[180:181], v[28:29]
	v_pk_fma_f32 v[182:183], v[14:15], v[182:183], v[30:31]
	v_pk_fma_f32 v[184:185], v[16:17], v[184:185], v[32:33]
	v_pk_fma_f32 v[186:187], v[18:19], v[186:187], v[34:35]
	v_cvt_pk_bf16_f32 v172, v172, v173
	v_cvt_pk_bf16_f32 v173, v174, v175
	v_cvt_pk_bf16_f32 v174, v176, v177
	v_cvt_pk_bf16_f32 v175, v178, v179
	v_cvt_pk_bf16_f32 v180, v180, v181
	v_cvt_pk_bf16_f32 v181, v182, v183
	v_cvt_pk_bf16_f32 v182, v184, v185
	v_cvt_pk_bf16_f32 v183, v186, v187
	v_lshl_add_u32 v3, s41, 11, v2
	global_store_dwordx4 v3, v[172:175], s[96:97] sc1
	global_store_dwordx4 v3, v[180:183], s[96:97] offset:1024 sc1
	v_pk_add_f32 v[188:189], v[188:189], v[242:243] op_sel_hi:[1,0] neg_lo:[0,1] neg_hi:[0,1]
	v_pk_add_f32 v[190:191], v[190:191], v[242:243] op_sel_hi:[1,0] neg_lo:[0,1] neg_hi:[0,1]
	v_pk_add_f32 v[192:193], v[192:193], v[242:243] op_sel_hi:[1,0] neg_lo:[0,1] neg_hi:[0,1]
	v_pk_add_f32 v[194:195], v[194:195], v[242:243] op_sel_hi:[1,0] neg_lo:[0,1] neg_hi:[0,1]
	v_pk_add_f32 v[196:197], v[196:197], v[242:243] op_sel_hi:[1,0] neg_lo:[0,1] neg_hi:[0,1]
	v_pk_add_f32 v[198:199], v[198:199], v[242:243] op_sel_hi:[1,0] neg_lo:[0,1] neg_hi:[0,1]
	v_pk_add_f32 v[200:201], v[200:201], v[242:243] op_sel_hi:[1,0] neg_lo:[0,1] neg_hi:[0,1]
	v_pk_add_f32 v[202:203], v[202:203], v[242:243] op_sel_hi:[1,0] neg_lo:[0,1] neg_hi:[0,1]
	v_pk_mul_f32 v[188:189], v[188:189], v[242:243] op_sel:[0,1] op_sel_hi:[1,1]
	v_pk_mul_f32 v[190:191], v[190:191], v[242:243] op_sel:[0,1] op_sel_hi:[1,1]
	v_pk_mul_f32 v[192:193], v[192:193], v[242:243] op_sel:[0,1] op_sel_hi:[1,1]
	v_pk_mul_f32 v[194:195], v[194:195], v[242:243] op_sel:[0,1] op_sel_hi:[1,1]
	v_pk_mul_f32 v[196:197], v[196:197], v[242:243] op_sel:[0,1] op_sel_hi:[1,1]
	v_pk_mul_f32 v[198:199], v[198:199], v[242:243] op_sel:[0,1] op_sel_hi:[1,1]
	v_pk_mul_f32 v[200:201], v[200:201], v[242:243] op_sel:[0,1] op_sel_hi:[1,1]
	v_pk_mul_f32 v[202:203], v[202:203], v[242:243] op_sel:[0,1] op_sel_hi:[1,1]
	v_pk_fma_f32 v[188:189], v[4:5], v[188:189], v[20:21]
	v_pk_fma_f32 v[190:191], v[6:7], v[190:191], v[22:23]
	v_pk_fma_f32 v[192:193], v[8:9], v[192:193], v[24:25]
	v_pk_fma_f32 v[194:195], v[10:11], v[194:195], v[26:27]
	v_pk_fma_f32 v[196:197], v[12:13], v[196:197], v[28:29]
	v_pk_fma_f32 v[198:199], v[14:15], v[198:199], v[30:31]
	v_pk_fma_f32 v[200:201], v[16:17], v[200:201], v[32:33]
	v_pk_fma_f32 v[202:203], v[18:19], v[202:203], v[34:35]
	v_cvt_pk_bf16_f32 v188, v188, v189
	v_cvt_pk_bf16_f32 v189, v190, v191
	v_cvt_pk_bf16_f32 v190, v192, v193
	v_cvt_pk_bf16_f32 v191, v194, v195
	v_cvt_pk_bf16_f32 v196, v196, v197
	v_cvt_pk_bf16_f32 v197, v198, v199
	v_cvt_pk_bf16_f32 v198, v200, v201
	v_cvt_pk_bf16_f32 v199, v202, v203
	v_lshl_add_u32 v3, s42, 11, v2
	global_store_dwordx4 v3, v[188:191], s[96:97] sc1
	global_store_dwordx4 v3, v[196:199], s[96:97] offset:1024 sc1
	v_pk_add_f32 v[204:205], v[204:205], v[244:245] op_sel_hi:[1,0] neg_lo:[0,1] neg_hi:[0,1]
	v_pk_add_f32 v[206:207], v[206:207], v[244:245] op_sel_hi:[1,0] neg_lo:[0,1] neg_hi:[0,1]
	v_pk_add_f32 v[208:209], v[208:209], v[244:245] op_sel_hi:[1,0] neg_lo:[0,1] neg_hi:[0,1]
	v_pk_add_f32 v[210:211], v[210:211], v[244:245] op_sel_hi:[1,0] neg_lo:[0,1] neg_hi:[0,1]
	v_pk_add_f32 v[212:213], v[212:213], v[244:245] op_sel_hi:[1,0] neg_lo:[0,1] neg_hi:[0,1]
	v_pk_add_f32 v[214:215], v[214:215], v[244:245] op_sel_hi:[1,0] neg_lo:[0,1] neg_hi:[0,1]
	v_pk_add_f32 v[216:217], v[216:217], v[244:245] op_sel_hi:[1,0] neg_lo:[0,1] neg_hi:[0,1]
	v_pk_add_f32 v[218:219], v[218:219], v[244:245] op_sel_hi:[1,0] neg_lo:[0,1] neg_hi:[0,1]
	v_pk_mul_f32 v[204:205], v[204:205], v[244:245] op_sel:[0,1] op_sel_hi:[1,1]
	v_pk_mul_f32 v[206:207], v[206:207], v[244:245] op_sel:[0,1] op_sel_hi:[1,1]
	v_pk_mul_f32 v[208:209], v[208:209], v[244:245] op_sel:[0,1] op_sel_hi:[1,1]
	v_pk_mul_f32 v[210:211], v[210:211], v[244:245] op_sel:[0,1] op_sel_hi:[1,1]
	v_pk_mul_f32 v[212:213], v[212:213], v[244:245] op_sel:[0,1] op_sel_hi:[1,1]
	v_pk_mul_f32 v[214:215], v[214:215], v[244:245] op_sel:[0,1] op_sel_hi:[1,1]
	v_pk_mul_f32 v[216:217], v[216:217], v[244:245] op_sel:[0,1] op_sel_hi:[1,1]
	v_pk_mul_f32 v[218:219], v[218:219], v[244:245] op_sel:[0,1] op_sel_hi:[1,1]
	v_pk_fma_f32 v[204:205], v[4:5], v[204:205], v[20:21]
	v_pk_fma_f32 v[206:207], v[6:7], v[206:207], v[22:23]
	v_pk_fma_f32 v[208:209], v[8:9], v[208:209], v[24:25]
	v_pk_fma_f32 v[210:211], v[10:11], v[210:211], v[26:27]
	v_pk_fma_f32 v[212:213], v[12:13], v[212:213], v[28:29]
	v_pk_fma_f32 v[214:215], v[14:15], v[214:215], v[30:31]
	v_pk_fma_f32 v[216:217], v[16:17], v[216:217], v[32:33]
	v_pk_fma_f32 v[218:219], v[18:19], v[218:219], v[34:35]
	v_cvt_pk_bf16_f32 v204, v204, v205
	v_cvt_pk_bf16_f32 v205, v206, v207
	v_cvt_pk_bf16_f32 v206, v208, v209
	v_cvt_pk_bf16_f32 v207, v210, v211
	v_cvt_pk_bf16_f32 v212, v212, v213
	v_cvt_pk_bf16_f32 v213, v214, v215
	v_cvt_pk_bf16_f32 v214, v216, v217
	v_cvt_pk_bf16_f32 v215, v218, v219
	v_lshl_add_u32 v3, s43, 11, v2
	global_store_dwordx4 v3, v[204:207], s[96:97] sc1
	global_store_dwordx4 v3, v[212:215], s[96:97] offset:1024 sc1
	s_mov_b64 s[52:53], exec
	s_mov_b64 exec, 1
	v_mov_b32_e32 v3, s40
	v_lshlrev_b32_e32 v3, 3, v3
	global_store_dwordx2 v3, v[238:239], s[92:93] sc1
	v_mov_b32_e32 v3, s41
	v_lshlrev_b32_e32 v3, 3, v3
	global_store_dwordx2 v3, v[240:241], s[92:93] sc1
	v_mov_b32_e32 v3, s42
	v_lshlrev_b32_e32 v3, 3, v3
	global_store_dwordx2 v3, v[242:243], s[92:93] sc1
	v_mov_b32_e32 v3, s43
	v_lshlrev_b32_e32 v3, 3, v3
	global_store_dwordx2 v3, v[244:245], s[92:93] sc1
	s_mov_b64 exec, s[52:53]
	s_add_u32 s40, s46, 0x4800
	v_lshl_add_u32 v132, s40, 12, v1
	s_add_u32 s41, s46, 0x5800
	v_lshl_add_u32 v133, s41, 12, v1
	s_add_u32 s42, s46, 0x6800
	v_lshl_add_u32 v134, s42, 12, v1
	s_add_u32 s43, s46, 0x7800
	v_lshl_add_u32 v135, s43, 12, v1
	global_load_dwordx4 v[156:159], v132, s[64:65] nt
	global_load_dwordx4 v[160:163], v132, s[64:65] offset:16 nt
	global_load_dwordx4 v[164:167], v132, s[64:65] offset:2048 nt
	global_load_dwordx4 v[168:171], v132, s[64:65] offset:2064 nt
	global_load_dwordx4 v[172:175], v133, s[64:65] nt
	global_load_dwordx4 v[176:179], v133, s[64:65] offset:16 nt
	global_load_dwordx4 v[180:183], v133, s[64:65] offset:2048 nt
	global_load_dwordx4 v[184:187], v133, s[64:65] offset:2064 nt
	global_load_dwordx4 v[188:191], v134, s[64:65] nt
	global_load_dwordx4 v[192:195], v134, s[64:65] offset:16 nt
	global_load_dwordx4 v[196:199], v134, s[64:65] offset:2048 nt
	global_load_dwordx4 v[200:203], v134, s[64:65] offset:2064 nt
	global_load_dwordx4 v[204:207], v135, s[64:65] nt
	global_load_dwordx4 v[208:211], v135, s[64:65] offset:16 nt
	global_load_dwordx4 v[212:215], v135, s[64:65] offset:2048 nt
	global_load_dwordx4 v[216:219], v135, s[64:65] offset:2064 nt
	s_waitcnt vmcnt(28)
	v_pk_add_f32 v[108:109], v[36:37], v[38:39]
	v_pk_add_f32 v[110:111], v[40:41], v[42:43]
	v_pk_add_f32 v[112:113], v[44:45], v[46:47]
	v_pk_add_f32 v[114:115], v[48:49], v[50:51]
	v_pk_mul_f32 v[116:117], v[36:37], v[36:37]
	v_pk_fma_f32 v[116:117], v[38:39], v[38:39], v[116:117]
	v_pk_fma_f32 v[116:117], v[40:41], v[40:41], v[116:117]
	v_pk_fma_f32 v[116:117], v[42:43], v[42:43], v[116:117]
	v_pk_fma_f32 v[116:117], v[44:45], v[44:45], v[116:117]
	v_pk_fma_f32 v[116:117], v[46:47], v[46:47], v[116:117]
	v_pk_fma_f32 v[116:117], v[48:49], v[48:49], v[116:117]
	v_pk_fma_f32 v[116:117], v[50:51], v[50:51], v[116:117]
	v_pk_add_f32 v[108:109], v[108:109], v[110:111]
	v_pk_add_f32 v[112:113], v[112:113], v[114:115]
	v_pk_add_f32 v[108:109], v[108:109], v[112:113]
	v_add_f32_e32 v100, v108, v109
	v_add_f32_e32 v101, v116, v117
	v_pk_add_f32 v[108:109], v[52:53], v[54:55]
	v_pk_add_f32 v[110:111], v[56:57], v[58:59]
	v_pk_add_f32 v[112:113], v[60:61], v[62:63]
	v_pk_add_f32 v[114:115], v[64:65], v[66:67]
	v_pk_mul_f32 v[116:117], v[52:53], v[52:53]
	v_pk_fma_f32 v[116:117], v[54:55], v[54:55], v[116:117]
	v_pk_fma_f32 v[116:117], v[56:57], v[56:57], v[116:117]
	v_pk_fma_f32 v[116:117], v[58:59], v[58:59], v[116:117]
	v_pk_fma_f32 v[116:117], v[60:61], v[60:61], v[116:117]
	v_pk_fma_f32 v[116:117], v[62:63], v[62:63], v[116:117]
	v_pk_fma_f32 v[116:117], v[64:65], v[64:65], v[116:117]
	v_pk_fma_f32 v[116:117], v[66:67], v[66:67], v[116:117]
	v_pk_add_f32 v[108:109], v[108:109], v[110:111]
	v_pk_add_f32 v[112:113], v[112:113], v[114:115]
	v_pk_add_f32 v[108:109], v[108:109], v[112:113]
	v_add_f32_e32 v102, v108, v109
	v_add_f32_e32 v103, v116, v117
	v_pk_add_f32 v[108:109], v[68:69], v[70:71]
	v_pk_add_f32 v[110:111], v[72:73], v[74:75]
	v_pk_add_f32 v[112:113], v[76:77], v[78:79]
	v_pk_add_f32 v[114:115], v[80:81], v[82:83]
	v_pk_mul_f32 v[116:117], v[68:69], v[68:69]
	v_pk_fma_f32 v[116:117], v[70:71], v[70:71], v[116:117]
	v_pk_fma_f32 v[116:117], v[72:73], v[72:73], v[116:117]
	v_pk_fma_f32 v[116:117], v[74:75], v[74:75], v[116:117]
	v_pk_fma_f32 v[116:117], v[76:77], v[76:77], v[116:117]
	v_pk_fma_f32 v[116:117], v[78:79], v[78:79], v[116:117]
	v_pk_fma_f32 v[116:117], v[80:81], v[80:81], v[116:117]
	v_pk_fma_f32 v[116:117], v[82:83], v[82:83], v[116:117]
	v_pk_add_f32 v[108:109], v[108:109], v[110:111]
	v_pk_add_f32 v[112:113], v[112:113], v[114:115]
	v_pk_add_f32 v[108:109], v[108:109], v[112:113]
	v_add_f32_e32 v104, v108, v109
	v_add_f32_e32 v105, v116, v117
	v_pk_add_f32 v[108:109], v[84:85], v[86:87]
	v_pk_add_f32 v[110:111], v[88:89], v[90:91]
	v_pk_add_f32 v[112:113], v[92:93], v[94:95]
	v_pk_add_f32 v[114:115], v[96:97], v[98:99]
	v_pk_mul_f32 v[116:117], v[84:85], v[84:85]
	v_pk_fma_f32 v[116:117], v[86:87], v[86:87], v[116:117]
	v_pk_fma_f32 v[116:117], v[88:89], v[88:89], v[116:117]
	v_pk_fma_f32 v[116:117], v[90:91], v[90:91], v[116:117]
	v_pk_fma_f32 v[116:117], v[92:93], v[92:93], v[116:117]
	v_pk_fma_f32 v[116:117], v[94:95], v[94:95], v[116:117]
	v_pk_fma_f32 v[116:117], v[96:97], v[96:97], v[116:117]
	v_pk_fma_f32 v[116:117], v[98:99], v[98:99], v[116:117]
	v_pk_add_f32 v[108:109], v[108:109], v[110:111]
	v_pk_add_f32 v[112:113], v[112:113], v[114:115]
	v_pk_add_f32 v[108:109], v[108:109], v[112:113]
	v_add_f32_e32 v106, v108, v109
	v_add_f32_e32 v107, v116, v117
	v_add_f32_dpp v100, v100, v100 quad_perm:[1,0,3,2] row_mask:0xf bank_mask:0xf
	v_add_f32_dpp v101, v101, v101 quad_perm:[1,0,3,2] row_mask:0xf bank_mask:0xf
	v_add_f32_dpp v102, v102, v102 quad_perm:[1,0,3,2] row_mask:0xf bank_mask:0xf
	v_add_f32_dpp v103, v103, v103 quad_perm:[1,0,3,2] row_mask:0xf bank_mask:0xf
	v_add_f32_dpp v104, v104, v104 quad_perm:[1,0,3,2] row_mask:0xf bank_mask:0xf
	v_add_f32_dpp v105, v105, v105 quad_perm:[1,0,3,2] row_mask:0xf bank_mask:0xf
	v_add_f32_dpp v106, v106, v106 quad_perm:[1,0,3,2] row_mask:0xf bank_mask:0xf
	v_add_f32_dpp v107, v107, v107 quad_perm:[1,0,3,2] row_mask:0xf bank_mask:0xf
	v_add_f32_dpp v100, v100, v100 quad_perm:[2,3,0,1] row_mask:0xf bank_mask:0xf
	v_add_f32_dpp v101, v101, v101 quad_perm:[2,3,0,1] row_mask:0xf bank_mask:0xf
	v_add_f32_dpp v102, v102, v102 quad_perm:[2,3,0,1] row_mask:0xf bank_mask:0xf
	v_add_f32_dpp v103, v103, v103 quad_perm:[2,3,0,1] row_mask:0xf bank_mask:0xf
	v_add_f32_dpp v104, v104, v104 quad_perm:[2,3,0,1] row_mask:0xf bank_mask:0xf
	v_add_f32_dpp v105, v105, v105 quad_perm:[2,3,0,1] row_mask:0xf bank_mask:0xf
	v_add_f32_dpp v106, v106, v106 quad_perm:[2,3,0,1] row_mask:0xf bank_mask:0xf
	v_add_f32_dpp v107, v107, v107 quad_perm:[2,3,0,1] row_mask:0xf bank_mask:0xf
	v_add_f32_dpp v100, v100, v100 row_half_mirror row_mask:0xf bank_mask:0xf
	v_add_f32_dpp v101, v101, v101 row_half_mirror row_mask:0xf bank_mask:0xf
	v_add_f32_dpp v102, v102, v102 row_half_mirror row_mask:0xf bank_mask:0xf
	v_add_f32_dpp v103, v103, v103 row_half_mirror row_mask:0xf bank_mask:0xf
	v_add_f32_dpp v104, v104, v104 row_half_mirror row_mask:0xf bank_mask:0xf
	v_add_f32_dpp v105, v105, v105 row_half_mirror row_mask:0xf bank_mask:0xf
	v_add_f32_dpp v106, v106, v106 row_half_mirror row_mask:0xf bank_mask:0xf
	v_add_f32_dpp v107, v107, v107 row_half_mirror row_mask:0xf bank_mask:0xf
	v_add_f32_dpp v100, v100, v100 row_mirror row_mask:0xf bank_mask:0xf
	v_add_f32_dpp v101, v101, v101 row_mirror row_mask:0xf bank_mask:0xf
	v_add_f32_dpp v102, v102, v102 row_mirror row_mask:0xf bank_mask:0xf
	v_add_f32_dpp v103, v103, v103 row_mirror row_mask:0xf bank_mask:0xf
	v_add_f32_dpp v104, v104, v104 row_mirror row_mask:0xf bank_mask:0xf
	v_add_f32_dpp v105, v105, v105 row_mirror row_mask:0xf bank_mask:0xf
	v_add_f32_dpp v106, v106, v106 row_mirror row_mask:0xf bank_mask:0xf
	v_add_f32_dpp v107, v107, v107 row_mirror row_mask:0xf bank_mask:0xf
	v_mov_b32_e32 v108, v100
	v_mov_b32_e32 v109, v101
	v_mov_b32_e32 v110, v102
	v_mov_b32_e32 v111, v103
	v_mov_b32_e32 v112, v104
	v_mov_b32_e32 v113, v105
	v_mov_b32_e32 v114, v106
	v_mov_b32_e32 v115, v107
	s_nop 1
	v_permlane16_swap_b32_e32 v108, v100
	v_permlane16_swap_b32_e32 v109, v101
	v_permlane16_swap_b32_e32 v110, v102
	v_permlane16_swap_b32_e32 v111, v103
	v_permlane16_swap_b32_e32 v112, v104
	v_permlane16_swap_b32_e32 v113, v105
	v_permlane16_swap_b32_e32 v114, v106
	v_permlane16_swap_b32_e32 v115, v107
	v_add_f32_e32 v100, v100, v108
	v_add_f32_e32 v101, v101, v109
	v_add_f32_e32 v102, v102, v110
	v_add_f32_e32 v103, v103, v111
	v_add_f32_e32 v104, v104, v112
	v_add_f32_e32 v105, v105, v113
	v_add_f32_e32 v106, v106, v114
	v_add_f32_e32 v107, v107, v115
	v_mov_b32_e32 v108, v100
	v_mov_b32_e32 v109, v101
	v_mov_b32_e32 v110, v102
	v_mov_b32_e32 v111, v103
	v_mov_b32_e32 v112, v104
	v_mov_b32_e32 v113, v105
	v_mov_b32_e32 v114, v106
	v_mov_b32_e32 v115, v107
	s_nop 1
	v_permlane32_swap_b32_e32 v108, v100
	v_permlane32_swap_b32_e32 v109, v101
	v_permlane32_swap_b32_e32 v110, v102
	v_permlane32_swap_b32_e32 v111, v103
	v_permlane32_swap_b32_e32 v112, v104
	v_permlane32_swap_b32_e32 v113, v105
	v_permlane32_swap_b32_e32 v114, v106
	v_permlane32_swap_b32_e32 v115, v107
	v_add_f32_e32 v100, v100, v108
	v_add_f32_e32 v101, v101, v109
	v_add_f32_e32 v102, v102, v110
	v_add_f32_e32 v103, v103, v111
	v_add_f32_e32 v104, v104, v112
	v_add_f32_e32 v105, v105, v113
	v_add_f32_e32 v106, v106, v114
	v_add_f32_e32 v107, v107, v115
	v_mul_f32_e32 v230, 0x3a800000, v100
	v_mul_f32_e32 v116, 0x3a800000, v101
	v_fma_f32 v116, -v230, v230, v116
	v_max_f32_e32 v116, 0, v116
	v_add_f32_e32 v116, 0x3727c5ac, v116
	v_mul_f32_e32 v232, 0x3a800000, v102
	v_mul_f32_e32 v118, 0x3a800000, v103
	v_fma_f32 v118, -v232, v232, v118
	v_max_f32_e32 v118, 0, v118
	v_add_f32_e32 v118, 0x3727c5ac, v118
	v_mul_f32_e32 v234, 0x3a800000, v104
	v_mul_f32_e32 v120, 0x3a800000, v105
	v_fma_f32 v120, -v234, v234, v120
	v_max_f32_e32 v120, 0, v120
	v_add_f32_e32 v120, 0x3727c5ac, v120
	v_mul_f32_e32 v236, 0x3a800000, v106
	v_mul_f32_e32 v122, 0x3a800000, v107
	v_fma_f32 v122, -v236, v236, v122
	v_max_f32_e32 v122, 0, v122
	v_add_f32_e32 v122, 0x3727c5ac, v122
	v_rsq_f32_e32 v117, v116
	v_rsq_f32_e32 v119, v118
	v_rsq_f32_e32 v121, v120
	v_rsq_f32_e32 v123, v122
	s_nop 0
	v_mul_f32_e32 v124, v116, v117
	v_mul_f32_e32 v124, v124, v117
	v_fmaak_f32 v124, -0.5, v124, 0x3fc00000
	v_mul_f32_e32 v231, v117, v124
	v_mul_f32_e32 v125, v118, v119
	v_mul_f32_e32 v125, v125, v119
	v_fmaak_f32 v125, -0.5, v125, 0x3fc00000
	v_mul_f32_e32 v233, v119, v125
	v_mul_f32_e32 v126, v120, v121
	v_mul_f32_e32 v126, v126, v121
	v_fmaak_f32 v126, -0.5, v126, 0x3fc00000
	v_mul_f32_e32 v235, v121, v126
	v_mul_f32_e32 v127, v122, v123
	v_mul_f32_e32 v127, v127, v123
	v_fmaak_f32 v127, -0.5, v127, 0x3fc00000
	v_mul_f32_e32 v237, v123, v127
	v_pk_add_f32 v[36:37], v[36:37], v[230:231] op_sel_hi:[1,0] neg_lo:[0,1] neg_hi:[0,1]
	v_pk_add_f32 v[38:39], v[38:39], v[230:231] op_sel_hi:[1,0] neg_lo:[0,1] neg_hi:[0,1]
	v_pk_add_f32 v[40:41], v[40:41], v[230:231] op_sel_hi:[1,0] neg_lo:[0,1] neg_hi:[0,1]
	v_pk_add_f32 v[42:43], v[42:43], v[230:231] op_sel_hi:[1,0] neg_lo:[0,1] neg_hi:[0,1]
	v_pk_add_f32 v[44:45], v[44:45], v[230:231] op_sel_hi:[1,0] neg_lo:[0,1] neg_hi:[0,1]
	v_pk_add_f32 v[46:47], v[46:47], v[230:231] op_sel_hi:[1,0] neg_lo:[0,1] neg_hi:[0,1]
	v_pk_add_f32 v[48:49], v[48:49], v[230:231] op_sel_hi:[1,0] neg_lo:[0,1] neg_hi:[0,1]
	v_pk_add_f32 v[50:51], v[50:51], v[230:231] op_sel_hi:[1,0] neg_lo:[0,1] neg_hi:[0,1]
	v_pk_mul_f32 v[36:37], v[36:37], v[230:231] op_sel:[0,1] op_sel_hi:[1,1]
	v_pk_mul_f32 v[38:39], v[38:39], v[230:231] op_sel:[0,1] op_sel_hi:[1,1]
	v_pk_mul_f32 v[40:41], v[40:41], v[230:231] op_sel:[0,1] op_sel_hi:[1,1]
	v_pk_mul_f32 v[42:43], v[42:43], v[230:231] op_sel:[0,1] op_sel_hi:[1,1]
	v_pk_mul_f32 v[44:45], v[44:45], v[230:231] op_sel:[0,1] op_sel_hi:[1,1]
	v_pk_mul_f32 v[46:47], v[46:47], v[230:231] op_sel:[0,1] op_sel_hi:[1,1]
	v_pk_mul_f32 v[48:49], v[48:49], v[230:231] op_sel:[0,1] op_sel_hi:[1,1]
	v_pk_mul_f32 v[50:51], v[50:51], v[230:231] op_sel:[0,1] op_sel_hi:[1,1]
	v_pk_fma_f32 v[36:37], v[4:5], v[36:37], v[20:21]
	v_pk_fma_f32 v[38:39], v[6:7], v[38:39], v[22:23]
	v_pk_fma_f32 v[40:41], v[8:9], v[40:41], v[24:25]
	v_pk_fma_f32 v[42:43], v[10:11], v[42:43], v[26:27]
	v_pk_fma_f32 v[44:45], v[12:13], v[44:45], v[28:29]
	v_pk_fma_f32 v[46:47], v[14:15], v[46:47], v[30:31]
	v_pk_fma_f32 v[48:49], v[16:17], v[48:49], v[32:33]
	v_pk_fma_f32 v[50:51], v[18:19], v[50:51], v[34:35]
	v_cvt_pk_bf16_f32 v36, v36, v37
	v_cvt_pk_bf16_f32 v37, v38, v39
	v_cvt_pk_bf16_f32 v38, v40, v41
	v_cvt_pk_bf16_f32 v39, v42, v43
	v_cvt_pk_bf16_f32 v44, v44, v45
	v_cvt_pk_bf16_f32 v45, v46, v47
	v_cvt_pk_bf16_f32 v46, v48, v49
	v_cvt_pk_bf16_f32 v47, v50, v51
	v_lshl_add_u32 v3, s36, 11, v2
	global_store_dwordx4 v3, v[36:39], s[96:97] sc1
	global_store_dwordx4 v3, v[44:47], s[96:97] offset:1024 sc1
	v_pk_add_f32 v[52:53], v[52:53], v[232:233] op_sel_hi:[1,0] neg_lo:[0,1] neg_hi:[0,1]
	v_pk_add_f32 v[54:55], v[54:55], v[232:233] op_sel_hi:[1,0] neg_lo:[0,1] neg_hi:[0,1]
	v_pk_add_f32 v[56:57], v[56:57], v[232:233] op_sel_hi:[1,0] neg_lo:[0,1] neg_hi:[0,1]
	v_pk_add_f32 v[58:59], v[58:59], v[232:233] op_sel_hi:[1,0] neg_lo:[0,1] neg_hi:[0,1]
	v_pk_add_f32 v[60:61], v[60:61], v[232:233] op_sel_hi:[1,0] neg_lo:[0,1] neg_hi:[0,1]
	v_pk_add_f32 v[62:63], v[62:63], v[232:233] op_sel_hi:[1,0] neg_lo:[0,1] neg_hi:[0,1]
	v_pk_add_f32 v[64:65], v[64:65], v[232:233] op_sel_hi:[1,0] neg_lo:[0,1] neg_hi:[0,1]
	v_pk_add_f32 v[66:67], v[66:67], v[232:233] op_sel_hi:[1,0] neg_lo:[0,1] neg_hi:[0,1]
	v_pk_mul_f32 v[52:53], v[52:53], v[232:233] op_sel:[0,1] op_sel_hi:[1,1]
	v_pk_mul_f32 v[54:55], v[54:55], v[232:233] op_sel:[0,1] op_sel_hi:[1,1]
	v_pk_mul_f32 v[56:57], v[56:57], v[232:233] op_sel:[0,1] op_sel_hi:[1,1]
	v_pk_mul_f32 v[58:59], v[58:59], v[232:233] op_sel:[0,1] op_sel_hi:[1,1]
	v_pk_mul_f32 v[60:61], v[60:61], v[232:233] op_sel:[0,1] op_sel_hi:[1,1]
	v_pk_mul_f32 v[62:63], v[62:63], v[232:233] op_sel:[0,1] op_sel_hi:[1,1]
	v_pk_mul_f32 v[64:65], v[64:65], v[232:233] op_sel:[0,1] op_sel_hi:[1,1]
	v_pk_mul_f32 v[66:67], v[66:67], v[232:233] op_sel:[0,1] op_sel_hi:[1,1]
	v_pk_fma_f32 v[52:53], v[4:5], v[52:53], v[20:21]
	v_pk_fma_f32 v[54:55], v[6:7], v[54:55], v[22:23]
	v_pk_fma_f32 v[56:57], v[8:9], v[56:57], v[24:25]
	v_pk_fma_f32 v[58:59], v[10:11], v[58:59], v[26:27]
	v_pk_fma_f32 v[60:61], v[12:13], v[60:61], v[28:29]
	v_pk_fma_f32 v[62:63], v[14:15], v[62:63], v[30:31]
	v_pk_fma_f32 v[64:65], v[16:17], v[64:65], v[32:33]
	v_pk_fma_f32 v[66:67], v[18:19], v[66:67], v[34:35]
	v_cvt_pk_bf16_f32 v52, v52, v53
	v_cvt_pk_bf16_f32 v53, v54, v55
	v_cvt_pk_bf16_f32 v54, v56, v57
	v_cvt_pk_bf16_f32 v55, v58, v59
	v_cvt_pk_bf16_f32 v60, v60, v61
	v_cvt_pk_bf16_f32 v61, v62, v63
	v_cvt_pk_bf16_f32 v62, v64, v65
	v_cvt_pk_bf16_f32 v63, v66, v67
	v_lshl_add_u32 v3, s37, 11, v2
	global_store_dwordx4 v3, v[52:55], s[96:97] sc1
	global_store_dwordx4 v3, v[60:63], s[96:97] offset:1024 sc1
	v_pk_add_f32 v[68:69], v[68:69], v[234:235] op_sel_hi:[1,0] neg_lo:[0,1] neg_hi:[0,1]
	v_pk_add_f32 v[70:71], v[70:71], v[234:235] op_sel_hi:[1,0] neg_lo:[0,1] neg_hi:[0,1]
	v_pk_add_f32 v[72:73], v[72:73], v[234:235] op_sel_hi:[1,0] neg_lo:[0,1] neg_hi:[0,1]
	v_pk_add_f32 v[74:75], v[74:75], v[234:235] op_sel_hi:[1,0] neg_lo:[0,1] neg_hi:[0,1]
	v_pk_add_f32 v[76:77], v[76:77], v[234:235] op_sel_hi:[1,0] neg_lo:[0,1] neg_hi:[0,1]
	v_pk_add_f32 v[78:79], v[78:79], v[234:235] op_sel_hi:[1,0] neg_lo:[0,1] neg_hi:[0,1]
	v_pk_add_f32 v[80:81], v[80:81], v[234:235] op_sel_hi:[1,0] neg_lo:[0,1] neg_hi:[0,1]
	v_pk_add_f32 v[82:83], v[82:83], v[234:235] op_sel_hi:[1,0] neg_lo:[0,1] neg_hi:[0,1]
	v_pk_mul_f32 v[68:69], v[68:69], v[234:235] op_sel:[0,1] op_sel_hi:[1,1]
	v_pk_mul_f32 v[70:71], v[70:71], v[234:235] op_sel:[0,1] op_sel_hi:[1,1]
	v_pk_mul_f32 v[72:73], v[72:73], v[234:235] op_sel:[0,1] op_sel_hi:[1,1]
	v_pk_mul_f32 v[74:75], v[74:75], v[234:235] op_sel:[0,1] op_sel_hi:[1,1]
	v_pk_mul_f32 v[76:77], v[76:77], v[234:235] op_sel:[0,1] op_sel_hi:[1,1]
	v_pk_mul_f32 v[78:79], v[78:79], v[234:235] op_sel:[0,1] op_sel_hi:[1,1]
	v_pk_mul_f32 v[80:81], v[80:81], v[234:235] op_sel:[0,1] op_sel_hi:[1,1]
	v_pk_mul_f32 v[82:83], v[82:83], v[234:235] op_sel:[0,1] op_sel_hi:[1,1]
	v_pk_fma_f32 v[68:69], v[4:5], v[68:69], v[20:21]
	v_pk_fma_f32 v[70:71], v[6:7], v[70:71], v[22:23]
	v_pk_fma_f32 v[72:73], v[8:9], v[72:73], v[24:25]
	v_pk_fma_f32 v[74:75], v[10:11], v[74:75], v[26:27]
	v_pk_fma_f32 v[76:77], v[12:13], v[76:77], v[28:29]
	v_pk_fma_f32 v[78:79], v[14:15], v[78:79], v[30:31]
	v_pk_fma_f32 v[80:81], v[16:17], v[80:81], v[32:33]
	v_pk_fma_f32 v[82:83], v[18:19], v[82:83], v[34:35]
	v_cvt_pk_bf16_f32 v68, v68, v69
	v_cvt_pk_bf16_f32 v69, v70, v71
	v_cvt_pk_bf16_f32 v70, v72, v73
	v_cvt_pk_bf16_f32 v71, v74, v75
	v_cvt_pk_bf16_f32 v76, v76, v77
	v_cvt_pk_bf16_f32 v77, v78, v79
	v_cvt_pk_bf16_f32 v78, v80, v81
	v_cvt_pk_bf16_f32 v79, v82, v83
	v_lshl_add_u32 v3, s38, 11, v2
	global_store_dwordx4 v3, v[68:71], s[96:97] sc1
	global_store_dwordx4 v3, v[76:79], s[96:97] offset:1024 sc1
	v_pk_add_f32 v[84:85], v[84:85], v[236:237] op_sel_hi:[1,0] neg_lo:[0,1] neg_hi:[0,1]
	v_pk_add_f32 v[86:87], v[86:87], v[236:237] op_sel_hi:[1,0] neg_lo:[0,1] neg_hi:[0,1]
	v_pk_add_f32 v[88:89], v[88:89], v[236:237] op_sel_hi:[1,0] neg_lo:[0,1] neg_hi:[0,1]
	v_pk_add_f32 v[90:91], v[90:91], v[236:237] op_sel_hi:[1,0] neg_lo:[0,1] neg_hi:[0,1]
	v_pk_add_f32 v[92:93], v[92:93], v[236:237] op_sel_hi:[1,0] neg_lo:[0,1] neg_hi:[0,1]
	v_pk_add_f32 v[94:95], v[94:95], v[236:237] op_sel_hi:[1,0] neg_lo:[0,1] neg_hi:[0,1]
	v_pk_add_f32 v[96:97], v[96:97], v[236:237] op_sel_hi:[1,0] neg_lo:[0,1] neg_hi:[0,1]
	v_pk_add_f32 v[98:99], v[98:99], v[236:237] op_sel_hi:[1,0] neg_lo:[0,1] neg_hi:[0,1]
	v_pk_mul_f32 v[84:85], v[84:85], v[236:237] op_sel:[0,1] op_sel_hi:[1,1]
	v_pk_mul_f32 v[86:87], v[86:87], v[236:237] op_sel:[0,1] op_sel_hi:[1,1]
	v_pk_mul_f32 v[88:89], v[88:89], v[236:237] op_sel:[0,1] op_sel_hi:[1,1]
	v_pk_mul_f32 v[90:91], v[90:91], v[236:237] op_sel:[0,1] op_sel_hi:[1,1]
	v_pk_mul_f32 v[92:93], v[92:93], v[236:237] op_sel:[0,1] op_sel_hi:[1,1]
	v_pk_mul_f32 v[94:95], v[94:95], v[236:237] op_sel:[0,1] op_sel_hi:[1,1]
	v_pk_mul_f32 v[96:97], v[96:97], v[236:237] op_sel:[0,1] op_sel_hi:[1,1]
	v_pk_mul_f32 v[98:99], v[98:99], v[236:237] op_sel:[0,1] op_sel_hi:[1,1]
	v_pk_fma_f32 v[84:85], v[4:5], v[84:85], v[20:21]
	v_pk_fma_f32 v[86:87], v[6:7], v[86:87], v[22:23]
	v_pk_fma_f32 v[88:89], v[8:9], v[88:89], v[24:25]
	v_pk_fma_f32 v[90:91], v[10:11], v[90:91], v[26:27]
	v_pk_fma_f32 v[92:93], v[12:13], v[92:93], v[28:29]
	v_pk_fma_f32 v[94:95], v[14:15], v[94:95], v[30:31]
	v_pk_fma_f32 v[96:97], v[16:17], v[96:97], v[32:33]
	v_pk_fma_f32 v[98:99], v[18:19], v[98:99], v[34:35]
	v_cvt_pk_bf16_f32 v84, v84, v85
	v_cvt_pk_bf16_f32 v85, v86, v87
	v_cvt_pk_bf16_f32 v86, v88, v89
	v_cvt_pk_bf16_f32 v87, v90, v91
	v_cvt_pk_bf16_f32 v92, v92, v93
	v_cvt_pk_bf16_f32 v93, v94, v95
	v_cvt_pk_bf16_f32 v94, v96, v97
	v_cvt_pk_bf16_f32 v95, v98, v99
	v_lshl_add_u32 v3, s39, 11, v2
	global_store_dwordx4 v3, v[84:87], s[96:97] sc1
	global_store_dwordx4 v3, v[92:95], s[96:97] offset:1024 sc1
	s_mov_b64 s[52:53], exec
	s_mov_b64 exec, 1
	v_mov_b32_e32 v3, s36
	v_lshlrev_b32_e32 v3, 3, v3
	global_store_dwordx2 v3, v[230:231], s[92:93] sc1
	v_mov_b32_e32 v3, s37
	v_lshlrev_b32_e32 v3, 3, v3
	global_store_dwordx2 v3, v[232:233], s[92:93] sc1
	v_mov_b32_e32 v3, s38
	v_lshlrev_b32_e32 v3, 3, v3
	global_store_dwordx2 v3, v[234:235], s[92:93] sc1
	v_mov_b32_e32 v3, s39
	v_lshlrev_b32_e32 v3, 3, v3
	global_store_dwordx2 v3, v[236:237], s[92:93] sc1
	s_mov_b64 exec, s[52:53]
	s_waitcnt vmcnt(12)
	v_pk_add_f32 v[108:109], v[156:157], v[158:159]
	v_pk_add_f32 v[110:111], v[160:161], v[162:163]
	v_pk_add_f32 v[112:113], v[164:165], v[166:167]
	v_pk_add_f32 v[114:115], v[168:169], v[170:171]
	v_pk_mul_f32 v[116:117], v[156:157], v[156:157]
	v_pk_fma_f32 v[116:117], v[158:159], v[158:159], v[116:117]
	v_pk_fma_f32 v[116:117], v[160:161], v[160:161], v[116:117]
	v_pk_fma_f32 v[116:117], v[162:163], v[162:163], v[116:117]
	v_pk_fma_f32 v[116:117], v[164:165], v[164:165], v[116:117]
	v_pk_fma_f32 v[116:117], v[166:167], v[166:167], v[116:117]
	v_pk_fma_f32 v[116:117], v[168:169], v[168:169], v[116:117]
	v_pk_fma_f32 v[116:117], v[170:171], v[170:171], v[116:117]
	v_pk_add_f32 v[108:109], v[108:109], v[110:111]
	v_pk_add_f32 v[112:113], v[112:113], v[114:115]
	v_pk_add_f32 v[108:109], v[108:109], v[112:113]
	v_add_f32_e32 v100, v108, v109
	v_add_f32_e32 v101, v116, v117
	v_pk_add_f32 v[108:109], v[172:173], v[174:175]
	v_pk_add_f32 v[110:111], v[176:177], v[178:179]
	v_pk_add_f32 v[112:113], v[180:181], v[182:183]
	v_pk_add_f32 v[114:115], v[184:185], v[186:187]
	v_pk_mul_f32 v[116:117], v[172:173], v[172:173]
	v_pk_fma_f32 v[116:117], v[174:175], v[174:175], v[116:117]
	v_pk_fma_f32 v[116:117], v[176:177], v[176:177], v[116:117]
	v_pk_fma_f32 v[116:117], v[178:179], v[178:179], v[116:117]
	v_pk_fma_f32 v[116:117], v[180:181], v[180:181], v[116:117]
	v_pk_fma_f32 v[116:117], v[182:183], v[182:183], v[116:117]
	v_pk_fma_f32 v[116:117], v[184:185], v[184:185], v[116:117]
	v_pk_fma_f32 v[116:117], v[186:187], v[186:187], v[116:117]
	v_pk_add_f32 v[108:109], v[108:109], v[110:111]
	v_pk_add_f32 v[112:113], v[112:113], v[114:115]
	v_pk_add_f32 v[108:109], v[108:109], v[112:113]
	v_add_f32_e32 v102, v108, v109
	v_add_f32_e32 v103, v116, v117
	v_pk_add_f32 v[108:109], v[188:189], v[190:191]
	v_pk_add_f32 v[110:111], v[192:193], v[194:195]
	v_pk_add_f32 v[112:113], v[196:197], v[198:199]
	v_pk_add_f32 v[114:115], v[200:201], v[202:203]
	v_pk_mul_f32 v[116:117], v[188:189], v[188:189]
	v_pk_fma_f32 v[116:117], v[190:191], v[190:191], v[116:117]
	v_pk_fma_f32 v[116:117], v[192:193], v[192:193], v[116:117]
	v_pk_fma_f32 v[116:117], v[194:195], v[194:195], v[116:117]
	v_pk_fma_f32 v[116:117], v[196:197], v[196:197], v[116:117]
	v_pk_fma_f32 v[116:117], v[198:199], v[198:199], v[116:117]
	v_pk_fma_f32 v[116:117], v[200:201], v[200:201], v[116:117]
	v_pk_fma_f32 v[116:117], v[202:203], v[202:203], v[116:117]
	v_pk_add_f32 v[108:109], v[108:109], v[110:111]
	v_pk_add_f32 v[112:113], v[112:113], v[114:115]
	v_pk_add_f32 v[108:109], v[108:109], v[112:113]
	v_add_f32_e32 v104, v108, v109
	v_add_f32_e32 v105, v116, v117
	v_pk_add_f32 v[108:109], v[204:205], v[206:207]
	v_pk_add_f32 v[110:111], v[208:209], v[210:211]
	v_pk_add_f32 v[112:113], v[212:213], v[214:215]
	v_pk_add_f32 v[114:115], v[216:217], v[218:219]
	v_pk_mul_f32 v[116:117], v[204:205], v[204:205]
	v_pk_fma_f32 v[116:117], v[206:207], v[206:207], v[116:117]
	v_pk_fma_f32 v[116:117], v[208:209], v[208:209], v[116:117]
	v_pk_fma_f32 v[116:117], v[210:211], v[210:211], v[116:117]
	v_pk_fma_f32 v[116:117], v[212:213], v[212:213], v[116:117]
	v_pk_fma_f32 v[116:117], v[214:215], v[214:215], v[116:117]
	v_pk_fma_f32 v[116:117], v[216:217], v[216:217], v[116:117]
	v_pk_fma_f32 v[116:117], v[218:219], v[218:219], v[116:117]
	v_pk_add_f32 v[108:109], v[108:109], v[110:111]
	v_pk_add_f32 v[112:113], v[112:113], v[114:115]
	v_pk_add_f32 v[108:109], v[108:109], v[112:113]
	v_add_f32_e32 v106, v108, v109
	v_add_f32_e32 v107, v116, v117
	v_add_f32_dpp v100, v100, v100 quad_perm:[1,0,3,2] row_mask:0xf bank_mask:0xf
	v_add_f32_dpp v101, v101, v101 quad_perm:[1,0,3,2] row_mask:0xf bank_mask:0xf
	v_add_f32_dpp v102, v102, v102 quad_perm:[1,0,3,2] row_mask:0xf bank_mask:0xf
	v_add_f32_dpp v103, v103, v103 quad_perm:[1,0,3,2] row_mask:0xf bank_mask:0xf
	v_add_f32_dpp v104, v104, v104 quad_perm:[1,0,3,2] row_mask:0xf bank_mask:0xf
	v_add_f32_dpp v105, v105, v105 quad_perm:[1,0,3,2] row_mask:0xf bank_mask:0xf
	v_add_f32_dpp v106, v106, v106 quad_perm:[1,0,3,2] row_mask:0xf bank_mask:0xf
	v_add_f32_dpp v107, v107, v107 quad_perm:[1,0,3,2] row_mask:0xf bank_mask:0xf
	v_add_f32_dpp v100, v100, v100 quad_perm:[2,3,0,1] row_mask:0xf bank_mask:0xf
	v_add_f32_dpp v101, v101, v101 quad_perm:[2,3,0,1] row_mask:0xf bank_mask:0xf
	v_add_f32_dpp v102, v102, v102 quad_perm:[2,3,0,1] row_mask:0xf bank_mask:0xf
	v_add_f32_dpp v103, v103, v103 quad_perm:[2,3,0,1] row_mask:0xf bank_mask:0xf
	v_add_f32_dpp v104, v104, v104 quad_perm:[2,3,0,1] row_mask:0xf bank_mask:0xf
	v_add_f32_dpp v105, v105, v105 quad_perm:[2,3,0,1] row_mask:0xf bank_mask:0xf
	v_add_f32_dpp v106, v106, v106 quad_perm:[2,3,0,1] row_mask:0xf bank_mask:0xf
	v_add_f32_dpp v107, v107, v107 quad_perm:[2,3,0,1] row_mask:0xf bank_mask:0xf
	v_add_f32_dpp v100, v100, v100 row_half_mirror row_mask:0xf bank_mask:0xf
	v_add_f32_dpp v101, v101, v101 row_half_mirror row_mask:0xf bank_mask:0xf
	v_add_f32_dpp v102, v102, v102 row_half_mirror row_mask:0xf bank_mask:0xf
	v_add_f32_dpp v103, v103, v103 row_half_mirror row_mask:0xf bank_mask:0xf
	v_add_f32_dpp v104, v104, v104 row_half_mirror row_mask:0xf bank_mask:0xf
	v_add_f32_dpp v105, v105, v105 row_half_mirror row_mask:0xf bank_mask:0xf
	v_add_f32_dpp v106, v106, v106 row_half_mirror row_mask:0xf bank_mask:0xf
	v_add_f32_dpp v107, v107, v107 row_half_mirror row_mask:0xf bank_mask:0xf
	v_add_f32_dpp v100, v100, v100 row_mirror row_mask:0xf bank_mask:0xf
	v_add_f32_dpp v101, v101, v101 row_mirror row_mask:0xf bank_mask:0xf
	v_add_f32_dpp v102, v102, v102 row_mirror row_mask:0xf bank_mask:0xf
	v_add_f32_dpp v103, v103, v103 row_mirror row_mask:0xf bank_mask:0xf
	v_add_f32_dpp v104, v104, v104 row_mirror row_mask:0xf bank_mask:0xf
	v_add_f32_dpp v105, v105, v105 row_mirror row_mask:0xf bank_mask:0xf
	v_add_f32_dpp v106, v106, v106 row_mirror row_mask:0xf bank_mask:0xf
	v_add_f32_dpp v107, v107, v107 row_mirror row_mask:0xf bank_mask:0xf
	v_mov_b32_e32 v108, v100
	v_mov_b32_e32 v109, v101
	v_mov_b32_e32 v110, v102
	v_mov_b32_e32 v111, v103
	v_mov_b32_e32 v112, v104
	v_mov_b32_e32 v113, v105
	v_mov_b32_e32 v114, v106
	v_mov_b32_e32 v115, v107
	s_nop 1
	v_permlane16_swap_b32_e32 v108, v100
	v_permlane16_swap_b32_e32 v109, v101
	v_permlane16_swap_b32_e32 v110, v102
	v_permlane16_swap_b32_e32 v111, v103
	v_permlane16_swap_b32_e32 v112, v104
	v_permlane16_swap_b32_e32 v113, v105
	v_permlane16_swap_b32_e32 v114, v106
	v_permlane16_swap_b32_e32 v115, v107
	v_add_f32_e32 v100, v100, v108
	v_add_f32_e32 v101, v101, v109
	v_add_f32_e32 v102, v102, v110
	v_add_f32_e32 v103, v103, v111
	v_add_f32_e32 v104, v104, v112
	v_add_f32_e32 v105, v105, v113
	v_add_f32_e32 v106, v106, v114
	v_add_f32_e32 v107, v107, v115
	v_mov_b32_e32 v108, v100
	v_mov_b32_e32 v109, v101
	v_mov_b32_e32 v110, v102
	v_mov_b32_e32 v111, v103
	v_mov_b32_e32 v112, v104
	v_mov_b32_e32 v113, v105
	v_mov_b32_e32 v114, v106
	v_mov_b32_e32 v115, v107
	s_nop 1
	v_permlane32_swap_b32_e32 v108, v100
	v_permlane32_swap_b32_e32 v109, v101
	v_permlane32_swap_b32_e32 v110, v102
	v_permlane32_swap_b32_e32 v111, v103
	v_permlane32_swap_b32_e32 v112, v104
	v_permlane32_swap_b32_e32 v113, v105
	v_permlane32_swap_b32_e32 v114, v106
	v_permlane32_swap_b32_e32 v115, v107
	v_add_f32_e32 v100, v100, v108
	v_add_f32_e32 v101, v101, v109
	v_add_f32_e32 v102, v102, v110
	v_add_f32_e32 v103, v103, v111
	v_add_f32_e32 v104, v104, v112
	v_add_f32_e32 v105, v105, v113
	v_add_f32_e32 v106, v106, v114
	v_add_f32_e32 v107, v107, v115
	v_mul_f32_e32 v238, 0x3a800000, v100
	v_mul_f32_e32 v116, 0x3a800000, v101
	v_fma_f32 v116, -v238, v238, v116
	v_max_f32_e32 v116, 0, v116
	v_add_f32_e32 v116, 0x3727c5ac, v116
	v_mul_f32_e32 v240, 0x3a800000, v102
	v_mul_f32_e32 v118, 0x3a800000, v103
	v_fma_f32 v118, -v240, v240, v118
	v_max_f32_e32 v118, 0, v118
	v_add_f32_e32 v118, 0x3727c5ac, v118
	v_mul_f32_e32 v242, 0x3a800000, v104
	v_mul_f32_e32 v120, 0x3a800000, v105
	v_fma_f32 v120, -v242, v242, v120
	v_max_f32_e32 v120, 0, v120
	v_add_f32_e32 v120, 0x3727c5ac, v120
	v_mul_f32_e32 v244, 0x3a800000, v106
	v_mul_f32_e32 v122, 0x3a800000, v107
	v_fma_f32 v122, -v244, v244, v122
	v_max_f32_e32 v122, 0, v122
	v_add_f32_e32 v122, 0x3727c5ac, v122
	v_rsq_f32_e32 v117, v116
	v_rsq_f32_e32 v119, v118
	v_rsq_f32_e32 v121, v120
	v_rsq_f32_e32 v123, v122
	s_nop 0
	v_mul_f32_e32 v124, v116, v117
	v_mul_f32_e32 v124, v124, v117
	v_fmaak_f32 v124, -0.5, v124, 0x3fc00000
	v_mul_f32_e32 v239, v117, v124
	v_mul_f32_e32 v125, v118, v119
	v_mul_f32_e32 v125, v125, v119
	v_fmaak_f32 v125, -0.5, v125, 0x3fc00000
	v_mul_f32_e32 v241, v119, v125
	v_mul_f32_e32 v126, v120, v121
	v_mul_f32_e32 v126, v126, v121
	v_fmaak_f32 v126, -0.5, v126, 0x3fc00000
	v_mul_f32_e32 v243, v121, v126
	v_mul_f32_e32 v127, v122, v123
	v_mul_f32_e32 v127, v127, v123
	v_fmaak_f32 v127, -0.5, v127, 0x3fc00000
	v_mul_f32_e32 v245, v123, v127
	v_pk_add_f32 v[156:157], v[156:157], v[238:239] op_sel_hi:[1,0] neg_lo:[0,1] neg_hi:[0,1]
	v_pk_add_f32 v[158:159], v[158:159], v[238:239] op_sel_hi:[1,0] neg_lo:[0,1] neg_hi:[0,1]
	v_pk_add_f32 v[160:161], v[160:161], v[238:239] op_sel_hi:[1,0] neg_lo:[0,1] neg_hi:[0,1]
	v_pk_add_f32 v[162:163], v[162:163], v[238:239] op_sel_hi:[1,0] neg_lo:[0,1] neg_hi:[0,1]
	v_pk_add_f32 v[164:165], v[164:165], v[238:239] op_sel_hi:[1,0] neg_lo:[0,1] neg_hi:[0,1]
	v_pk_add_f32 v[166:167], v[166:167], v[238:239] op_sel_hi:[1,0] neg_lo:[0,1] neg_hi:[0,1]
	v_pk_add_f32 v[168:169], v[168:169], v[238:239] op_sel_hi:[1,0] neg_lo:[0,1] neg_hi:[0,1]
	v_pk_add_f32 v[170:171], v[170:171], v[238:239] op_sel_hi:[1,0] neg_lo:[0,1] neg_hi:[0,1]
	v_pk_mul_f32 v[156:157], v[156:157], v[238:239] op_sel:[0,1] op_sel_hi:[1,1]
	v_pk_mul_f32 v[158:159], v[158:159], v[238:239] op_sel:[0,1] op_sel_hi:[1,1]
	v_pk_mul_f32 v[160:161], v[160:161], v[238:239] op_sel:[0,1] op_sel_hi:[1,1]
	v_pk_mul_f32 v[162:163], v[162:163], v[238:239] op_sel:[0,1] op_sel_hi:[1,1]
	v_pk_mul_f32 v[164:165], v[164:165], v[238:239] op_sel:[0,1] op_sel_hi:[1,1]
	v_pk_mul_f32 v[166:167], v[166:167], v[238:239] op_sel:[0,1] op_sel_hi:[1,1]
	v_pk_mul_f32 v[168:169], v[168:169], v[238:239] op_sel:[0,1] op_sel_hi:[1,1]
	v_pk_mul_f32 v[170:171], v[170:171], v[238:239] op_sel:[0,1] op_sel_hi:[1,1]
	v_pk_fma_f32 v[156:157], v[4:5], v[156:157], v[20:21]
	v_pk_fma_f32 v[158:159], v[6:7], v[158:159], v[22:23]
	v_pk_fma_f32 v[160:161], v[8:9], v[160:161], v[24:25]
	v_pk_fma_f32 v[162:163], v[10:11], v[162:163], v[26:27]
	v_pk_fma_f32 v[164:165], v[12:13], v[164:165], v[28:29]
	v_pk_fma_f32 v[166:167], v[14:15], v[166:167], v[30:31]
	v_pk_fma_f32 v[168:169], v[16:17], v[168:169], v[32:33]
	v_pk_fma_f32 v[170:171], v[18:19], v[170:171], v[34:35]
	v_cvt_pk_bf16_f32 v156, v156, v157
	v_cvt_pk_bf16_f32 v157, v158, v159
	v_cvt_pk_bf16_f32 v158, v160, v161
	v_cvt_pk_bf16_f32 v159, v162, v163
	v_cvt_pk_bf16_f32 v164, v164, v165
	v_cvt_pk_bf16_f32 v165, v166, v167
	v_cvt_pk_bf16_f32 v166, v168, v169
	v_cvt_pk_bf16_f32 v167, v170, v171
	v_lshl_add_u32 v3, s40, 11, v2
	global_store_dwordx4 v3, v[156:159], s[96:97] sc1
	global_store_dwordx4 v3, v[164:167], s[96:97] offset:1024 sc1
	v_pk_add_f32 v[172:173], v[172:173], v[240:241] op_sel_hi:[1,0] neg_lo:[0,1] neg_hi:[0,1]
	v_pk_add_f32 v[174:175], v[174:175], v[240:241] op_sel_hi:[1,0] neg_lo:[0,1] neg_hi:[0,1]
	v_pk_add_f32 v[176:177], v[176:177], v[240:241] op_sel_hi:[1,0] neg_lo:[0,1] neg_hi:[0,1]
	v_pk_add_f32 v[178:179], v[178:179], v[240:241] op_sel_hi:[1,0] neg_lo:[0,1] neg_hi:[0,1]
	v_pk_add_f32 v[180:181], v[180:181], v[240:241] op_sel_hi:[1,0] neg_lo:[0,1] neg_hi:[0,1]
	v_pk_add_f32 v[182:183], v[182:183], v[240:241] op_sel_hi:[1,0] neg_lo:[0,1] neg_hi:[0,1]
	v_pk_add_f32 v[184:185], v[184:185], v[240:241] op_sel_hi:[1,0] neg_lo:[0,1] neg_hi:[0,1]
	v_pk_add_f32 v[186:187], v[186:187], v[240:241] op_sel_hi:[1,0] neg_lo:[0,1] neg_hi:[0,1]
	v_pk_mul_f32 v[172:173], v[172:173], v[240:241] op_sel:[0,1] op_sel_hi:[1,1]
	v_pk_mul_f32 v[174:175], v[174:175], v[240:241] op_sel:[0,1] op_sel_hi:[1,1]
	v_pk_mul_f32 v[176:177], v[176:177], v[240:241] op_sel:[0,1] op_sel_hi:[1,1]
	v_pk_mul_f32 v[178:179], v[178:179], v[240:241] op_sel:[0,1] op_sel_hi:[1,1]
	v_pk_mul_f32 v[180:181], v[180:181], v[240:241] op_sel:[0,1] op_sel_hi:[1,1]
	v_pk_mul_f32 v[182:183], v[182:183], v[240:241] op_sel:[0,1] op_sel_hi:[1,1]
	v_pk_mul_f32 v[184:185], v[184:185], v[240:241] op_sel:[0,1] op_sel_hi:[1,1]
	v_pk_mul_f32 v[186:187], v[186:187], v[240:241] op_sel:[0,1] op_sel_hi:[1,1]
	v_pk_fma_f32 v[172:173], v[4:5], v[172:173], v[20:21]
	v_pk_fma_f32 v[174:175], v[6:7], v[174:175], v[22:23]
	v_pk_fma_f32 v[176:177], v[8:9], v[176:177], v[24:25]
	v_pk_fma_f32 v[178:179], v[10:11], v[178:179], v[26:27]
	v_pk_fma_f32 v[180:181], v[12:13], v[180:181], v[28:29]
	v_pk_fma_f32 v[182:183], v[14:15], v[182:183], v[30:31]
	v_pk_fma_f32 v[184:185], v[16:17], v[184:185], v[32:33]
	v_pk_fma_f32 v[186:187], v[18:19], v[186:187], v[34:35]
	v_cvt_pk_bf16_f32 v172, v172, v173
	v_cvt_pk_bf16_f32 v173, v174, v175
	v_cvt_pk_bf16_f32 v174, v176, v177
	v_cvt_pk_bf16_f32 v175, v178, v179
	v_cvt_pk_bf16_f32 v180, v180, v181
	v_cvt_pk_bf16_f32 v181, v182, v183
	v_cvt_pk_bf16_f32 v182, v184, v185
	v_cvt_pk_bf16_f32 v183, v186, v187
	v_lshl_add_u32 v3, s41, 11, v2
	global_store_dwordx4 v3, v[172:175], s[96:97] sc1
	global_store_dwordx4 v3, v[180:183], s[96:97] offset:1024 sc1
	v_pk_add_f32 v[188:189], v[188:189], v[242:243] op_sel_hi:[1,0] neg_lo:[0,1] neg_hi:[0,1]
	v_pk_add_f32 v[190:191], v[190:191], v[242:243] op_sel_hi:[1,0] neg_lo:[0,1] neg_hi:[0,1]
	v_pk_add_f32 v[192:193], v[192:193], v[242:243] op_sel_hi:[1,0] neg_lo:[0,1] neg_hi:[0,1]
	v_pk_add_f32 v[194:195], v[194:195], v[242:243] op_sel_hi:[1,0] neg_lo:[0,1] neg_hi:[0,1]
	v_pk_add_f32 v[196:197], v[196:197], v[242:243] op_sel_hi:[1,0] neg_lo:[0,1] neg_hi:[0,1]
	v_pk_add_f32 v[198:199], v[198:199], v[242:243] op_sel_hi:[1,0] neg_lo:[0,1] neg_hi:[0,1]
	v_pk_add_f32 v[200:201], v[200:201], v[242:243] op_sel_hi:[1,0] neg_lo:[0,1] neg_hi:[0,1]
	v_pk_add_f32 v[202:203], v[202:203], v[242:243] op_sel_hi:[1,0] neg_lo:[0,1] neg_hi:[0,1]
	v_pk_mul_f32 v[188:189], v[188:189], v[242:243] op_sel:[0,1] op_sel_hi:[1,1]
	v_pk_mul_f32 v[190:191], v[190:191], v[242:243] op_sel:[0,1] op_sel_hi:[1,1]
	v_pk_mul_f32 v[192:193], v[192:193], v[242:243] op_sel:[0,1] op_sel_hi:[1,1]
	v_pk_mul_f32 v[194:195], v[194:195], v[242:243] op_sel:[0,1] op_sel_hi:[1,1]
	v_pk_mul_f32 v[196:197], v[196:197], v[242:243] op_sel:[0,1] op_sel_hi:[1,1]
	v_pk_mul_f32 v[198:199], v[198:199], v[242:243] op_sel:[0,1] op_sel_hi:[1,1]
	v_pk_mul_f32 v[200:201], v[200:201], v[242:243] op_sel:[0,1] op_sel_hi:[1,1]
	v_pk_mul_f32 v[202:203], v[202:203], v[242:243] op_sel:[0,1] op_sel_hi:[1,1]
	v_pk_fma_f32 v[188:189], v[4:5], v[188:189], v[20:21]
	v_pk_fma_f32 v[190:191], v[6:7], v[190:191], v[22:23]
	v_pk_fma_f32 v[192:193], v[8:9], v[192:193], v[24:25]
	v_pk_fma_f32 v[194:195], v[10:11], v[194:195], v[26:27]
	v_pk_fma_f32 v[196:197], v[12:13], v[196:197], v[28:29]
	v_pk_fma_f32 v[198:199], v[14:15], v[198:199], v[30:31]
	v_pk_fma_f32 v[200:201], v[16:17], v[200:201], v[32:33]
	v_pk_fma_f32 v[202:203], v[18:19], v[202:203], v[34:35]
	v_cvt_pk_bf16_f32 v188, v188, v189
	v_cvt_pk_bf16_f32 v189, v190, v191
	v_cvt_pk_bf16_f32 v190, v192, v193
	v_cvt_pk_bf16_f32 v191, v194, v195
	v_cvt_pk_bf16_f32 v196, v196, v197
	v_cvt_pk_bf16_f32 v197, v198, v199
	v_cvt_pk_bf16_f32 v198, v200, v201
	v_cvt_pk_bf16_f32 v199, v202, v203
	v_lshl_add_u32 v3, s42, 11, v2
	global_store_dwordx4 v3, v[188:191], s[96:97] sc1
	global_store_dwordx4 v3, v[196:199], s[96:97] offset:1024 sc1
	v_pk_add_f32 v[204:205], v[204:205], v[244:245] op_sel_hi:[1,0] neg_lo:[0,1] neg_hi:[0,1]
	v_pk_add_f32 v[206:207], v[206:207], v[244:245] op_sel_hi:[1,0] neg_lo:[0,1] neg_hi:[0,1]
	v_pk_add_f32 v[208:209], v[208:209], v[244:245] op_sel_hi:[1,0] neg_lo:[0,1] neg_hi:[0,1]
	v_pk_add_f32 v[210:211], v[210:211], v[244:245] op_sel_hi:[1,0] neg_lo:[0,1] neg_hi:[0,1]
	v_pk_add_f32 v[212:213], v[212:213], v[244:245] op_sel_hi:[1,0] neg_lo:[0,1] neg_hi:[0,1]
	v_pk_add_f32 v[214:215], v[214:215], v[244:245] op_sel_hi:[1,0] neg_lo:[0,1] neg_hi:[0,1]
	v_pk_add_f32 v[216:217], v[216:217], v[244:245] op_sel_hi:[1,0] neg_lo:[0,1] neg_hi:[0,1]
	v_pk_add_f32 v[218:219], v[218:219], v[244:245] op_sel_hi:[1,0] neg_lo:[0,1] neg_hi:[0,1]
	v_pk_mul_f32 v[204:205], v[204:205], v[244:245] op_sel:[0,1] op_sel_hi:[1,1]
	v_pk_mul_f32 v[206:207], v[206:207], v[244:245] op_sel:[0,1] op_sel_hi:[1,1]
	v_pk_mul_f32 v[208:209], v[208:209], v[244:245] op_sel:[0,1] op_sel_hi:[1,1]
	v_pk_mul_f32 v[210:211], v[210:211], v[244:245] op_sel:[0,1] op_sel_hi:[1,1]
	v_pk_mul_f32 v[212:213], v[212:213], v[244:245] op_sel:[0,1] op_sel_hi:[1,1]
	v_pk_mul_f32 v[214:215], v[214:215], v[244:245] op_sel:[0,1] op_sel_hi:[1,1]
	v_pk_mul_f32 v[216:217], v[216:217], v[244:245] op_sel:[0,1] op_sel_hi:[1,1]
	v_pk_mul_f32 v[218:219], v[218:219], v[244:245] op_sel:[0,1] op_sel_hi:[1,1]
	v_pk_fma_f32 v[204:205], v[4:5], v[204:205], v[20:21]
	v_pk_fma_f32 v[206:207], v[6:7], v[206:207], v[22:23]
	v_pk_fma_f32 v[208:209], v[8:9], v[208:209], v[24:25]
	v_pk_fma_f32 v[210:211], v[10:11], v[210:211], v[26:27]
	v_pk_fma_f32 v[212:213], v[12:13], v[212:213], v[28:29]
	v_pk_fma_f32 v[214:215], v[14:15], v[214:215], v[30:31]
	v_pk_fma_f32 v[216:217], v[16:17], v[216:217], v[32:33]
	v_pk_fma_f32 v[218:219], v[18:19], v[218:219], v[34:35]
	v_cvt_pk_bf16_f32 v204, v204, v205
	v_cvt_pk_bf16_f32 v205, v206, v207
	v_cvt_pk_bf16_f32 v206, v208, v209
	v_cvt_pk_bf16_f32 v207, v210, v211
	v_cvt_pk_bf16_f32 v212, v212, v213
	v_cvt_pk_bf16_f32 v213, v214, v215
	v_cvt_pk_bf16_f32 v214, v216, v217
	v_cvt_pk_bf16_f32 v215, v218, v219
	v_lshl_add_u32 v3, s43, 11, v2
	global_store_dwordx4 v3, v[204:207], s[96:97] sc1
	global_store_dwordx4 v3, v[212:215], s[96:97] offset:1024 sc1
	s_mov_b64 s[52:53], exec
	s_mov_b64 exec, 1
	v_mov_b32_e32 v3, s40
	v_lshlrev_b32_e32 v3, 3, v3
	global_store_dwordx2 v3, v[238:239], s[92:93] sc1
	v_mov_b32_e32 v3, s41
	v_lshlrev_b32_e32 v3, 3, v3
	global_store_dwordx2 v3, v[240:241], s[92:93] sc1
	v_mov_b32_e32 v3, s42
	v_lshlrev_b32_e32 v3, 3, v3
	global_store_dwordx2 v3, v[242:243], s[92:93] sc1
	v_mov_b32_e32 v3, s43
	v_lshlrev_b32_e32 v3, 3, v3
	global_store_dwordx2 v3, v[244:245], s[92:93] sc1
	s_mov_b64 exec, s[52:53]
	s_cmp_gt_u32 s46, 15
	s_cbranch_scc1 .Lln1_done
	v_lshl_add_u32 v128, s46, 12, v1
	global_load_dwordx4 v[36:39], v128, s[30:31]
	global_load_dwordx4 v[40:43], v128, s[30:31] offset:16
	global_load_dwordx4 v[44:47], v128, s[30:31] offset:2048
	global_load_dwordx4 v[48:51], v128, s[30:31] offset:2064
	s_add_u32 s36, s46, 0x8000
	s_waitcnt vmcnt(0)
	v_pk_add_f32 v[108:109], v[36:37], v[38:39]
	v_pk_add_f32 v[110:111], v[40:41], v[42:43]
	v_pk_add_f32 v[112:113], v[44:45], v[46:47]
	v_pk_add_f32 v[114:115], v[48:49], v[50:51]
	v_pk_mul_f32 v[116:117], v[36:37], v[36:37]
	v_pk_fma_f32 v[116:117], v[38:39], v[38:39], v[116:117]
	v_pk_fma_f32 v[116:117], v[40:41], v[40:41], v[116:117]
	v_pk_fma_f32 v[116:117], v[42:43], v[42:43], v[116:117]
	v_pk_fma_f32 v[116:117], v[44:45], v[44:45], v[116:117]
	v_pk_fma_f32 v[116:117], v[46:47], v[46:47], v[116:117]
	v_pk_fma_f32 v[116:117], v[48:49], v[48:49], v[116:117]
	v_pk_fma_f32 v[116:117], v[50:51], v[50:51], v[116:117]
	v_pk_add_f32 v[108:109], v[108:109], v[110:111]
	v_pk_add_f32 v[112:113], v[112:113], v[114:115]
	v_pk_add_f32 v[108:109], v[108:109], v[112:113]
	v_add_f32_e32 v100, v108, v109
	v_add_f32_e32 v101, v116, v117
	s_nop 1
	v_add_f32_dpp v100, v100, v100 quad_perm:[1,0,3,2] row_mask:0xf bank_mask:0xf
	v_add_f32_dpp v101, v101, v101 quad_perm:[1,0,3,2] row_mask:0xf bank_mask:0xf
	s_nop 1
	v_add_f32_dpp v100, v100, v100 quad_perm:[2,3,0,1] row_mask:0xf bank_mask:0xf
	v_add_f32_dpp v101, v101, v101 quad_perm:[2,3,0,1] row_mask:0xf bank_mask:0xf
	s_nop 1
	v_add_f32_dpp v100, v100, v100 row_half_mirror row_mask:0xf bank_mask:0xf
	v_add_f32_dpp v101, v101, v101 row_half_mirror row_mask:0xf bank_mask:0xf
	s_nop 1
	v_add_f32_dpp v100, v100, v100 row_mirror row_mask:0xf bank_mask:0xf
	v_add_f32_dpp v101, v101, v101 row_mirror row_mask:0xf bank_mask:0xf
	s_nop 1
	v_mov_b32_e32 v108, v100
	v_mov_b32_e32 v109, v101
	s_nop 1
	v_permlane16_swap_b32_e32 v108, v100
	v_permlane16_swap_b32_e32 v109, v101
	v_add_f32_e32 v100, v100, v108
	v_add_f32_e32 v101, v101, v109
	v_mov_b32_e32 v108, v100
	v_mov_b32_e32 v109, v101
	s_nop 1
	v_permlane32_swap_b32_e32 v108, v100
	v_permlane32_swap_b32_e32 v109, v101
	v_add_f32_e32 v100, v100, v108
	v_add_f32_e32 v101, v101, v109
	v_mul_f32_e32 v230, 0x3a800000, v100
	v_mul_f32_e32 v116, 0x3a800000, v101
	v_fma_f32 v116, -v230, v230, v116
	v_max_f32_e32 v116, 0, v116
	v_add_f32_e32 v116, 0x3727c5ac, v116
	v_rsq_f32_e32 v117, v116
	s_nop 0
	v_mul_f32_e32 v124, v116, v117
	v_mul_f32_e32 v124, v124, v117
	v_fmaak_f32 v124, -0.5, v124, 0x3fc00000
	v_mul_f32_e32 v231, v117, v124
	v_pk_add_f32 v[36:37], v[36:37], v[230:231] op_sel_hi:[1,0] neg_lo:[0,1] neg_hi:[0,1]
	v_pk_add_f32 v[38:39], v[38:39], v[230:231] op_sel_hi:[1,0] neg_lo:[0,1] neg_hi:[0,1]
	v_pk_add_f32 v[40:41], v[40:41], v[230:231] op_sel_hi:[1,0] neg_lo:[0,1] neg_hi:[0,1]
	v_pk_add_f32 v[42:43], v[42:43], v[230:231] op_sel_hi:[1,0] neg_lo:[0,1] neg_hi:[0,1]
	v_pk_add_f32 v[44:45], v[44:45], v[230:231] op_sel_hi:[1,0] neg_lo:[0,1] neg_hi:[0,1]
	v_pk_add_f32 v[46:47], v[46:47], v[230:231] op_sel_hi:[1,0] neg_lo:[0,1] neg_hi:[0,1]
	v_pk_add_f32 v[48:49], v[48:49], v[230:231] op_sel_hi:[1,0] neg_lo:[0,1] neg_hi:[0,1]
	v_pk_add_f32 v[50:51], v[50:51], v[230:231] op_sel_hi:[1,0] neg_lo:[0,1] neg_hi:[0,1]
	v_pk_mul_f32 v[36:37], v[36:37], v[230:231] op_sel:[0,1] op_sel_hi:[1,1]
	v_pk_mul_f32 v[38:39], v[38:39], v[230:231] op_sel:[0,1] op_sel_hi:[1,1]
	v_pk_mul_f32 v[40:41], v[40:41], v[230:231] op_sel:[0,1] op_sel_hi:[1,1]
	v_pk_mul_f32 v[42:43], v[42:43], v[230:231] op_sel:[0,1] op_sel_hi:[1,1]
	v_pk_mul_f32 v[44:45], v[44:45], v[230:231] op_sel:[0,1] op_sel_hi:[1,1]
	v_pk_mul_f32 v[46:47], v[46:47], v[230:231] op_sel:[0,1] op_sel_hi:[1,1]
	v_pk_mul_f32 v[48:49], v[48:49], v[230:231] op_sel:[0,1] op_sel_hi:[1,1]
	v_pk_mul_f32 v[50:51], v[50:51], v[230:231] op_sel:[0,1] op_sel_hi:[1,1]
	v_pk_fma_f32 v[36:37], v[4:5], v[36:37], v[20:21]
	v_pk_fma_f32 v[38:39], v[6:7], v[38:39], v[22:23]
	v_pk_fma_f32 v[40:41], v[8:9], v[40:41], v[24:25]
	v_pk_fma_f32 v[42:43], v[10:11], v[42:43], v[26:27]
	v_pk_fma_f32 v[44:45], v[12:13], v[44:45], v[28:29]
	v_pk_fma_f32 v[46:47], v[14:15], v[46:47], v[30:31]
	v_pk_fma_f32 v[48:49], v[16:17], v[48:49], v[32:33]
	v_pk_fma_f32 v[50:51], v[18:19], v[50:51], v[34:35]
	v_cvt_pk_bf16_f32 v36, v36, v37
	v_cvt_pk_bf16_f32 v37, v38, v39
	v_cvt_pk_bf16_f32 v38, v40, v41
	v_cvt_pk_bf16_f32 v39, v42, v43
	v_cvt_pk_bf16_f32 v44, v44, v45
	v_cvt_pk_bf16_f32 v45, v46, v47
	v_cvt_pk_bf16_f32 v46, v48, v49
	v_cvt_pk_bf16_f32 v47, v50, v51
	v_lshl_add_u32 v3, s36, 11, v2
	global_store_dwordx4 v3, v[36:39], s[96:97] sc1
	global_store_dwordx4 v3, v[44:47], s[96:97] offset:1024 sc1
	s_mov_b64 s[52:53], exec
	s_mov_b64 exec, 1
	v_mov_b32_e32 v3, s36
	v_lshlrev_b32_e32 v3, 3, v3
	global_store_dwordx2 v3, v[230:231], s[92:93] sc1
	s_mov_b64 exec, s[52:53]

.LBB0_1142:
	s_or_b64 exec, exec, s[36:37]
	s_waitcnt lgkmcnt(0)
	v_mov_b32_e32 v0, v222
	s_barrier
	v_and_b32_e32 v0, 63, v222
	v_readfirstlane_b32 s46, v222
	v_lshlrev_b32_e32 v1, 5, v0
	v_lshlrev_b32_e32 v2, 4, v0
	s_lshl_b32 s2, s38, 2
	v_readlane_b32 s48, v252, 22
	v_readlane_b32 s49, v252, 23
	v_readlane_b32 s50, v252, 24
	v_readlane_b32 s51, v252, 25
	s_nop 3
	s_lshr_b32 s46, s46, 6
	s_add_u32 s46, s46, s95
	s_add_u32 s48, s48, s2
	s_addc_u32 s49, s49, 0
	s_add_u32 s50, s50, s2
	s_addc_u32 s51, s51, 0
	global_load_dwordx4 v[4:7], v1, s[48:49]
	global_load_dwordx4 v[20:23], v1, s[50:51]
	global_load_dwordx4 v[8:11], v1, s[48:49] offset:16
	global_load_dwordx4 v[24:27], v1, s[50:51] offset:16
	global_load_dwordx4 v[12:15], v1, s[48:49] offset:2048
	global_load_dwordx4 v[28:31], v1, s[50:51] offset:2048
	global_load_dwordx4 v[16:19], v1, s[48:49] offset:2064
	global_load_dwordx4 v[32:35], v1, s[50:51] offset:2064
	s_add_u32 s36, s46, 0x0
	v_lshl_add_u32 v128, s36, 12, v1
	s_add_u32 s37, s46, 0x1000
	v_lshl_add_u32 v129, s37, 12, v1
	s_add_u32 s38, s46, 0x2000
	v_lshl_add_u32 v130, s38, 12, v1
	s_add_u32 s39, s46, 0x3000
	v_lshl_add_u32 v131, s39, 12, v1
	global_load_dwordx4 v[36:39], v128, s[64:65] nt
	global_load_dwordx4 v[40:43], v128, s[64:65] offset:16 nt
	global_load_dwordx4 v[44:47], v128, s[64:65] offset:2048 nt
	global_load_dwordx4 v[48:51], v128, s[64:65] offset:2064 nt
	global_load_dwordx4 v[52:55], v129, s[64:65] nt
	global_load_dwordx4 v[56:59], v129, s[64:65] offset:16 nt
	global_load_dwordx4 v[60:63], v129, s[64:65] offset:2048 nt
	global_load_dwordx4 v[64:67], v129, s[64:65] offset:2064 nt
	global_load_dwordx4 v[68:71], v130, s[64:65] nt
	global_load_dwordx4 v[72:75], v130, s[64:65] offset:16 nt
	global_load_dwordx4 v[76:79], v130, s[64:65] offset:2048 nt
	global_load_dwordx4 v[80:83], v130, s[64:65] offset:2064 nt
	global_load_dwordx4 v[84:87], v131, s[64:65] nt
	global_load_dwordx4 v[88:91], v131, s[64:65] offset:16 nt
	global_load_dwordx4 v[92:95], v131, s[64:65] offset:2048 nt
	global_load_dwordx4 v[96:99], v131, s[64:65] offset:2064 nt
	s_add_u32 s40, s46, 0x4000
	v_lshl_add_u32 v132, s40, 12, v1
	s_add_u32 s41, s46, 0x5000
	v_lshl_add_u32 v133, s41, 12, v1
	s_add_u32 s42, s46, 0x6000
	v_lshl_add_u32 v134, s42, 12, v1
	s_add_u32 s43, s46, 0x7000
	v_lshl_add_u32 v135, s43, 12, v1
	global_load_dwordx4 v[156:159], v132, s[64:65] nt
	global_load_dwordx4 v[160:163], v132, s[64:65] offset:16 nt
	global_load_dwordx4 v[164:167], v132, s[64:65] offset:2048 nt
	global_load_dwordx4 v[168:171], v132, s[64:65] offset:2064 nt
	global_load_dwordx4 v[172:175], v133, s[64:65] nt
	global_load_dwordx4 v[176:179], v133, s[64:65] offset:16 nt
	global_load_dwordx4 v[180:183], v133, s[64:65] offset:2048 nt
	global_load_dwordx4 v[184:187], v133, s[64:65] offset:2064 nt
	global_load_dwordx4 v[188:191], v134, s[64:65] nt
	global_load_dwordx4 v[192:195], v134, s[64:65] offset:16 nt
	global_load_dwordx4 v[196:199], v134, s[64:65] offset:2048 nt
	global_load_dwordx4 v[200:203], v134, s[64:65] offset:2064 nt
	global_load_dwordx4 v[204:207], v135, s[64:65] nt
	global_load_dwordx4 v[208:211], v135, s[64:65] offset:16 nt
	global_load_dwordx4 v[212:215], v135, s[64:65] offset:2048 nt
	global_load_dwordx4 v[216:219], v135, s[64:65] offset:2064 nt
	s_waitcnt vmcnt(16)
	v_pk_add_f32 v[108:109], v[36:37], v[38:39]
	v_pk_add_f32 v[110:111], v[40:41], v[42:43]
	v_pk_add_f32 v[112:113], v[44:45], v[46:47]
	v_pk_add_f32 v[114:115], v[48:49], v[50:51]
	v_pk_mul_f32 v[116:117], v[36:37], v[36:37]
	v_pk_fma_f32 v[116:117], v[38:39], v[38:39], v[116:117]
	v_pk_fma_f32 v[116:117], v[40:41], v[40:41], v[116:117]
	v_pk_fma_f32 v[116:117], v[42:43], v[42:43], v[116:117]
	v_pk_fma_f32 v[116:117], v[44:45], v[44:45], v[116:117]
	v_pk_fma_f32 v[116:117], v[46:47], v[46:47], v[116:117]
	v_pk_fma_f32 v[116:117], v[48:49], v[48:49], v[116:117]
	v_pk_fma_f32 v[116:117], v[50:51], v[50:51], v[116:117]
	v_pk_add_f32 v[108:109], v[108:109], v[110:111]
	v_pk_add_f32 v[112:113], v[112:113], v[114:115]
	v_pk_add_f32 v[108:109], v[108:109], v[112:113]
	v_add_f32_e32 v100, v108, v109
	v_add_f32_e32 v101, v116, v117
	v_pk_add_f32 v[108:109], v[52:53], v[54:55]
	v_pk_add_f32 v[110:111], v[56:57], v[58:59]
	v_pk_add_f32 v[112:113], v[60:61], v[62:63]
	v_pk_add_f32 v[114:115], v[64:65], v[66:67]
	v_pk_mul_f32 v[116:117], v[52:53], v[52:53]
	v_pk_fma_f32 v[116:117], v[54:55], v[54:55], v[116:117]
	v_pk_fma_f32 v[116:117], v[56:57], v[56:57], v[116:117]
	v_pk_fma_f32 v[116:117], v[58:59], v[58:59], v[116:117]
	v_pk_fma_f32 v[116:117], v[60:61], v[60:61], v[116:117]
	v_pk_fma_f32 v[116:117], v[62:63], v[62:63], v[116:117]
	v_pk_fma_f32 v[116:117], v[64:65], v[64:65], v[116:117]
	v_pk_fma_f32 v[116:117], v[66:67], v[66:67], v[116:117]
	v_pk_add_f32 v[108:109], v[108:109], v[110:111]
	v_pk_add_f32 v[112:113], v[112:113], v[114:115]
	v_pk_add_f32 v[108:109], v[108:109], v[112:113]
	v_add_f32_e32 v102, v108, v109
	v_add_f32_e32 v103, v116, v117
	v_pk_add_f32 v[108:109], v[68:69], v[70:71]
	v_pk_add_f32 v[110:111], v[72:73], v[74:75]
	v_pk_add_f32 v[112:113], v[76:77], v[78:79]
	v_pk_add_f32 v[114:115], v[80:81], v[82:83]
	v_pk_mul_f32 v[116:117], v[68:69], v[68:69]
	v_pk_fma_f32 v[116:117], v[70:71], v[70:71], v[116:117]
	v_pk_fma_f32 v[116:117], v[72:73], v[72:73], v[116:117]
	v_pk_fma_f32 v[116:117], v[74:75], v[74:75], v[116:117]
	v_pk_fma_f32 v[116:117], v[76:77], v[76:77], v[116:117]
	v_pk_fma_f32 v[116:117], v[78:79], v[78:79], v[116:117]
	v_pk_fma_f32 v[116:117], v[80:81], v[80:81], v[116:117]
	v_pk_fma_f32 v[116:117], v[82:83], v[82:83], v[116:117]
	v_pk_add_f32 v[108:109], v[108:109], v[110:111]
	v_pk_add_f32 v[112:113], v[112:113], v[114:115]
	v_pk_add_f32 v[108:109], v[108:109], v[112:113]
	v_add_f32_e32 v104, v108, v109
	v_add_f32_e32 v105, v116, v117
	v_pk_add_f32 v[108:109], v[84:85], v[86:87]
	v_pk_add_f32 v[110:111], v[88:89], v[90:91]
	v_pk_add_f32 v[112:113], v[92:93], v[94:95]
	v_pk_add_f32 v[114:115], v[96:97], v[98:99]
	v_pk_mul_f32 v[116:117], v[84:85], v[84:85]
	v_pk_fma_f32 v[116:117], v[86:87], v[86:87], v[116:117]
	v_pk_fma_f32 v[116:117], v[88:89], v[88:89], v[116:117]
	v_pk_fma_f32 v[116:117], v[90:91], v[90:91], v[116:117]
	v_pk_fma_f32 v[116:117], v[92:93], v[92:93], v[116:117]
	v_pk_fma_f32 v[116:117], v[94:95], v[94:95], v[116:117]
	v_pk_fma_f32 v[116:117], v[96:97], v[96:97], v[116:117]
	v_pk_fma_f32 v[116:117], v[98:99], v[98:99], v[116:117]
	v_pk_add_f32 v[108:109], v[108:109], v[110:111]
	v_pk_add_f32 v[112:113], v[112:113], v[114:115]
	v_pk_add_f32 v[108:109], v[108:109], v[112:113]
	v_add_f32_e32 v106, v108, v109
	v_add_f32_e32 v107, v116, v117
	v_add_f32_dpp v100, v100, v100 quad_perm:[1,0,3,2] row_mask:0xf bank_mask:0xf
	v_add_f32_dpp v101, v101, v101 quad_perm:[1,0,3,2] row_mask:0xf bank_mask:0xf
	v_add_f32_dpp v102, v102, v102 quad_perm:[1,0,3,2] row_mask:0xf bank_mask:0xf
	v_add_f32_dpp v103, v103, v103 quad_perm:[1,0,3,2] row_mask:0xf bank_mask:0xf
	v_add_f32_dpp v104, v104, v104 quad_perm:[1,0,3,2] row_mask:0xf bank_mask:0xf
	v_add_f32_dpp v105, v105, v105 quad_perm:[1,0,3,2] row_mask:0xf bank_mask:0xf
	v_add_f32_dpp v106, v106, v106 quad_perm:[1,0,3,2] row_mask:0xf bank_mask:0xf
	v_add_f32_dpp v107, v107, v107 quad_perm:[1,0,3,2] row_mask:0xf bank_mask:0xf
	v_add_f32_dpp v100, v100, v100 quad_perm:[2,3,0,1] row_mask:0xf bank_mask:0xf
	v_add_f32_dpp v101, v101, v101 quad_perm:[2,3,0,1] row_mask:0xf bank_mask:0xf
	v_add_f32_dpp v102, v102, v102 quad_perm:[2,3,0,1] row_mask:0xf bank_mask:0xf
	v_add_f32_dpp v103, v103, v103 quad_perm:[2,3,0,1] row_mask:0xf bank_mask:0xf
	v_add_f32_dpp v104, v104, v104 quad_perm:[2,3,0,1] row_mask:0xf bank_mask:0xf
	v_add_f32_dpp v105, v105, v105 quad_perm:[2,3,0,1] row_mask:0xf bank_mask:0xf
	v_add_f32_dpp v106, v106, v106 quad_perm:[2,3,0,1] row_mask:0xf bank_mask:0xf
	v_add_f32_dpp v107, v107, v107 quad_perm:[2,3,0,1] row_mask:0xf bank_mask:0xf
	v_add_f32_dpp v100, v100, v100 row_half_mirror row_mask:0xf bank_mask:0xf
	v_add_f32_dpp v101, v101, v101 row_half_mirror row_mask:0xf bank_mask:0xf
	v_add_f32_dpp v102, v102, v102 row_half_mirror row_mask:0xf bank_mask:0xf
	v_add_f32_dpp v103, v103, v103 row_half_mirror row_mask:0xf bank_mask:0xf
	v_add_f32_dpp v104, v104, v104 row_half_mirror row_mask:0xf bank_mask:0xf
	v_add_f32_dpp v105, v105, v105 row_half_mirror row_mask:0xf bank_mask:0xf
	v_add_f32_dpp v106, v106, v106 row_half_mirror row_mask:0xf bank_mask:0xf
	v_add_f32_dpp v107, v107, v107 row_half_mirror row_mask:0xf bank_mask:0xf
	v_add_f32_dpp v100, v100, v100 row_mirror row_mask:0xf bank_mask:0xf
	v_add_f32_dpp v101, v101, v101 row_mirror row_mask:0xf bank_mask:0xf
	v_add_f32_dpp v102, v102, v102 row_mirror row_mask:0xf bank_mask:0xf
	v_add_f32_dpp v103, v103, v103 row_mirror row_mask:0xf bank_mask:0xf
	v_add_f32_dpp v104, v104, v104 row_mirror row_mask:0xf bank_mask:0xf
	v_add_f32_dpp v105, v105, v105 row_mirror row_mask:0xf bank_mask:0xf
	v_add_f32_dpp v106, v106, v106 row_mirror row_mask:0xf bank_mask:0xf
	v_add_f32_dpp v107, v107, v107 row_mirror row_mask:0xf bank_mask:0xf
	v_mov_b32_e32 v108, v100
	v_mov_b32_e32 v109, v101
	v_mov_b32_e32 v110, v102
	v_mov_b32_e32 v111, v103
	v_mov_b32_e32 v112, v104
	v_mov_b32_e32 v113, v105
	v_mov_b32_e32 v114, v106
	v_mov_b32_e32 v115, v107
	s_nop 1
	v_permlane16_swap_b32_e32 v108, v100
	v_permlane16_swap_b32_e32 v109, v101
	v_permlane16_swap_b32_e32 v110, v102
	v_permlane16_swap_b32_e32 v111, v103
	v_permlane16_swap_b32_e32 v112, v104
	v_permlane16_swap_b32_e32 v113, v105
	v_permlane16_swap_b32_e32 v114, v106
	v_permlane16_swap_b32_e32 v115, v107
	v_add_f32_e32 v100, v100, v108
	v_add_f32_e32 v101, v101, v109
	v_add_f32_e32 v102, v102, v110
	v_add_f32_e32 v103, v103, v111
	v_add_f32_e32 v104, v104, v112
	v_add_f32_e32 v105, v105, v113
	v_add_f32_e32 v106, v106, v114
	v_add_f32_e32 v107, v107, v115
	v_mov_b32_e32 v108, v100
	v_mov_b32_e32 v109, v101
	v_mov_b32_e32 v110, v102
	v_mov_b32_e32 v111, v103
	v_mov_b32_e32 v112, v104
	v_mov_b32_e32 v113, v105
	v_mov_b32_e32 v114, v106
	v_mov_b32_e32 v115, v107
	s_nop 1
	v_permlane32_swap_b32_e32 v108, v100
	v_permlane32_swap_b32_e32 v109, v101
	v_permlane32_swap_b32_e32 v110, v102
	v_permlane32_swap_b32_e32 v111, v103
	v_permlane32_swap_b32_e32 v112, v104
	v_permlane32_swap_b32_e32 v113, v105
	v_permlane32_swap_b32_e32 v114, v106
	v_permlane32_swap_b32_e32 v115, v107
	v_add_f32_e32 v100, v100, v108
	v_add_f32_e32 v101, v101, v109
	v_add_f32_e32 v102, v102, v110
	v_add_f32_e32 v103, v103, v111
	v_add_f32_e32 v104, v104, v112
	v_add_f32_e32 v105, v105, v113
	v_add_f32_e32 v106, v106, v114
	v_add_f32_e32 v107, v107, v115
	v_mul_f32_e32 v230, 0x3a800000, v100
	v_mul_f32_e32 v116, 0x3a800000, v101
	v_fma_f32 v116, -v230, v230, v116
	v_max_f32_e32 v116, 0, v116
	v_add_f32_e32 v116, 0x3727c5ac, v116
	v_mul_f32_e32 v232, 0x3a800000, v102
	v_mul_f32_e32 v118, 0x3a800000, v103
	v_fma_f32 v118, -v232, v232, v118
	v_max_f32_e32 v118, 0, v118
	v_add_f32_e32 v118, 0x3727c5ac, v118
	v_mul_f32_e32 v234, 0x3a800000, v104
	v_mul_f32_e32 v120, 0x3a800000, v105
	v_fma_f32 v120, -v234, v234, v120
	v_max_f32_e32 v120, 0, v120
	v_add_f32_e32 v120, 0x3727c5ac, v120
	v_mul_f32_e32 v236, 0x3a800000, v106
	v_mul_f32_e32 v122, 0x3a800000, v107
	v_fma_f32 v122, -v236, v236, v122
	v_max_f32_e32 v122, 0, v122
	v_add_f32_e32 v122, 0x3727c5ac, v122
	v_rsq_f32_e32 v117, v116
	v_rsq_f32_e32 v119, v118
	v_rsq_f32_e32 v121, v120
	v_rsq_f32_e32 v123, v122
	s_nop 0
	v_mul_f32_e32 v124, v116, v117
	v_mul_f32_e32 v124, v124, v117
	v_fmaak_f32 v124, -0.5, v124, 0x3fc00000
	v_mul_f32_e32 v231, v117, v124
	v_mul_f32_e32 v125, v118, v119
	v_mul_f32_e32 v125, v125, v119
	v_fmaak_f32 v125, -0.5, v125, 0x3fc00000
	v_mul_f32_e32 v233, v119, v125
	v_mul_f32_e32 v126, v120, v121
	v_mul_f32_e32 v126, v126, v121
	v_fmaak_f32 v126, -0.5, v126, 0x3fc00000
	v_mul_f32_e32 v235, v121, v126
	v_mul_f32_e32 v127, v122, v123
	v_mul_f32_e32 v127, v127, v123
	v_fmaak_f32 v127, -0.5, v127, 0x3fc00000
	v_mul_f32_e32 v237, v123, v127
	v_pk_add_f32 v[36:37], v[36:37], v[230:231] op_sel_hi:[1,0] neg_lo:[0,1] neg_hi:[0,1]
	v_pk_add_f32 v[38:39], v[38:39], v[230:231] op_sel_hi:[1,0] neg_lo:[0,1] neg_hi:[0,1]
	v_pk_add_f32 v[40:41], v[40:41], v[230:231] op_sel_hi:[1,0] neg_lo:[0,1] neg_hi:[0,1]
	v_pk_add_f32 v[42:43], v[42:43], v[230:231] op_sel_hi:[1,0] neg_lo:[0,1] neg_hi:[0,1]
	v_pk_add_f32 v[44:45], v[44:45], v[230:231] op_sel_hi:[1,0] neg_lo:[0,1] neg_hi:[0,1]
	v_pk_add_f32 v[46:47], v[46:47], v[230:231] op_sel_hi:[1,0] neg_lo:[0,1] neg_hi:[0,1]
	v_pk_add_f32 v[48:49], v[48:49], v[230:231] op_sel_hi:[1,0] neg_lo:[0,1] neg_hi:[0,1]
	v_pk_add_f32 v[50:51], v[50:51], v[230:231] op_sel_hi:[1,0] neg_lo:[0,1] neg_hi:[0,1]
	v_pk_mul_f32 v[36:37], v[36:37], v[230:231] op_sel:[0,1] op_sel_hi:[1,1]
	v_pk_mul_f32 v[38:39], v[38:39], v[230:231] op_sel:[0,1] op_sel_hi:[1,1]
	v_pk_mul_f32 v[40:41], v[40:41], v[230:231] op_sel:[0,1] op_sel_hi:[1,1]
	v_pk_mul_f32 v[42:43], v[42:43], v[230:231] op_sel:[0,1] op_sel_hi:[1,1]
	v_pk_mul_f32 v[44:45], v[44:45], v[230:231] op_sel:[0,1] op_sel_hi:[1,1]
	v_pk_mul_f32 v[46:47], v[46:47], v[230:231] op_sel:[0,1] op_sel_hi:[1,1]
	v_pk_mul_f32 v[48:49], v[48:49], v[230:231] op_sel:[0,1] op_sel_hi:[1,1]
	v_pk_mul_f32 v[50:51], v[50:51], v[230:231] op_sel:[0,1] op_sel_hi:[1,1]
	v_pk_fma_f32 v[36:37], v[4:5], v[36:37], v[20:21]
	v_pk_fma_f32 v[38:39], v[6:7], v[38:39], v[22:23]
	v_pk_fma_f32 v[40:41], v[8:9], v[40:41], v[24:25]
	v_pk_fma_f32 v[42:43], v[10:11], v[42:43], v[26:27]
	v_pk_fma_f32 v[44:45], v[12:13], v[44:45], v[28:29]
	v_pk_fma_f32 v[46:47], v[14:15], v[46:47], v[30:31]
	v_pk_fma_f32 v[48:49], v[16:17], v[48:49], v[32:33]
	v_pk_fma_f32 v[50:51], v[18:19], v[50:51], v[34:35]
	v_cvt_pk_bf16_f32 v36, v36, v37
	v_cvt_pk_bf16_f32 v37, v38, v39
	v_cvt_pk_bf16_f32 v38, v40, v41
	v_cvt_pk_bf16_f32 v39, v42, v43
	v_cvt_pk_bf16_f32 v44, v44, v45
	v_cvt_pk_bf16_f32 v45, v46, v47
	v_cvt_pk_bf16_f32 v46, v48, v49
	v_cvt_pk_bf16_f32 v47, v50, v51
	v_lshl_add_u32 v3, s36, 11, v2
	global_store_dwordx4 v3, v[36:39], s[96:97] sc1
	global_store_dwordx4 v3, v[44:47], s[96:97] offset:1024 sc1
	v_pk_add_f32 v[52:53], v[52:53], v[232:233] op_sel_hi:[1,0] neg_lo:[0,1] neg_hi:[0,1]
	v_pk_add_f32 v[54:55], v[54:55], v[232:233] op_sel_hi:[1,0] neg_lo:[0,1] neg_hi:[0,1]
	v_pk_add_f32 v[56:57], v[56:57], v[232:233] op_sel_hi:[1,0] neg_lo:[0,1] neg_hi:[0,1]
	v_pk_add_f32 v[58:59], v[58:59], v[232:233] op_sel_hi:[1,0] neg_lo:[0,1] neg_hi:[0,1]
	v_pk_add_f32 v[60:61], v[60:61], v[232:233] op_sel_hi:[1,0] neg_lo:[0,1] neg_hi:[0,1]
	v_pk_add_f32 v[62:63], v[62:63], v[232:233] op_sel_hi:[1,0] neg_lo:[0,1] neg_hi:[0,1]
	v_pk_add_f32 v[64:65], v[64:65], v[232:233] op_sel_hi:[1,0] neg_lo:[0,1] neg_hi:[0,1]
	v_pk_add_f32 v[66:67], v[66:67], v[232:233] op_sel_hi:[1,0] neg_lo:[0,1] neg_hi:[0,1]
	v_pk_mul_f32 v[52:53], v[52:53], v[232:233] op_sel:[0,1] op_sel_hi:[1,1]
	v_pk_mul_f32 v[54:55], v[54:55], v[232:233] op_sel:[0,1] op_sel_hi:[1,1]
	v_pk_mul_f32 v[56:57], v[56:57], v[232:233] op_sel:[0,1] op_sel_hi:[1,1]
	v_pk_mul_f32 v[58:59], v[58:59], v[232:233] op_sel:[0,1] op_sel_hi:[1,1]
	v_pk_mul_f32 v[60:61], v[60:61], v[232:233] op_sel:[0,1] op_sel_hi:[1,1]
	v_pk_mul_f32 v[62:63], v[62:63], v[232:233] op_sel:[0,1] op_sel_hi:[1,1]
	v_pk_mul_f32 v[64:65], v[64:65], v[232:233] op_sel:[0,1] op_sel_hi:[1,1]
	v_pk_mul_f32 v[66:67], v[66:67], v[232:233] op_sel:[0,1] op_sel_hi:[1,1]
	v_pk_fma_f32 v[52:53], v[4:5], v[52:53], v[20:21]
	v_pk_fma_f32 v[54:55], v[6:7], v[54:55], v[22:23]
	v_pk_fma_f32 v[56:57], v[8:9], v[56:57], v[24:25]
	v_pk_fma_f32 v[58:59], v[10:11], v[58:59], v[26:27]
	v_pk_fma_f32 v[60:61], v[12:13], v[60:61], v[28:29]
	v_pk_fma_f32 v[62:63], v[14:15], v[62:63], v[30:31]
	v_pk_fma_f32 v[64:65], v[16:17], v[64:65], v[32:33]
	v_pk_fma_f32 v[66:67], v[18:19], v[66:67], v[34:35]
	v_cvt_pk_bf16_f32 v52, v52, v53
	v_cvt_pk_bf16_f32 v53, v54, v55
	v_cvt_pk_bf16_f32 v54, v56, v57
	v_cvt_pk_bf16_f32 v55, v58, v59
	v_cvt_pk_bf16_f32 v60, v60, v61
	v_cvt_pk_bf16_f32 v61, v62, v63
	v_cvt_pk_bf16_f32 v62, v64, v65
	v_cvt_pk_bf16_f32 v63, v66, v67
	v_lshl_add_u32 v3, s37, 11, v2
	global_store_dwordx4 v3, v[52:55], s[96:97] sc1
	global_store_dwordx4 v3, v[60:63], s[96:97] offset:1024 sc1
	v_pk_add_f32 v[68:69], v[68:69], v[234:235] op_sel_hi:[1,0] neg_lo:[0,1] neg_hi:[0,1]
	v_pk_add_f32 v[70:71], v[70:71], v[234:235] op_sel_hi:[1,0] neg_lo:[0,1] neg_hi:[0,1]
	v_pk_add_f32 v[72:73], v[72:73], v[234:235] op_sel_hi:[1,0] neg_lo:[0,1] neg_hi:[0,1]
	v_pk_add_f32 v[74:75], v[74:75], v[234:235] op_sel_hi:[1,0] neg_lo:[0,1] neg_hi:[0,1]
	v_pk_add_f32 v[76:77], v[76:77], v[234:235] op_sel_hi:[1,0] neg_lo:[0,1] neg_hi:[0,1]
	v_pk_add_f32 v[78:79], v[78:79], v[234:235] op_sel_hi:[1,0] neg_lo:[0,1] neg_hi:[0,1]
	v_pk_add_f32 v[80:81], v[80:81], v[234:235] op_sel_hi:[1,0] neg_lo:[0,1] neg_hi:[0,1]
	v_pk_add_f32 v[82:83], v[82:83], v[234:235] op_sel_hi:[1,0] neg_lo:[0,1] neg_hi:[0,1]
	v_pk_mul_f32 v[68:69], v[68:69], v[234:235] op_sel:[0,1] op_sel_hi:[1,1]
	v_pk_mul_f32 v[70:71], v[70:71], v[234:235] op_sel:[0,1] op_sel_hi:[1,1]
	v_pk_mul_f32 v[72:73], v[72:73], v[234:235] op_sel:[0,1] op_sel_hi:[1,1]
	v_pk_mul_f32 v[74:75], v[74:75], v[234:235] op_sel:[0,1] op_sel_hi:[1,1]
	v_pk_mul_f32 v[76:77], v[76:77], v[234:235] op_sel:[0,1] op_sel_hi:[1,1]
	v_pk_mul_f32 v[78:79], v[78:79], v[234:235] op_sel:[0,1] op_sel_hi:[1,1]
	v_pk_mul_f32 v[80:81], v[80:81], v[234:235] op_sel:[0,1] op_sel_hi:[1,1]
	v_pk_mul_f32 v[82:83], v[82:83], v[234:235] op_sel:[0,1] op_sel_hi:[1,1]
	v_pk_fma_f32 v[68:69], v[4:5], v[68:69], v[20:21]
	v_pk_fma_f32 v[70:71], v[6:7], v[70:71], v[22:23]
	v_pk_fma_f32 v[72:73], v[8:9], v[72:73], v[24:25]
	v_pk_fma_f32 v[74:75], v[10:11], v[74:75], v[26:27]
	v_pk_fma_f32 v[76:77], v[12:13], v[76:77], v[28:29]
	v_pk_fma_f32 v[78:79], v[14:15], v[78:79], v[30:31]
	v_pk_fma_f32 v[80:81], v[16:17], v[80:81], v[32:33]
	v_pk_fma_f32 v[82:83], v[18:19], v[82:83], v[34:35]
	v_cvt_pk_bf16_f32 v68, v68, v69
	v_cvt_pk_bf16_f32 v69, v70, v71
	v_cvt_pk_bf16_f32 v70, v72, v73
	v_cvt_pk_bf16_f32 v71, v74, v75
	v_cvt_pk_bf16_f32 v76, v76, v77
	v_cvt_pk_bf16_f32 v77, v78, v79
	v_cvt_pk_bf16_f32 v78, v80, v81
	v_cvt_pk_bf16_f32 v79, v82, v83
	v_lshl_add_u32 v3, s38, 11, v2
	global_store_dwordx4 v3, v[68:71], s[96:97] sc1
	global_store_dwordx4 v3, v[76:79], s[96:97] offset:1024 sc1
	v_pk_add_f32 v[84:85], v[84:85], v[236:237] op_sel_hi:[1,0] neg_lo:[0,1] neg_hi:[0,1]
	v_pk_add_f32 v[86:87], v[86:87], v[236:237] op_sel_hi:[1,0] neg_lo:[0,1] neg_hi:[0,1]
	v_pk_add_f32 v[88:89], v[88:89], v[236:237] op_sel_hi:[1,0] neg_lo:[0,1] neg_hi:[0,1]
	v_pk_add_f32 v[90:91], v[90:91], v[236:237] op_sel_hi:[1,0] neg_lo:[0,1] neg_hi:[0,1]
	v_pk_add_f32 v[92:93], v[92:93], v[236:237] op_sel_hi:[1,0] neg_lo:[0,1] neg_hi:[0,1]
	v_pk_add_f32 v[94:95], v[94:95], v[236:237] op_sel_hi:[1,0] neg_lo:[0,1] neg_hi:[0,1]
	v_pk_add_f32 v[96:97], v[96:97], v[236:237] op_sel_hi:[1,0] neg_lo:[0,1] neg_hi:[0,1]
	v_pk_add_f32 v[98:99], v[98:99], v[236:237] op_sel_hi:[1,0] neg_lo:[0,1] neg_hi:[0,1]
	v_pk_mul_f32 v[84:85], v[84:85], v[236:237] op_sel:[0,1] op_sel_hi:[1,1]
	v_pk_mul_f32 v[86:87], v[86:87], v[236:237] op_sel:[0,1] op_sel_hi:[1,1]
	v_pk_mul_f32 v[88:89], v[88:89], v[236:237] op_sel:[0,1] op_sel_hi:[1,1]
	v_pk_mul_f32 v[90:91], v[90:91], v[236:237] op_sel:[0,1] op_sel_hi:[1,1]
	v_pk_mul_f32 v[92:93], v[92:93], v[236:237] op_sel:[0,1] op_sel_hi:[1,1]
	v_pk_mul_f32 v[94:95], v[94:95], v[236:237] op_sel:[0,1] op_sel_hi:[1,1]
	v_pk_mul_f32 v[96:97], v[96:97], v[236:237] op_sel:[0,1] op_sel_hi:[1,1]
	v_pk_mul_f32 v[98:99], v[98:99], v[236:237] op_sel:[0,1] op_sel_hi:[1,1]
	v_pk_fma_f32 v[84:85], v[4:5], v[84:85], v[20:21]
	v_pk_fma_f32 v[86:87], v[6:7], v[86:87], v[22:23]
	v_pk_fma_f32 v[88:89], v[8:9], v[88:89], v[24:25]
	v_pk_fma_f32 v[90:91], v[10:11], v[90:91], v[26:27]
	v_pk_fma_f32 v[92:93], v[12:13], v[92:93], v[28:29]
	v_pk_fma_f32 v[94:95], v[14:15], v[94:95], v[30:31]
	v_pk_fma_f32 v[96:97], v[16:17], v[96:97], v[32:33]
	v_pk_fma_f32 v[98:99], v[18:19], v[98:99], v[34:35]
	v_cvt_pk_bf16_f32 v84, v84, v85
	v_cvt_pk_bf16_f32 v85, v86, v87
	v_cvt_pk_bf16_f32 v86, v88, v89
	v_cvt_pk_bf16_f32 v87, v90, v91
	v_cvt_pk_bf16_f32 v92, v92, v93
	v_cvt_pk_bf16_f32 v93, v94, v95
	v_cvt_pk_bf16_f32 v94, v96, v97
	v_cvt_pk_bf16_f32 v95, v98, v99
	v_lshl_add_u32 v3, s39, 11, v2
	global_store_dwordx4 v3, v[84:87], s[96:97] sc1
	global_store_dwordx4 v3, v[92:95], s[96:97] offset:1024 sc1
	s_mov_b64 s[52:53], exec
	s_mov_b64 exec, 1
	v_mov_b32_e32 v3, s36
	v_lshlrev_b32_e32 v3, 3, v3
	global_store_dwordx2 v3, v[230:231], s[92:93] sc1
	v_mov_b32_e32 v3, s37
	v_lshlrev_b32_e32 v3, 3, v3
	global_store_dwordx2 v3, v[232:233], s[92:93] sc1
	v_mov_b32_e32 v3, s38
	v_lshlrev_b32_e32 v3, 3, v3
	global_store_dwordx2 v3, v[234:235], s[92:93] sc1
	v_mov_b32_e32 v3, s39
	v_lshlrev_b32_e32 v3, 3, v3
	global_store_dwordx2 v3, v[236:237], s[92:93] sc1
	s_mov_b64 exec, s[52:53]
	s_add_u32 s36, s46, 0x800
	v_lshl_add_u32 v128, s36, 12, v1
	s_add_u32 s37, s46, 0x1800
	v_lshl_add_u32 v129, s37, 12, v1
	s_add_u32 s38, s46, 0x2800
	v_lshl_add_u32 v130, s38, 12, v1
	s_add_u32 s39, s46, 0x3800
	v_lshl_add_u32 v131, s39, 12, v1
	global_load_dwordx4 v[36:39], v128, s[64:65] nt
	global_load_dwordx4 v[40:43], v128, s[64:65] offset:16 nt
	global_load_dwordx4 v[44:47], v128, s[64:65] offset:2048 nt
	global_load_dwordx4 v[48:51], v128, s[64:65] offset:2064 nt
	global_load_dwordx4 v[52:55], v129, s[64:65] nt
	global_load_dwordx4 v[56:59], v129, s[64:65] offset:16 nt
	global_load_dwordx4 v[60:63], v129, s[64:65] offset:2048 nt
	global_load_dwordx4 v[64:67], v129, s[64:65] offset:2064 nt
	global_load_dwordx4 v[68:71], v130, s[64:65] nt
	global_load_dwordx4 v[72:75], v130, s[64:65] offset:16 nt
	global_load_dwordx4 v[76:79], v130, s[64:65] offset:2048 nt
	global_load_dwordx4 v[80:83], v130, s[64:65] offset:2064 nt
	global_load_dwordx4 v[84:87], v131, s[64:65] nt
	global_load_dwordx4 v[88:91], v131, s[64:65] offset:16 nt
	global_load_dwordx4 v[92:95], v131, s[64:65] offset:2048 nt
	global_load_dwordx4 v[96:99], v131, s[64:65] offset:2064 nt
	s_waitcnt vmcnt(28)
	v_pk_add_f32 v[108:109], v[156:157], v[158:159]
	v_pk_add_f32 v[110:111], v[160:161], v[162:163]
	v_pk_add_f32 v[112:113], v[164:165], v[166:167]
	v_pk_add_f32 v[114:115], v[168:169], v[170:171]
	v_pk_mul_f32 v[116:117], v[156:157], v[156:157]
	v_pk_fma_f32 v[116:117], v[158:159], v[158:159], v[116:117]
	v_pk_fma_f32 v[116:117], v[160:161], v[160:161], v[116:117]
	v_pk_fma_f32 v[116:117], v[162:163], v[162:163], v[116:117]
	v_pk_fma_f32 v[116:117], v[164:165], v[164:165], v[116:117]
	v_pk_fma_f32 v[116:117], v[166:167], v[166:167], v[116:117]
	v_pk_fma_f32 v[116:117], v[168:169], v[168:169], v[116:117]
	v_pk_fma_f32 v[116:117], v[170:171], v[170:171], v[116:117]
	v_pk_add_f32 v[108:109], v[108:109], v[110:111]
	v_pk_add_f32 v[112:113], v[112:113], v[114:115]
	v_pk_add_f32 v[108:109], v[108:109], v[112:113]
	v_add_f32_e32 v100, v108, v109
	v_add_f32_e32 v101, v116, v117
	v_pk_add_f32 v[108:109], v[172:173], v[174:175]
	v_pk_add_f32 v[110:111], v[176:177], v[178:179]
	v_pk_add_f32 v[112:113], v[180:181], v[182:183]
	v_pk_add_f32 v[114:115], v[184:185], v[186:187]
	v_pk_mul_f32 v[116:117], v[172:173], v[172:173]
	v_pk_fma_f32 v[116:117], v[174:175], v[174:175], v[116:117]
	v_pk_fma_f32 v[116:117], v[176:177], v[176:177], v[116:117]
	v_pk_fma_f32 v[116:117], v[178:179], v[178:179], v[116:117]
	v_pk_fma_f32 v[116:117], v[180:181], v[180:181], v[116:117]
	v_pk_fma_f32 v[116:117], v[182:183], v[182:183], v[116:117]
	v_pk_fma_f32 v[116:117], v[184:185], v[184:185], v[116:117]
	v_pk_fma_f32 v[116:117], v[186:187], v[186:187], v[116:117]
	v_pk_add_f32 v[108:109], v[108:109], v[110:111]
	v_pk_add_f32 v[112:113], v[112:113], v[114:115]
	v_pk_add_f32 v[108:109], v[108:109], v[112:113]
	v_add_f32_e32 v102, v108, v109
	v_add_f32_e32 v103, v116, v117
	v_pk_add_f32 v[108:109], v[188:189], v[190:191]
	v_pk_add_f32 v[110:111], v[192:193], v[194:195]
	v_pk_add_f32 v[112:113], v[196:197], v[198:199]
	v_pk_add_f32 v[114:115], v[200:201], v[202:203]
	v_pk_mul_f32 v[116:117], v[188:189], v[188:189]
	v_pk_fma_f32 v[116:117], v[190:191], v[190:191], v[116:117]
	v_pk_fma_f32 v[116:117], v[192:193], v[192:193], v[116:117]
	v_pk_fma_f32 v[116:117], v[194:195], v[194:195], v[116:117]
	v_pk_fma_f32 v[116:117], v[196:197], v[196:197], v[116:117]
	v_pk_fma_f32 v[116:117], v[198:199], v[198:199], v[116:117]
	v_pk_fma_f32 v[116:117], v[200:201], v[200:201], v[116:117]
	v_pk_fma_f32 v[116:117], v[202:203], v[202:203], v[116:117]
	v_pk_add_f32 v[108:109], v[108:109], v[110:111]
	v_pk_add_f32 v[112:113], v[112:113], v[114:115]
	v_pk_add_f32 v[108:109], v[108:109], v[112:113]
	v_add_f32_e32 v104, v108, v109
	v_add_f32_e32 v105, v116, v117
	v_pk_add_f32 v[108:109], v[204:205], v[206:207]
	v_pk_add_f32 v[110:111], v[208:209], v[210:211]
	v_pk_add_f32 v[112:113], v[212:213], v[214:215]
	v_pk_add_f32 v[114:115], v[216:217], v[218:219]
	v_pk_mul_f32 v[116:117], v[204:205], v[204:205]
	v_pk_fma_f32 v[116:117], v[206:207], v[206:207], v[116:117]
	v_pk_fma_f32 v[116:117], v[208:209], v[208:209], v[116:117]
	v_pk_fma_f32 v[116:117], v[210:211], v[210:211], v[116:117]
	v_pk_fma_f32 v[116:117], v[212:213], v[212:213], v[116:117]
	v_pk_fma_f32 v[116:117], v[214:215], v[214:215], v[116:117]
	v_pk_fma_f32 v[116:117], v[216:217], v[216:217], v[116:117]
	v_pk_fma_f32 v[116:117], v[218:219], v[218:219], v[116:117]
	v_pk_add_f32 v[108:109], v[108:109], v[110:111]
	v_pk_add_f32 v[112:113], v[112:113], v[114:115]
	v_pk_add_f32 v[108:109], v[108:109], v[112:113]
	v_add_f32_e32 v106, v108, v109
	v_add_f32_e32 v107, v116, v117
	v_add_f32_dpp v100, v100, v100 quad_perm:[1,0,3,2] row_mask:0xf bank_mask:0xf
	v_add_f32_dpp v101, v101, v101 quad_perm:[1,0,3,2] row_mask:0xf bank_mask:0xf
	v_add_f32_dpp v102, v102, v102 quad_perm:[1,0,3,2] row_mask:0xf bank_mask:0xf
	v_add_f32_dpp v103, v103, v103 quad_perm:[1,0,3,2] row_mask:0xf bank_mask:0xf
	v_add_f32_dpp v104, v104, v104 quad_perm:[1,0,3,2] row_mask:0xf bank_mask:0xf
	v_add_f32_dpp v105, v105, v105 quad_perm:[1,0,3,2] row_mask:0xf bank_mask:0xf
	v_add_f32_dpp v106, v106, v106 quad_perm:[1,0,3,2] row_mask:0xf bank_mask:0xf
	v_add_f32_dpp v107, v107, v107 quad_perm:[1,0,3,2] row_mask:0xf bank_mask:0xf
	v_add_f32_dpp v100, v100, v100 quad_perm:[2,3,0,1] row_mask:0xf bank_mask:0xf
	v_add_f32_dpp v101, v101, v101 quad_perm:[2,3,0,1] row_mask:0xf bank_mask:0xf
	v_add_f32_dpp v102, v102, v102 quad_perm:[2,3,0,1] row_mask:0xf bank_mask:0xf
	v_add_f32_dpp v103, v103, v103 quad_perm:[2,3,0,1] row_mask:0xf bank_mask:0xf
	v_add_f32_dpp v104, v104, v104 quad_perm:[2,3,0,1] row_mask:0xf bank_mask:0xf
	v_add_f32_dpp v105, v105, v105 quad_perm:[2,3,0,1] row_mask:0xf bank_mask:0xf
	v_add_f32_dpp v106, v106, v106 quad_perm:[2,3,0,1] row_mask:0xf bank_mask:0xf
	v_add_f32_dpp v107, v107, v107 quad_perm:[2,3,0,1] row_mask:0xf bank_mask:0xf
	v_add_f32_dpp v100, v100, v100 row_half_mirror row_mask:0xf bank_mask:0xf
	v_add_f32_dpp v101, v101, v101 row_half_mirror row_mask:0xf bank_mask:0xf
	v_add_f32_dpp v102, v102, v102 row_half_mirror row_mask:0xf bank_mask:0xf
	v_add_f32_dpp v103, v103, v103 row_half_mirror row_mask:0xf bank_mask:0xf
	v_add_f32_dpp v104, v104, v104 row_half_mirror row_mask:0xf bank_mask:0xf
	v_add_f32_dpp v105, v105, v105 row_half_mirror row_mask:0xf bank_mask:0xf
	v_add_f32_dpp v106, v106, v106 row_half_mirror row_mask:0xf bank_mask:0xf
	v_add_f32_dpp v107, v107, v107 row_half_mirror row_mask:0xf bank_mask:0xf
	v_add_f32_dpp v100, v100, v100 row_mirror row_mask:0xf bank_mask:0xf
	v_add_f32_dpp v101, v101, v101 row_mirror row_mask:0xf bank_mask:0xf
	v_add_f32_dpp v102, v102, v102 row_mirror row_mask:0xf bank_mask:0xf
	v_add_f32_dpp v103, v103, v103 row_mirror row_mask:0xf bank_mask:0xf
	v_add_f32_dpp v104, v104, v104 row_mirror row_mask:0xf bank_mask:0xf
	v_add_f32_dpp v105, v105, v105 row_mirror row_mask:0xf bank_mask:0xf
	v_add_f32_dpp v106, v106, v106 row_mirror row_mask:0xf bank_mask:0xf
	v_add_f32_dpp v107, v107, v107 row_mirror row_mask:0xf bank_mask:0xf
	v_mov_b32_e32 v108, v100
	v_mov_b32_e32 v109, v101
	v_mov_b32_e32 v110, v102
	v_mov_b32_e32 v111, v103
	v_mov_b32_e32 v112, v104
	v_mov_b32_e32 v113, v105
	v_mov_b32_e32 v114, v106
	v_mov_b32_e32 v115, v107
	s_nop 1
	v_permlane16_swap_b32_e32 v108, v100
	v_permlane16_swap_b32_e32 v109, v101
	v_permlane16_swap_b32_e32 v110, v102
	v_permlane16_swap_b32_e32 v111, v103
	v_permlane16_swap_b32_e32 v112, v104
	v_permlane16_swap_b32_e32 v113, v105
	v_permlane16_swap_b32_e32 v114, v106
	v_permlane16_swap_b32_e32 v115, v107
	v_add_f32_e32 v100, v100, v108
	v_add_f32_e32 v101, v101, v109
	v_add_f32_e32 v102, v102, v110
	v_add_f32_e32 v103, v103, v111
	v_add_f32_e32 v104, v104, v112
	v_add_f32_e32 v105, v105, v113
	v_add_f32_e32 v106, v106, v114
	v_add_f32_e32 v107, v107, v115
	v_mov_b32_e32 v108, v100
	v_mov_b32_e32 v109, v101
	v_mov_b32_e32 v110, v102
	v_mov_b32_e32 v111, v103
	v_mov_b32_e32 v112, v104
	v_mov_b32_e32 v113, v105
	v_mov_b32_e32 v114, v106
	v_mov_b32_e32 v115, v107
	s_nop 1
	v_permlane32_swap_b32_e32 v108, v100
	v_permlane32_swap_b32_e32 v109, v101
	v_permlane32_swap_b32_e32 v110, v102
	v_permlane32_swap_b32_e32 v111, v103
	v_permlane32_swap_b32_e32 v112, v104
	v_permlane32_swap_b32_e32 v113, v105
	v_permlane32_swap_b32_e32 v114, v106
	v_permlane32_swap_b32_e32 v115, v107
	v_add_f32_e32 v100, v100, v108
	v_add_f32_e32 v101, v101, v109
	v_add_f32_e32 v102, v102, v110
	v_add_f32_e32 v103, v103, v111
	v_add_f32_e32 v104, v104, v112
	v_add_f32_e32 v105, v105, v113
	v_add_f32_e32 v106, v106, v114
	v_add_f32_e32 v107, v107, v115
	v_mul_f32_e32 v238, 0x3a800000, v100
	v_mul_f32_e32 v116, 0x3a800000, v101
	v_fma_f32 v116, -v238, v238, v116
	v_max_f32_e32 v116, 0, v116
	v_add_f32_e32 v116, 0x3727c5ac, v116
	v_mul_f32_e32 v240, 0x3a800000, v102
	v_mul_f32_e32 v118, 0x3a800000, v103
	v_fma_f32 v118, -v240, v240, v118
	v_max_f32_e32 v118, 0, v118
	v_add_f32_e32 v118, 0x3727c5ac, v118
	v_mul_f32_e32 v242, 0x3a800000, v104
	v_mul_f32_e32 v120, 0x3a800000, v105
	v_fma_f32 v120, -v242, v242, v120
	v_max_f32_e32 v120, 0, v120
	v_add_f32_e32 v120, 0x3727c5ac, v120
	v_mul_f32_e32 v244, 0x3a800000, v106
	v_mul_f32_e32 v122, 0x3a800000, v107
	v_fma_f32 v122, -v244, v244, v122
	v_max_f32_e32 v122, 0, v122
	v_add_f32_e32 v122, 0x3727c5ac, v122
	v_rsq_f32_e32 v117, v116
	v_rsq_f32_e32 v119, v118
	v_rsq_f32_e32 v121, v120
	v_rsq_f32_e32 v123, v122
	s_nop 0
	v_mul_f32_e32 v124, v116, v117
	v_mul_f32_e32 v124, v124, v117
	v_fmaak_f32 v124, -0.5, v124, 0x3fc00000
	v_mul_f32_e32 v239, v117, v124
	v_mul_f32_e32 v125, v118, v119
	v_mul_f32_e32 v125, v125, v119
	v_fmaak_f32 v125, -0.5, v125, 0x3fc00000
	v_mul_f32_e32 v241, v119, v125
	v_mul_f32_e32 v126, v120, v121
	v_mul_f32_e32 v126, v126, v121
	v_fmaak_f32 v126, -0.5, v126, 0x3fc00000
	v_mul_f32_e32 v243, v121, v126
	v_mul_f32_e32 v127, v122, v123
	v_mul_f32_e32 v127, v127, v123
	v_fmaak_f32 v127, -0.5, v127, 0x3fc00000
	v_mul_f32_e32 v245, v123, v127
	v_pk_add_f32 v[156:157], v[156:157], v[238:239] op_sel_hi:[1,0] neg_lo:[0,1] neg_hi:[0,1]
	v_pk_add_f32 v[158:159], v[158:159], v[238:239] op_sel_hi:[1,0] neg_lo:[0,1] neg_hi:[0,1]
	v_pk_add_f32 v[160:161], v[160:161], v[238:239] op_sel_hi:[1,0] neg_lo:[0,1] neg_hi:[0,1]
	v_pk_add_f32 v[162:163], v[162:163], v[238:239] op_sel_hi:[1,0] neg_lo:[0,1] neg_hi:[0,1]
	v_pk_add_f32 v[164:165], v[164:165], v[238:239] op_sel_hi:[1,0] neg_lo:[0,1] neg_hi:[0,1]
	v_pk_add_f32 v[166:167], v[166:167], v[238:239] op_sel_hi:[1,0] neg_lo:[0,1] neg_hi:[0,1]
	v_pk_add_f32 v[168:169], v[168:169], v[238:239] op_sel_hi:[1,0] neg_lo:[0,1] neg_hi:[0,1]
	v_pk_add_f32 v[170:171], v[170:171], v[238:239] op_sel_hi:[1,0] neg_lo:[0,1] neg_hi:[0,1]
	v_pk_mul_f32 v[156:157], v[156:157], v[238:239] op_sel:[0,1] op_sel_hi:[1,1]
	v_pk_mul_f32 v[158:159], v[158:159], v[238:239] op_sel:[0,1] op_sel_hi:[1,1]
	v_pk_mul_f32 v[160:161], v[160:161], v[238:239] op_sel:[0,1] op_sel_hi:[1,1]
	v_pk_mul_f32 v[162:163], v[162:163], v[238:239] op_sel:[0,1] op_sel_hi:[1,1]
	v_pk_mul_f32 v[164:165], v[164:165], v[238:239] op_sel:[0,1] op_sel_hi:[1,1]
	v_pk_mul_f32 v[166:167], v[166:167], v[238:239] op_sel:[0,1] op_sel_hi:[1,1]
	v_pk_mul_f32 v[168:169], v[168:169], v[238:239] op_sel:[0,1] op_sel_hi:[1,1]
	v_pk_mul_f32 v[170:171], v[170:171], v[238:239] op_sel:[0,1] op_sel_hi:[1,1]
	v_pk_fma_f32 v[156:157], v[4:5], v[156:157], v[20:21]
	v_pk_fma_f32 v[158:159], v[6:7], v[158:159], v[22:23]
	v_pk_fma_f32 v[160:161], v[8:9], v[160:161], v[24:25]
	v_pk_fma_f32 v[162:163], v[10:11], v[162:163], v[26:27]
	v_pk_fma_f32 v[164:165], v[12:13], v[164:165], v[28:29]
	v_pk_fma_f32 v[166:167], v[14:15], v[166:167], v[30:31]
	v_pk_fma_f32 v[168:169], v[16:17], v[168:169], v[32:33]
	v_pk_fma_f32 v[170:171], v[18:19], v[170:171], v[34:35]
	v_cvt_pk_bf16_f32 v156, v156, v157
	v_cvt_pk_bf16_f32 v157, v158, v159
	v_cvt_pk_bf16_f32 v158, v160, v161
	v_cvt_pk_bf16_f32 v159, v162, v163
	v_cvt_pk_bf16_f32 v164, v164, v165
	v_cvt_pk_bf16_f32 v165, v166, v167
	v_cvt_pk_bf16_f32 v166, v168, v169
	v_cvt_pk_bf16_f32 v167, v170, v171
	v_lshl_add_u32 v3, s40, 11, v2
	global_store_dwordx4 v3, v[156:159], s[96:97] sc1
	global_store_dwordx4 v3, v[164:167], s[96:97] offset:1024 sc1
	v_pk_add_f32 v[172:173], v[172:173], v[240:241] op_sel_hi:[1,0] neg_lo:[0,1] neg_hi:[0,1]
	v_pk_add_f32 v[174:175], v[174:175], v[240:241] op_sel_hi:[1,0] neg_lo:[0,1] neg_hi:[0,1]
	v_pk_add_f32 v[176:177], v[176:177], v[240:241] op_sel_hi:[1,0] neg_lo:[0,1] neg_hi:[0,1]
	v_pk_add_f32 v[178:179], v[178:179], v[240:241] op_sel_hi:[1,0] neg_lo:[0,1] neg_hi:[0,1]
	v_pk_add_f32 v[180:181], v[180:181], v[240:241] op_sel_hi:[1,0] neg_lo:[0,1] neg_hi:[0,1]
	v_pk_add_f32 v[182:183], v[182:183], v[240:241] op_sel_hi:[1,0] neg_lo:[0,1] neg_hi:[0,1]
	v_pk_add_f32 v[184:185], v[184:185], v[240:241] op_sel_hi:[1,0] neg_lo:[0,1] neg_hi:[0,1]
	v_pk_add_f32 v[186:187], v[186:187], v[240:241] op_sel_hi:[1,0] neg_lo:[0,1] neg_hi:[0,1]
	v_pk_mul_f32 v[172:173], v[172:173], v[240:241] op_sel:[0,1] op_sel_hi:[1,1]
	v_pk_mul_f32 v[174:175], v[174:175], v[240:241] op_sel:[0,1] op_sel_hi:[1,1]
	v_pk_mul_f32 v[176:177], v[176:177], v[240:241] op_sel:[0,1] op_sel_hi:[1,1]
	v_pk_mul_f32 v[178:179], v[178:179], v[240:241] op_sel:[0,1] op_sel_hi:[1,1]
	v_pk_mul_f32 v[180:181], v[180:181], v[240:241] op_sel:[0,1] op_sel_hi:[1,1]
	v_pk_mul_f32 v[182:183], v[182:183], v[240:241] op_sel:[0,1] op_sel_hi:[1,1]
	v_pk_mul_f32 v[184:185], v[184:185], v[240:241] op_sel:[0,1] op_sel_hi:[1,1]
	v_pk_mul_f32 v[186:187], v[186:187], v[240:241] op_sel:[0,1] op_sel_hi:[1,1]
	v_pk_fma_f32 v[172:173], v[4:5], v[172:173], v[20:21]
	v_pk_fma_f32 v[174:175], v[6:7], v[174:175], v[22:23]
	v_pk_fma_f32 v[176:177], v[8:9], v[176:177], v[24:25]
	v_pk_fma_f32 v[178:179], v[10:11], v[178:179], v[26:27]
	v_pk_fma_f32 v[180:181], v[12:13], v[180:181], v[28:29]
	v_pk_fma_f32 v[182:183], v[14:15], v[182:183], v[30:31]
	v_pk_fma_f32 v[184:185], v[16:17], v[184:185], v[32:33]
	v_pk_fma_f32 v[186:187], v[18:19], v[186:187], v[34:35]
	v_cvt_pk_bf16_f32 v172, v172, v173
	v_cvt_pk_bf16_f32 v173, v174, v175
	v_cvt_pk_bf16_f32 v174, v176, v177
	v_cvt_pk_bf16_f32 v175, v178, v179
	v_cvt_pk_bf16_f32 v180, v180, v181
	v_cvt_pk_bf16_f32 v181, v182, v183
	v_cvt_pk_bf16_f32 v182, v184, v185
	v_cvt_pk_bf16_f32 v183, v186, v187
	v_lshl_add_u32 v3, s41, 11, v2
	global_store_dwordx4 v3, v[172:175], s[96:97] sc1
	global_store_dwordx4 v3, v[180:183], s[96:97] offset:1024 sc1
	v_pk_add_f32 v[188:189], v[188:189], v[242:243] op_sel_hi:[1,0] neg_lo:[0,1] neg_hi:[0,1]
	v_pk_add_f32 v[190:191], v[190:191], v[242:243] op_sel_hi:[1,0] neg_lo:[0,1] neg_hi:[0,1]
	v_pk_add_f32 v[192:193], v[192:193], v[242:243] op_sel_hi:[1,0] neg_lo:[0,1] neg_hi:[0,1]
	v_pk_add_f32 v[194:195], v[194:195], v[242:243] op_sel_hi:[1,0] neg_lo:[0,1] neg_hi:[0,1]
	v_pk_add_f32 v[196:197], v[196:197], v[242:243] op_sel_hi:[1,0] neg_lo:[0,1] neg_hi:[0,1]
	v_pk_add_f32 v[198:199], v[198:199], v[242:243] op_sel_hi:[1,0] neg_lo:[0,1] neg_hi:[0,1]
	v_pk_add_f32 v[200:201], v[200:201], v[242:243] op_sel_hi:[1,0] neg_lo:[0,1] neg_hi:[0,1]
	v_pk_add_f32 v[202:203], v[202:203], v[242:243] op_sel_hi:[1,0] neg_lo:[0,1] neg_hi:[0,1]
	v_pk_mul_f32 v[188:189], v[188:189], v[242:243] op_sel:[0,1] op_sel_hi:[1,1]
	v_pk_mul_f32 v[190:191], v[190:191], v[242:243] op_sel:[0,1] op_sel_hi:[1,1]
	v_pk_mul_f32 v[192:193], v[192:193], v[242:243] op_sel:[0,1] op_sel_hi:[1,1]
	v_pk_mul_f32 v[194:195], v[194:195], v[242:243] op_sel:[0,1] op_sel_hi:[1,1]
	v_pk_mul_f32 v[196:197], v[196:197], v[242:243] op_sel:[0,1] op_sel_hi:[1,1]
	v_pk_mul_f32 v[198:199], v[198:199], v[242:243] op_sel:[0,1] op_sel_hi:[1,1]
	v_pk_mul_f32 v[200:201], v[200:201], v[242:243] op_sel:[0,1] op_sel_hi:[1,1]
	v_pk_mul_f32 v[202:203], v[202:203], v[242:243] op_sel:[0,1] op_sel_hi:[1,1]
	v_pk_fma_f32 v[188:189], v[4:5], v[188:189], v[20:21]
	v_pk_fma_f32 v[190:191], v[6:7], v[190:191], v[22:23]
	v_pk_fma_f32 v[192:193], v[8:9], v[192:193], v[24:25]
	v_pk_fma_f32 v[194:195], v[10:11], v[194:195], v[26:27]
	v_pk_fma_f32 v[196:197], v[12:13], v[196:197], v[28:29]
	v_pk_fma_f32 v[198:199], v[14:15], v[198:199], v[30:31]
	v_pk_fma_f32 v[200:201], v[16:17], v[200:201], v[32:33]
	v_pk_fma_f32 v[202:203], v[18:19], v[202:203], v[34:35]
	v_cvt_pk_bf16_f32 v188, v188, v189
	v_cvt_pk_bf16_f32 v189, v190, v191
	v_cvt_pk_bf16_f32 v190, v192, v193
	v_cvt_pk_bf16_f32 v191, v194, v195
	v_cvt_pk_bf16_f32 v196, v196, v197
	v_cvt_pk_bf16_f32 v197, v198, v199
	v_cvt_pk_bf16_f32 v198, v200, v201
	v_cvt_pk_bf16_f32 v199, v202, v203
	v_lshl_add_u32 v3, s42, 11, v2
	global_store_dwordx4 v3, v[188:191], s[96:97] sc1
	global_store_dwordx4 v3, v[196:199], s[96:97] offset:1024 sc1
	v_pk_add_f32 v[204:205], v[204:205], v[244:245] op_sel_hi:[1,0] neg_lo:[0,1] neg_hi:[0,1]
	v_pk_add_f32 v[206:207], v[206:207], v[244:245] op_sel_hi:[1,0] neg_lo:[0,1] neg_hi:[0,1]
	v_pk_add_f32 v[208:209], v[208:209], v[244:245] op_sel_hi:[1,0] neg_lo:[0,1] neg_hi:[0,1]
	v_pk_add_f32 v[210:211], v[210:211], v[244:245] op_sel_hi:[1,0] neg_lo:[0,1] neg_hi:[0,1]
	v_pk_add_f32 v[212:213], v[212:213], v[244:245] op_sel_hi:[1,0] neg_lo:[0,1] neg_hi:[0,1]
	v_pk_add_f32 v[214:215], v[214:215], v[244:245] op_sel_hi:[1,0] neg_lo:[0,1] neg_hi:[0,1]
	v_pk_add_f32 v[216:217], v[216:217], v[244:245] op_sel_hi:[1,0] neg_lo:[0,1] neg_hi:[0,1]
	v_pk_add_f32 v[218:219], v[218:219], v[244:245] op_sel_hi:[1,0] neg_lo:[0,1] neg_hi:[0,1]
	v_pk_mul_f32 v[204:205], v[204:205], v[244:245] op_sel:[0,1] op_sel_hi:[1,1]
	v_pk_mul_f32 v[206:207], v[206:207], v[244:245] op_sel:[0,1] op_sel_hi:[1,1]
	v_pk_mul_f32 v[208:209], v[208:209], v[244:245] op_sel:[0,1] op_sel_hi:[1,1]
	v_pk_mul_f32 v[210:211], v[210:211], v[244:245] op_sel:[0,1] op_sel_hi:[1,1]
	v_pk_mul_f32 v[212:213], v[212:213], v[244:245] op_sel:[0,1] op_sel_hi:[1,1]
	v_pk_mul_f32 v[214:215], v[214:215], v[244:245] op_sel:[0,1] op_sel_hi:[1,1]
	v_pk_mul_f32 v[216:217], v[216:217], v[244:245] op_sel:[0,1] op_sel_hi:[1,1]
	v_pk_mul_f32 v[218:219], v[218:219], v[244:245] op_sel:[0,1] op_sel_hi:[1,1]
	v_pk_fma_f32 v[204:205], v[4:5], v[204:205], v[20:21]
	v_pk_fma_f32 v[206:207], v[6:7], v[206:207], v[22:23]
	v_pk_fma_f32 v[208:209], v[8:9], v[208:209], v[24:25]
	v_pk_fma_f32 v[210:211], v[10:11], v[210:211], v[26:27]
	v_pk_fma_f32 v[212:213], v[12:13], v[212:213], v[28:29]
	v_pk_fma_f32 v[214:215], v[14:15], v[214:215], v[30:31]
	v_pk_fma_f32 v[216:217], v[16:17], v[216:217], v[32:33]
	v_pk_fma_f32 v[218:219], v[18:19], v[218:219], v[34:35]
	v_cvt_pk_bf16_f32 v204, v204, v205
	v_cvt_pk_bf16_f32 v205, v206, v207
	v_cvt_pk_bf16_f32 v206, v208, v209
	v_cvt_pk_bf16_f32 v207, v210, v211
	v_cvt_pk_bf16_f32 v212, v212, v213
	v_cvt_pk_bf16_f32 v213, v214, v215
	v_cvt_pk_bf16_f32 v214, v216, v217
	v_cvt_pk_bf16_f32 v215, v218, v219
	v_lshl_add_u32 v3, s43, 11, v2
	global_store_dwordx4 v3, v[204:207], s[96:97] sc1
	global_store_dwordx4 v3, v[212:215], s[96:97] offset:1024 sc1
	s_mov_b64 s[52:53], exec
	s_mov_b64 exec, 1
	v_mov_b32_e32 v3, s40
	v_lshlrev_b32_e32 v3, 3, v3
	global_store_dwordx2 v3, v[238:239], s[92:93] sc1
	v_mov_b32_e32 v3, s41
	v_lshlrev_b32_e32 v3, 3, v3
	global_store_dwordx2 v3, v[240:241], s[92:93] sc1
	v_mov_b32_e32 v3, s42
	v_lshlrev_b32_e32 v3, 3, v3
	global_store_dwordx2 v3, v[242:243], s[92:93] sc1
	v_mov_b32_e32 v3, s43
	v_lshlrev_b32_e32 v3, 3, v3
	global_store_dwordx2 v3, v[244:245], s[92:93] sc1
	s_mov_b64 exec, s[52:53]
	s_add_u32 s40, s46, 0x4800
	v_lshl_add_u32 v132, s40, 12, v1
	s_add_u32 s41, s46, 0x5800
	v_lshl_add_u32 v133, s41, 12, v1
	s_add_u32 s42, s46, 0x6800
	v_lshl_add_u32 v134, s42, 12, v1
	s_add_u32 s43, s46, 0x7800
	v_lshl_add_u32 v135, s43, 12, v1
	global_load_dwordx4 v[156:159], v132, s[64:65] nt
	global_load_dwordx4 v[160:163], v132, s[64:65] offset:16 nt
	global_load_dwordx4 v[164:167], v132, s[64:65] offset:2048 nt
	global_load_dwordx4 v[168:171], v132, s[64:65] offset:2064 nt
	global_load_dwordx4 v[172:175], v133, s[64:65] nt
	global_load_dwordx4 v[176:179], v133, s[64:65] offset:16 nt
	global_load_dwordx4 v[180:183], v133, s[64:65] offset:2048 nt
	global_load_dwordx4 v[184:187], v133, s[64:65] offset:2064 nt
	global_load_dwordx4 v[188:191], v134, s[64:65] nt
	global_load_dwordx4 v[192:195], v134, s[64:65] offset:16 nt
	global_load_dwordx4 v[196:199], v134, s[64:65] offset:2048 nt
	global_load_dwordx4 v[200:203], v134, s[64:65] offset:2064 nt
	global_load_dwordx4 v[204:207], v135, s[64:65] nt
	global_load_dwordx4 v[208:211], v135, s[64:65] offset:16 nt
	global_load_dwordx4 v[212:215], v135, s[64:65] offset:2048 nt
	global_load_dwordx4 v[216:219], v135, s[64:65] offset:2064 nt
	s_waitcnt vmcnt(28)
	v_pk_add_f32 v[108:109], v[36:37], v[38:39]
	v_pk_add_f32 v[110:111], v[40:41], v[42:43]
	v_pk_add_f32 v[112:113], v[44:45], v[46:47]
	v_pk_add_f32 v[114:115], v[48:49], v[50:51]
	v_pk_mul_f32 v[116:117], v[36:37], v[36:37]
	v_pk_fma_f32 v[116:117], v[38:39], v[38:39], v[116:117]
	v_pk_fma_f32 v[116:117], v[40:41], v[40:41], v[116:117]
	v_pk_fma_f32 v[116:117], v[42:43], v[42:43], v[116:117]
	v_pk_fma_f32 v[116:117], v[44:45], v[44:45], v[116:117]
	v_pk_fma_f32 v[116:117], v[46:47], v[46:47], v[116:117]
	v_pk_fma_f32 v[116:117], v[48:49], v[48:49], v[116:117]
	v_pk_fma_f32 v[116:117], v[50:51], v[50:51], v[116:117]
	v_pk_add_f32 v[108:109], v[108:109], v[110:111]
	v_pk_add_f32 v[112:113], v[112:113], v[114:115]
	v_pk_add_f32 v[108:109], v[108:109], v[112:113]
	v_add_f32_e32 v100, v108, v109
	v_add_f32_e32 v101, v116, v117
	v_pk_add_f32 v[108:109], v[52:53], v[54:55]
	v_pk_add_f32 v[110:111], v[56:57], v[58:59]
	v_pk_add_f32 v[112:113], v[60:61], v[62:63]
	v_pk_add_f32 v[114:115], v[64:65], v[66:67]
	v_pk_mul_f32 v[116:117], v[52:53], v[52:53]
	v_pk_fma_f32 v[116:117], v[54:55], v[54:55], v[116:117]
	v_pk_fma_f32 v[116:117], v[56:57], v[56:57], v[116:117]
	v_pk_fma_f32 v[116:117], v[58:59], v[58:59], v[116:117]
	v_pk_fma_f32 v[116:117], v[60:61], v[60:61], v[116:117]
	v_pk_fma_f32 v[116:117], v[62:63], v[62:63], v[116:117]
	v_pk_fma_f32 v[116:117], v[64:65], v[64:65], v[116:117]
	v_pk_fma_f32 v[116:117], v[66:67], v[66:67], v[116:117]
	v_pk_add_f32 v[108:109], v[108:109], v[110:111]
	v_pk_add_f32 v[112:113], v[112:113], v[114:115]
	v_pk_add_f32 v[108:109], v[108:109], v[112:113]
	v_add_f32_e32 v102, v108, v109
	v_add_f32_e32 v103, v116, v117
	v_pk_add_f32 v[108:109], v[68:69], v[70:71]
	v_pk_add_f32 v[110:111], v[72:73], v[74:75]
	v_pk_add_f32 v[112:113], v[76:77], v[78:79]
	v_pk_add_f32 v[114:115], v[80:81], v[82:83]
	v_pk_mul_f32 v[116:117], v[68:69], v[68:69]
	v_pk_fma_f32 v[116:117], v[70:71], v[70:71], v[116:117]
	v_pk_fma_f32 v[116:117], v[72:73], v[72:73], v[116:117]
	v_pk_fma_f32 v[116:117], v[74:75], v[74:75], v[116:117]
	v_pk_fma_f32 v[116:117], v[76:77], v[76:77], v[116:117]
	v_pk_fma_f32 v[116:117], v[78:79], v[78:79], v[116:117]
	v_pk_fma_f32 v[116:117], v[80:81], v[80:81], v[116:117]
	v_pk_fma_f32 v[116:117], v[82:83], v[82:83], v[116:117]
	v_pk_add_f32 v[108:109], v[108:109], v[110:111]
	v_pk_add_f32 v[112:113], v[112:113], v[114:115]
	v_pk_add_f32 v[108:109], v[108:109], v[112:113]
	v_add_f32_e32 v104, v108, v109
	v_add_f32_e32 v105, v116, v117
	v_pk_add_f32 v[108:109], v[84:85], v[86:87]
	v_pk_add_f32 v[110:111], v[88:89], v[90:91]
	v_pk_add_f32 v[112:113], v[92:93], v[94:95]
	v_pk_add_f32 v[114:115], v[96:97], v[98:99]
	v_pk_mul_f32 v[116:117], v[84:85], v[84:85]
	v_pk_fma_f32 v[116:117], v[86:87], v[86:87], v[116:117]
	v_pk_fma_f32 v[116:117], v[88:89], v[88:89], v[116:117]
	v_pk_fma_f32 v[116:117], v[90:91], v[90:91], v[116:117]
	v_pk_fma_f32 v[116:117], v[92:93], v[92:93], v[116:117]
	v_pk_fma_f32 v[116:117], v[94:95], v[94:95], v[116:117]
	v_pk_fma_f32 v[116:117], v[96:97], v[96:97], v[116:117]
	v_pk_fma_f32 v[116:117], v[98:99], v[98:99], v[116:117]
	v_pk_add_f32 v[108:109], v[108:109], v[110:111]
	v_pk_add_f32 v[112:113], v[112:113], v[114:115]
	v_pk_add_f32 v[108:109], v[108:109], v[112:113]
	v_add_f32_e32 v106, v108, v109
	v_add_f32_e32 v107, v116, v117
	v_add_f32_dpp v100, v100, v100 quad_perm:[1,0,3,2] row_mask:0xf bank_mask:0xf
	v_add_f32_dpp v101, v101, v101 quad_perm:[1,0,3,2] row_mask:0xf bank_mask:0xf
	v_add_f32_dpp v102, v102, v102 quad_perm:[1,0,3,2] row_mask:0xf bank_mask:0xf
	v_add_f32_dpp v103, v103, v103 quad_perm:[1,0,3,2] row_mask:0xf bank_mask:0xf
	v_add_f32_dpp v104, v104, v104 quad_perm:[1,0,3,2] row_mask:0xf bank_mask:0xf
	v_add_f32_dpp v105, v105, v105 quad_perm:[1,0,3,2] row_mask:0xf bank_mask:0xf
	v_add_f32_dpp v106, v106, v106 quad_perm:[1,0,3,2] row_mask:0xf bank_mask:0xf
	v_add_f32_dpp v107, v107, v107 quad_perm:[1,0,3,2] row_mask:0xf bank_mask:0xf
	v_add_f32_dpp v100, v100, v100 quad_perm:[2,3,0,1] row_mask:0xf bank_mask:0xf
	v_add_f32_dpp v101, v101, v101 quad_perm:[2,3,0,1] row_mask:0xf bank_mask:0xf
	v_add_f32_dpp v102, v102, v102 quad_perm:[2,3,0,1] row_mask:0xf bank_mask:0xf
	v_add_f32_dpp v103, v103, v103 quad_perm:[2,3,0,1] row_mask:0xf bank_mask:0xf
	v_add_f32_dpp v104, v104, v104 quad_perm:[2,3,0,1] row_mask:0xf bank_mask:0xf
	v_add_f32_dpp v105, v105, v105 quad_perm:[2,3,0,1] row_mask:0xf bank_mask:0xf
	v_add_f32_dpp v106, v106, v106 quad_perm:[2,3,0,1] row_mask:0xf bank_mask:0xf
	v_add_f32_dpp v107, v107, v107 quad_perm:[2,3,0,1] row_mask:0xf bank_mask:0xf
	v_add_f32_dpp v100, v100, v100 row_half_mirror row_mask:0xf bank_mask:0xf
	v_add_f32_dpp v101, v101, v101 row_half_mirror row_mask:0xf bank_mask:0xf
	v_add_f32_dpp v102, v102, v102 row_half_mirror row_mask:0xf bank_mask:0xf
	v_add_f32_dpp v103, v103, v103 row_half_mirror row_mask:0xf bank_mask:0xf
	v_add_f32_dpp v104, v104, v104 row_half_mirror row_mask:0xf bank_mask:0xf
	v_add_f32_dpp v105, v105, v105 row_half_mirror row_mask:0xf bank_mask:0xf
	v_add_f32_dpp v106, v106, v106 row_half_mirror row_mask:0xf bank_mask:0xf
	v_add_f32_dpp v107, v107, v107 row_half_mirror row_mask:0xf bank_mask:0xf
	v_add_f32_dpp v100, v100, v100 row_mirror row_mask:0xf bank_mask:0xf
	v_add_f32_dpp v101, v101, v101 row_mirror row_mask:0xf bank_mask:0xf
	v_add_f32_dpp v102, v102, v102 row_mirror row_mask:0xf bank_mask:0xf
	v_add_f32_dpp v103, v103, v103 row_mirror row_mask:0xf bank_mask:0xf
	v_add_f32_dpp v104, v104, v104 row_mirror row_mask:0xf bank_mask:0xf
	v_add_f32_dpp v105, v105, v105 row_mirror row_mask:0xf bank_mask:0xf
	v_add_f32_dpp v106, v106, v106 row_mirror row_mask:0xf bank_mask:0xf
	v_add_f32_dpp v107, v107, v107 row_mirror row_mask:0xf bank_mask:0xf
	v_mov_b32_e32 v108, v100
	v_mov_b32_e32 v109, v101
	v_mov_b32_e32 v110, v102
	v_mov_b32_e32 v111, v103
	v_mov_b32_e32 v112, v104
	v_mov_b32_e32 v113, v105
	v_mov_b32_e32 v114, v106
	v_mov_b32_e32 v115, v107
	s_nop 1
	v_permlane16_swap_b32_e32 v108, v100
	v_permlane16_swap_b32_e32 v109, v101
	v_permlane16_swap_b32_e32 v110, v102
	v_permlane16_swap_b32_e32 v111, v103
	v_permlane16_swap_b32_e32 v112, v104
	v_permlane16_swap_b32_e32 v113, v105
	v_permlane16_swap_b32_e32 v114, v106
	v_permlane16_swap_b32_e32 v115, v107
	v_add_f32_e32 v100, v100, v108
	v_add_f32_e32 v101, v101, v109
	v_add_f32_e32 v102, v102, v110
	v_add_f32_e32 v103, v103, v111
	v_add_f32_e32 v104, v104, v112
	v_add_f32_e32 v105, v105, v113
	v_add_f32_e32 v106, v106, v114
	v_add_f32_e32 v107, v107, v115
	v_mov_b32_e32 v108, v100
	v_mov_b32_e32 v109, v101
	v_mov_b32_e32 v110, v102
	v_mov_b32_e32 v111, v103
	v_mov_b32_e32 v112, v104
	v_mov_b32_e32 v113, v105
	v_mov_b32_e32 v114, v106
	v_mov_b32_e32 v115, v107
	s_nop 1
	v_permlane32_swap_b32_e32 v108, v100
	v_permlane32_swap_b32_e32 v109, v101
	v_permlane32_swap_b32_e32 v110, v102
	v_permlane32_swap_b32_e32 v111, v103
	v_permlane32_swap_b32_e32 v112, v104
	v_permlane32_swap_b32_e32 v113, v105
	v_permlane32_swap_b32_e32 v114, v106
	v_permlane32_swap_b32_e32 v115, v107
	v_add_f32_e32 v100, v100, v108
	v_add_f32_e32 v101, v101, v109
	v_add_f32_e32 v102, v102, v110
	v_add_f32_e32 v103, v103, v111
	v_add_f32_e32 v104, v104, v112
	v_add_f32_e32 v105, v105, v113
	v_add_f32_e32 v106, v106, v114
	v_add_f32_e32 v107, v107, v115
	v_mul_f32_e32 v230, 0x3a800000, v100
	v_mul_f32_e32 v116, 0x3a800000, v101
	v_fma_f32 v116, -v230, v230, v116
	v_max_f32_e32 v116, 0, v116
	v_add_f32_e32 v116, 0x3727c5ac, v116
	v_mul_f32_e32 v232, 0x3a800000, v102
	v_mul_f32_e32 v118, 0x3a800000, v103
	v_fma_f32 v118, -v232, v232, v118
	v_max_f32_e32 v118, 0, v118
	v_add_f32_e32 v118, 0x3727c5ac, v118
	v_mul_f32_e32 v234, 0x3a800000, v104
	v_mul_f32_e32 v120, 0x3a800000, v105
	v_fma_f32 v120, -v234, v234, v120
	v_max_f32_e32 v120, 0, v120
	v_add_f32_e32 v120, 0x3727c5ac, v120
	v_mul_f32_e32 v236, 0x3a800000, v106
	v_mul_f32_e32 v122, 0x3a800000, v107
	v_fma_f32 v122, -v236, v236, v122
	v_max_f32_e32 v122, 0, v122
	v_add_f32_e32 v122, 0x3727c5ac, v122
	v_rsq_f32_e32 v117, v116
	v_rsq_f32_e32 v119, v118
	v_rsq_f32_e32 v121, v120
	v_rsq_f32_e32 v123, v122
	s_nop 0
	v_mul_f32_e32 v124, v116, v117
	v_mul_f32_e32 v124, v124, v117
	v_fmaak_f32 v124, -0.5, v124, 0x3fc00000
	v_mul_f32_e32 v231, v117, v124
	v_mul_f32_e32 v125, v118, v119
	v_mul_f32_e32 v125, v125, v119
	v_fmaak_f32 v125, -0.5, v125, 0x3fc00000
	v_mul_f32_e32 v233, v119, v125
	v_mul_f32_e32 v126, v120, v121
	v_mul_f32_e32 v126, v126, v121
	v_fmaak_f32 v126, -0.5, v126, 0x3fc00000
	v_mul_f32_e32 v235, v121, v126
	v_mul_f32_e32 v127, v122, v123
	v_mul_f32_e32 v127, v127, v123
	v_fmaak_f32 v127, -0.5, v127, 0x3fc00000
	v_mul_f32_e32 v237, v123, v127
	v_pk_add_f32 v[36:37], v[36:37], v[230:231] op_sel_hi:[1,0] neg_lo:[0,1] neg_hi:[0,1]
	v_pk_add_f32 v[38:39], v[38:39], v[230:231] op_sel_hi:[1,0] neg_lo:[0,1] neg_hi:[0,1]
	v_pk_add_f32 v[40:41], v[40:41], v[230:231] op_sel_hi:[1,0] neg_lo:[0,1] neg_hi:[0,1]
	v_pk_add_f32 v[42:43], v[42:43], v[230:231] op_sel_hi:[1,0] neg_lo:[0,1] neg_hi:[0,1]
	v_pk_add_f32 v[44:45], v[44:45], v[230:231] op_sel_hi:[1,0] neg_lo:[0,1] neg_hi:[0,1]
	v_pk_add_f32 v[46:47], v[46:47], v[230:231] op_sel_hi:[1,0] neg_lo:[0,1] neg_hi:[0,1]
	v_pk_add_f32 v[48:49], v[48:49], v[230:231] op_sel_hi:[1,0] neg_lo:[0,1] neg_hi:[0,1]
	v_pk_add_f32 v[50:51], v[50:51], v[230:231] op_sel_hi:[1,0] neg_lo:[0,1] neg_hi:[0,1]
	v_pk_mul_f32 v[36:37], v[36:37], v[230:231] op_sel:[0,1] op_sel_hi:[1,1]
	v_pk_mul_f32 v[38:39], v[38:39], v[230:231] op_sel:[0,1] op_sel_hi:[1,1]
	v_pk_mul_f32 v[40:41], v[40:41], v[230:231] op_sel:[0,1] op_sel_hi:[1,1]
	v_pk_mul_f32 v[42:43], v[42:43], v[230:231] op_sel:[0,1] op_sel_hi:[1,1]
	v_pk_mul_f32 v[44:45], v[44:45], v[230:231] op_sel:[0,1] op_sel_hi:[1,1]
	v_pk_mul_f32 v[46:47], v[46:47], v[230:231] op_sel:[0,1] op_sel_hi:[1,1]
	v_pk_mul_f32 v[48:49], v[48:49], v[230:231] op_sel:[0,1] op_sel_hi:[1,1]
	v_pk_mul_f32 v[50:51], v[50:51], v[230:231] op_sel:[0,1] op_sel_hi:[1,1]
	v_pk_fma_f32 v[36:37], v[4:5], v[36:37], v[20:21]
	v_pk_fma_f32 v[38:39], v[6:7], v[38:39], v[22:23]
	v_pk_fma_f32 v[40:41], v[8:9], v[40:41], v[24:25]
	v_pk_fma_f32 v[42:43], v[10:11], v[42:43], v[26:27]
	v_pk_fma_f32 v[44:45], v[12:13], v[44:45], v[28:29]
	v_pk_fma_f32 v[46:47], v[14:15], v[46:47], v[30:31]
	v_pk_fma_f32 v[48:49], v[16:17], v[48:49], v[32:33]
	v_pk_fma_f32 v[50:51], v[18:19], v[50:51], v[34:35]
	v_cvt_pk_bf16_f32 v36, v36, v37
	v_cvt_pk_bf16_f32 v37, v38, v39
	v_cvt_pk_bf16_f32 v38, v40, v41
	v_cvt_pk_bf16_f32 v39, v42, v43
	v_cvt_pk_bf16_f32 v44, v44, v45
	v_cvt_pk_bf16_f32 v45, v46, v47
	v_cvt_pk_bf16_f32 v46, v48, v49
	v_cvt_pk_bf16_f32 v47, v50, v51
	v_lshl_add_u32 v3, s36, 11, v2
	global_store_dwordx4 v3, v[36:39], s[96:97] sc1
	global_store_dwordx4 v3, v[44:47], s[96:97] offset:1024 sc1
	v_pk_add_f32 v[52:53], v[52:53], v[232:233] op_sel_hi:[1,0] neg_lo:[0,1] neg_hi:[0,1]
	v_pk_add_f32 v[54:55], v[54:55], v[232:233] op_sel_hi:[1,0] neg_lo:[0,1] neg_hi:[0,1]
	v_pk_add_f32 v[56:57], v[56:57], v[232:233] op_sel_hi:[1,0] neg_lo:[0,1] neg_hi:[0,1]
	v_pk_add_f32 v[58:59], v[58:59], v[232:233] op_sel_hi:[1,0] neg_lo:[0,1] neg_hi:[0,1]
	v_pk_add_f32 v[60:61], v[60:61], v[232:233] op_sel_hi:[1,0] neg_lo:[0,1] neg_hi:[0,1]
	v_pk_add_f32 v[62:63], v[62:63], v[232:233] op_sel_hi:[1,0] neg_lo:[0,1] neg_hi:[0,1]
	v_pk_add_f32 v[64:65], v[64:65], v[232:233] op_sel_hi:[1,0] neg_lo:[0,1] neg_hi:[0,1]
	v_pk_add_f32 v[66:67], v[66:67], v[232:233] op_sel_hi:[1,0] neg_lo:[0,1] neg_hi:[0,1]
	v_pk_mul_f32 v[52:53], v[52:53], v[232:233] op_sel:[0,1] op_sel_hi:[1,1]
	v_pk_mul_f32 v[54:55], v[54:55], v[232:233] op_sel:[0,1] op_sel_hi:[1,1]
	v_pk_mul_f32 v[56:57], v[56:57], v[232:233] op_sel:[0,1] op_sel_hi:[1,1]
	v_pk_mul_f32 v[58:59], v[58:59], v[232:233] op_sel:[0,1] op_sel_hi:[1,1]
	v_pk_mul_f32 v[60:61], v[60:61], v[232:233] op_sel:[0,1] op_sel_hi:[1,1]
	v_pk_mul_f32 v[62:63], v[62:63], v[232:233] op_sel:[0,1] op_sel_hi:[1,1]
	v_pk_mul_f32 v[64:65], v[64:65], v[232:233] op_sel:[0,1] op_sel_hi:[1,1]
	v_pk_mul_f32 v[66:67], v[66:67], v[232:233] op_sel:[0,1] op_sel_hi:[1,1]
	v_pk_fma_f32 v[52:53], v[4:5], v[52:53], v[20:21]
	v_pk_fma_f32 v[54:55], v[6:7], v[54:55], v[22:23]
	v_pk_fma_f32 v[56:57], v[8:9], v[56:57], v[24:25]
	v_pk_fma_f32 v[58:59], v[10:11], v[58:59], v[26:27]
	v_pk_fma_f32 v[60:61], v[12:13], v[60:61], v[28:29]
	v_pk_fma_f32 v[62:63], v[14:15], v[62:63], v[30:31]
	v_pk_fma_f32 v[64:65], v[16:17], v[64:65], v[32:33]
	v_pk_fma_f32 v[66:67], v[18:19], v[66:67], v[34:35]
	v_cvt_pk_bf16_f32 v52, v52, v53
	v_cvt_pk_bf16_f32 v53, v54, v55
	v_cvt_pk_bf16_f32 v54, v56, v57
	v_cvt_pk_bf16_f32 v55, v58, v59
	v_cvt_pk_bf16_f32 v60, v60, v61
	v_cvt_pk_bf16_f32 v61, v62, v63
	v_cvt_pk_bf16_f32 v62, v64, v65
	v_cvt_pk_bf16_f32 v63, v66, v67
	v_lshl_add_u32 v3, s37, 11, v2
	global_store_dwordx4 v3, v[52:55], s[96:97] sc1
	global_store_dwordx4 v3, v[60:63], s[96:97] offset:1024 sc1
	v_pk_add_f32 v[68:69], v[68:69], v[234:235] op_sel_hi:[1,0] neg_lo:[0,1] neg_hi:[0,1]
	v_pk_add_f32 v[70:71], v[70:71], v[234:235] op_sel_hi:[1,0] neg_lo:[0,1] neg_hi:[0,1]
	v_pk_add_f32 v[72:73], v[72:73], v[234:235] op_sel_hi:[1,0] neg_lo:[0,1] neg_hi:[0,1]
	v_pk_add_f32 v[74:75], v[74:75], v[234:235] op_sel_hi:[1,0] neg_lo:[0,1] neg_hi:[0,1]
	v_pk_add_f32 v[76:77], v[76:77], v[234:235] op_sel_hi:[1,0] neg_lo:[0,1] neg_hi:[0,1]
	v_pk_add_f32 v[78:79], v[78:79], v[234:235] op_sel_hi:[1,0] neg_lo:[0,1] neg_hi:[0,1]
	v_pk_add_f32 v[80:81], v[80:81], v[234:235] op_sel_hi:[1,0] neg_lo:[0,1] neg_hi:[0,1]
	v_pk_add_f32 v[82:83], v[82:83], v[234:235] op_sel_hi:[1,0] neg_lo:[0,1] neg_hi:[0,1]
	v_pk_mul_f32 v[68:69], v[68:69], v[234:235] op_sel:[0,1] op_sel_hi:[1,1]
	v_pk_mul_f32 v[70:71], v[70:71], v[234:235] op_sel:[0,1] op_sel_hi:[1,1]
	v_pk_mul_f32 v[72:73], v[72:73], v[234:235] op_sel:[0,1] op_sel_hi:[1,1]
	v_pk_mul_f32 v[74:75], v[74:75], v[234:235] op_sel:[0,1] op_sel_hi:[1,1]
	v_pk_mul_f32 v[76:77], v[76:77], v[234:235] op_sel:[0,1] op_sel_hi:[1,1]
	v_pk_mul_f32 v[78:79], v[78:79], v[234:235] op_sel:[0,1] op_sel_hi:[1,1]
	v_pk_mul_f32 v[80:81], v[80:81], v[234:235] op_sel:[0,1] op_sel_hi:[1,1]
	v_pk_mul_f32 v[82:83], v[82:83], v[234:235] op_sel:[0,1] op_sel_hi:[1,1]
	v_pk_fma_f32 v[68:69], v[4:5], v[68:69], v[20:21]
	v_pk_fma_f32 v[70:71], v[6:7], v[70:71], v[22:23]
	v_pk_fma_f32 v[72:73], v[8:9], v[72:73], v[24:25]
	v_pk_fma_f32 v[74:75], v[10:11], v[74:75], v[26:27]
	v_pk_fma_f32 v[76:77], v[12:13], v[76:77], v[28:29]
	v_pk_fma_f32 v[78:79], v[14:15], v[78:79], v[30:31]
	v_pk_fma_f32 v[80:81], v[16:17], v[80:81], v[32:33]
	v_pk_fma_f32 v[82:83], v[18:19], v[82:83], v[34:35]
	v_cvt_pk_bf16_f32 v68, v68, v69
	v_cvt_pk_bf16_f32 v69, v70, v71
	v_cvt_pk_bf16_f32 v70, v72, v73
	v_cvt_pk_bf16_f32 v71, v74, v75
	v_cvt_pk_bf16_f32 v76, v76, v77
	v_cvt_pk_bf16_f32 v77, v78, v79
	v_cvt_pk_bf16_f32 v78, v80, v81
	v_cvt_pk_bf16_f32 v79, v82, v83
	v_lshl_add_u32 v3, s38, 11, v2
	global_store_dwordx4 v3, v[68:71], s[96:97] sc1
	global_store_dwordx4 v3, v[76:79], s[96:97] offset:1024 sc1
	v_pk_add_f32 v[84:85], v[84:85], v[236:237] op_sel_hi:[1,0] neg_lo:[0,1] neg_hi:[0,1]
	v_pk_add_f32 v[86:87], v[86:87], v[236:237] op_sel_hi:[1,0] neg_lo:[0,1] neg_hi:[0,1]
	v_pk_add_f32 v[88:89], v[88:89], v[236:237] op_sel_hi:[1,0] neg_lo:[0,1] neg_hi:[0,1]
	v_pk_add_f32 v[90:91], v[90:91], v[236:237] op_sel_hi:[1,0] neg_lo:[0,1] neg_hi:[0,1]
	v_pk_add_f32 v[92:93], v[92:93], v[236:237] op_sel_hi:[1,0] neg_lo:[0,1] neg_hi:[0,1]
	v_pk_add_f32 v[94:95], v[94:95], v[236:237] op_sel_hi:[1,0] neg_lo:[0,1] neg_hi:[0,1]
	v_pk_add_f32 v[96:97], v[96:97], v[236:237] op_sel_hi:[1,0] neg_lo:[0,1] neg_hi:[0,1]
	v_pk_add_f32 v[98:99], v[98:99], v[236:237] op_sel_hi:[1,0] neg_lo:[0,1] neg_hi:[0,1]
	v_pk_mul_f32 v[84:85], v[84:85], v[236:237] op_sel:[0,1] op_sel_hi:[1,1]
	v_pk_mul_f32 v[86:87], v[86:87], v[236:237] op_sel:[0,1] op_sel_hi:[1,1]
	v_pk_mul_f32 v[88:89], v[88:89], v[236:237] op_sel:[0,1] op_sel_hi:[1,1]
	v_pk_mul_f32 v[90:91], v[90:91], v[236:237] op_sel:[0,1] op_sel_hi:[1,1]
	v_pk_mul_f32 v[92:93], v[92:93], v[236:237] op_sel:[0,1] op_sel_hi:[1,1]
	v_pk_mul_f32 v[94:95], v[94:95], v[236:237] op_sel:[0,1] op_sel_hi:[1,1]
	v_pk_mul_f32 v[96:97], v[96:97], v[236:237] op_sel:[0,1] op_sel_hi:[1,1]
	v_pk_mul_f32 v[98:99], v[98:99], v[236:237] op_sel:[0,1] op_sel_hi:[1,1]
	v_pk_fma_f32 v[84:85], v[4:5], v[84:85], v[20:21]
	v_pk_fma_f32 v[86:87], v[6:7], v[86:87], v[22:23]
	v_pk_fma_f32 v[88:89], v[8:9], v[88:89], v[24:25]
	v_pk_fma_f32 v[90:91], v[10:11], v[90:91], v[26:27]
	v_pk_fma_f32 v[92:93], v[12:13], v[92:93], v[28:29]
	v_pk_fma_f32 v[94:95], v[14:15], v[94:95], v[30:31]
	v_pk_fma_f32 v[96:97], v[16:17], v[96:97], v[32:33]
	v_pk_fma_f32 v[98:99], v[18:19], v[98:99], v[34:35]
	v_cvt_pk_bf16_f32 v84, v84, v85
	v_cvt_pk_bf16_f32 v85, v86, v87
	v_cvt_pk_bf16_f32 v86, v88, v89
	v_cvt_pk_bf16_f32 v87, v90, v91
	v_cvt_pk_bf16_f32 v92, v92, v93
	v_cvt_pk_bf16_f32 v93, v94, v95
	v_cvt_pk_bf16_f32 v94, v96, v97
	v_cvt_pk_bf16_f32 v95, v98, v99
	v_lshl_add_u32 v3, s39, 11, v2
	global_store_dwordx4 v3, v[84:87], s[96:97] sc1
	global_store_dwordx4 v3, v[92:95], s[96:97] offset:1024 sc1
	s_mov_b64 s[52:53], exec
	s_mov_b64 exec, 1
	v_mov_b32_e32 v3, s36
	v_lshlrev_b32_e32 v3, 3, v3
	global_store_dwordx2 v3, v[230:231], s[92:93] sc1
	v_mov_b32_e32 v3, s37
	v_lshlrev_b32_e32 v3, 3, v3
	global_store_dwordx2 v3, v[232:233], s[92:93] sc1
	v_mov_b32_e32 v3, s38
	v_lshlrev_b32_e32 v3, 3, v3
	global_store_dwordx2 v3, v[234:235], s[92:93] sc1
	v_mov_b32_e32 v3, s39
	v_lshlrev_b32_e32 v3, 3, v3
	global_store_dwordx2 v3, v[236:237], s[92:93] sc1
	s_mov_b64 exec, s[52:53]
	s_waitcnt vmcnt(12)
	v_pk_add_f32 v[108:109], v[156:157], v[158:159]
	v_pk_add_f32 v[110:111], v[160:161], v[162:163]
	v_pk_add_f32 v[112:113], v[164:165], v[166:167]
	v_pk_add_f32 v[114:115], v[168:169], v[170:171]
	v_pk_mul_f32 v[116:117], v[156:157], v[156:157]
	v_pk_fma_f32 v[116:117], v[158:159], v[158:159], v[116:117]
	v_pk_fma_f32 v[116:117], v[160:161], v[160:161], v[116:117]
	v_pk_fma_f32 v[116:117], v[162:163], v[162:163], v[116:117]
	v_pk_fma_f32 v[116:117], v[164:165], v[164:165], v[116:117]
	v_pk_fma_f32 v[116:117], v[166:167], v[166:167], v[116:117]
	v_pk_fma_f32 v[116:117], v[168:169], v[168:169], v[116:117]
	v_pk_fma_f32 v[116:117], v[170:171], v[170:171], v[116:117]
	v_pk_add_f32 v[108:109], v[108:109], v[110:111]
	v_pk_add_f32 v[112:113], v[112:113], v[114:115]
	v_pk_add_f32 v[108:109], v[108:109], v[112:113]
	v_add_f32_e32 v100, v108, v109
	v_add_f32_e32 v101, v116, v117
	v_pk_add_f32 v[108:109], v[172:173], v[174:175]
	v_pk_add_f32 v[110:111], v[176:177], v[178:179]
	v_pk_add_f32 v[112:113], v[180:181], v[182:183]
	v_pk_add_f32 v[114:115], v[184:185], v[186:187]
	v_pk_mul_f32 v[116:117], v[172:173], v[172:173]
	v_pk_fma_f32 v[116:117], v[174:175], v[174:175], v[116:117]
	v_pk_fma_f32 v[116:117], v[176:177], v[176:177], v[116:117]
	v_pk_fma_f32 v[116:117], v[178:179], v[178:179], v[116:117]
	v_pk_fma_f32 v[116:117], v[180:181], v[180:181], v[116:117]
	v_pk_fma_f32 v[116:117], v[182:183], v[182:183], v[116:117]
	v_pk_fma_f32 v[116:117], v[184:185], v[184:185], v[116:117]
	v_pk_fma_f32 v[116:117], v[186:187], v[186:187], v[116:117]
	v_pk_add_f32 v[108:109], v[108:109], v[110:111]
	v_pk_add_f32 v[112:113], v[112:113], v[114:115]
	v_pk_add_f32 v[108:109], v[108:109], v[112:113]
	v_add_f32_e32 v102, v108, v109
	v_add_f32_e32 v103, v116, v117
	v_pk_add_f32 v[108:109], v[188:189], v[190:191]
	v_pk_add_f32 v[110:111], v[192:193], v[194:195]
	v_pk_add_f32 v[112:113], v[196:197], v[198:199]
	v_pk_add_f32 v[114:115], v[200:201], v[202:203]
	v_pk_mul_f32 v[116:117], v[188:189], v[188:189]
	v_pk_fma_f32 v[116:117], v[190:191], v[190:191], v[116:117]
	v_pk_fma_f32 v[116:117], v[192:193], v[192:193], v[116:117]
	v_pk_fma_f32 v[116:117], v[194:195], v[194:195], v[116:117]
	v_pk_fma_f32 v[116:117], v[196:197], v[196:197], v[116:117]
	v_pk_fma_f32 v[116:117], v[198:199], v[198:199], v[116:117]
	v_pk_fma_f32 v[116:117], v[200:201], v[200:201], v[116:117]
	v_pk_fma_f32 v[116:117], v[202:203], v[202:203], v[116:117]
	v_pk_add_f32 v[108:109], v[108:109], v[110:111]
	v_pk_add_f32 v[112:113], v[112:113], v[114:115]
	v_pk_add_f32 v[108:109], v[108:109], v[112:113]
	v_add_f32_e32 v104, v108, v109
	v_add_f32_e32 v105, v116, v117
	v_pk_add_f32 v[108:109], v[204:205], v[206:207]
	v_pk_add_f32 v[110:111], v[208:209], v[210:211]
	v_pk_add_f32 v[112:113], v[212:213], v[214:215]
	v_pk_add_f32 v[114:115], v[216:217], v[218:219]
	v_pk_mul_f32 v[116:117], v[204:205], v[204:205]
	v_pk_fma_f32 v[116:117], v[206:207], v[206:207], v[116:117]
	v_pk_fma_f32 v[116:117], v[208:209], v[208:209], v[116:117]
	v_pk_fma_f32 v[116:117], v[210:211], v[210:211], v[116:117]
	v_pk_fma_f32 v[116:117], v[212:213], v[212:213], v[116:117]
	v_pk_fma_f32 v[116:117], v[214:215], v[214:215], v[116:117]
	v_pk_fma_f32 v[116:117], v[216:217], v[216:217], v[116:117]
	v_pk_fma_f32 v[116:117], v[218:219], v[218:219], v[116:117]
	v_pk_add_f32 v[108:109], v[108:109], v[110:111]
	v_pk_add_f32 v[112:113], v[112:113], v[114:115]
	v_pk_add_f32 v[108:109], v[108:109], v[112:113]
	v_add_f32_e32 v106, v108, v109
	v_add_f32_e32 v107, v116, v117
	v_add_f32_dpp v100, v100, v100 quad_perm:[1,0,3,2] row_mask:0xf bank_mask:0xf
	v_add_f32_dpp v101, v101, v101 quad_perm:[1,0,3,2] row_mask:0xf bank_mask:0xf
	v_add_f32_dpp v102, v102, v102 quad_perm:[1,0,3,2] row_mask:0xf bank_mask:0xf
	v_add_f32_dpp v103, v103, v103 quad_perm:[1,0,3,2] row_mask:0xf bank_mask:0xf
	v_add_f32_dpp v104, v104, v104 quad_perm:[1,0,3,2] row_mask:0xf bank_mask:0xf
	v_add_f32_dpp v105, v105, v105 quad_perm:[1,0,3,2] row_mask:0xf bank_mask:0xf
	v_add_f32_dpp v106, v106, v106 quad_perm:[1,0,3,2] row_mask:0xf bank_mask:0xf
	v_add_f32_dpp v107, v107, v107 quad_perm:[1,0,3,2] row_mask:0xf bank_mask:0xf
	v_add_f32_dpp v100, v100, v100 quad_perm:[2,3,0,1] row_mask:0xf bank_mask:0xf
	v_add_f32_dpp v101, v101, v101 quad_perm:[2,3,0,1] row_mask:0xf bank_mask:0xf
	v_add_f32_dpp v102, v102, v102 quad_perm:[2,3,0,1] row_mask:0xf bank_mask:0xf
	v_add_f32_dpp v103, v103, v103 quad_perm:[2,3,0,1] row_mask:0xf bank_mask:0xf
	v_add_f32_dpp v104, v104, v104 quad_perm:[2,3,0,1] row_mask:0xf bank_mask:0xf
	v_add_f32_dpp v105, v105, v105 quad_perm:[2,3,0,1] row_mask:0xf bank_mask:0xf
	v_add_f32_dpp v106, v106, v106 quad_perm:[2,3,0,1] row_mask:0xf bank_mask:0xf
	v_add_f32_dpp v107, v107, v107 quad_perm:[2,3,0,1] row_mask:0xf bank_mask:0xf
	v_add_f32_dpp v100, v100, v100 row_half_mirror row_mask:0xf bank_mask:0xf
	v_add_f32_dpp v101, v101, v101 row_half_mirror row_mask:0xf bank_mask:0xf
	v_add_f32_dpp v102, v102, v102 row_half_mirror row_mask:0xf bank_mask:0xf
	v_add_f32_dpp v103, v103, v103 row_half_mirror row_mask:0xf bank_mask:0xf
	v_add_f32_dpp v104, v104, v104 row_half_mirror row_mask:0xf bank_mask:0xf
	v_add_f32_dpp v105, v105, v105 row_half_mirror row_mask:0xf bank_mask:0xf
	v_add_f32_dpp v106, v106, v106 row_half_mirror row_mask:0xf bank_mask:0xf
	v_add_f32_dpp v107, v107, v107 row_half_mirror row_mask:0xf bank_mask:0xf
	v_add_f32_dpp v100, v100, v100 row_mirror row_mask:0xf bank_mask:0xf
	v_add_f32_dpp v101, v101, v101 row_mirror row_mask:0xf bank_mask:0xf
	v_add_f32_dpp v102, v102, v102 row_mirror row_mask:0xf bank_mask:0xf
	v_add_f32_dpp v103, v103, v103 row_mirror row_mask:0xf bank_mask:0xf
	v_add_f32_dpp v104, v104, v104 row_mirror row_mask:0xf bank_mask:0xf
	v_add_f32_dpp v105, v105, v105 row_mirror row_mask:0xf bank_mask:0xf
	v_add_f32_dpp v106, v106, v106 row_mirror row_mask:0xf bank_mask:0xf
	v_add_f32_dpp v107, v107, v107 row_mirror row_mask:0xf bank_mask:0xf
	v_mov_b32_e32 v108, v100
	v_mov_b32_e32 v109, v101
	v_mov_b32_e32 v110, v102
	v_mov_b32_e32 v111, v103
	v_mov_b32_e32 v112, v104
	v_mov_b32_e32 v113, v105
	v_mov_b32_e32 v114, v106
	v_mov_b32_e32 v115, v107
	s_nop 1
	v_permlane16_swap_b32_e32 v108, v100
	v_permlane16_swap_b32_e32 v109, v101
	v_permlane16_swap_b32_e32 v110, v102
	v_permlane16_swap_b32_e32 v111, v103
	v_permlane16_swap_b32_e32 v112, v104
	v_permlane16_swap_b32_e32 v113, v105
	v_permlane16_swap_b32_e32 v114, v106
	v_permlane16_swap_b32_e32 v115, v107
	v_add_f32_e32 v100, v100, v108
	v_add_f32_e32 v101, v101, v109
	v_add_f32_e32 v102, v102, v110
	v_add_f32_e32 v103, v103, v111
	v_add_f32_e32 v104, v104, v112
	v_add_f32_e32 v105, v105, v113
	v_add_f32_e32 v106, v106, v114
	v_add_f32_e32 v107, v107, v115
	v_mov_b32_e32 v108, v100
	v_mov_b32_e32 v109, v101
	v_mov_b32_e32 v110, v102
	v_mov_b32_e32 v111, v103
	v_mov_b32_e32 v112, v104
	v_mov_b32_e32 v113, v105
	v_mov_b32_e32 v114, v106
	v_mov_b32_e32 v115, v107
	s_nop 1
	v_permlane32_swap_b32_e32 v108, v100
	v_permlane32_swap_b32_e32 v109, v101
	v_permlane32_swap_b32_e32 v110, v102
	v_permlane32_swap_b32_e32 v111, v103
	v_permlane32_swap_b32_e32 v112, v104
	v_permlane32_swap_b32_e32 v113, v105
	v_permlane32_swap_b32_e32 v114, v106
	v_permlane32_swap_b32_e32 v115, v107
	v_add_f32_e32 v100, v100, v108
	v_add_f32_e32 v101, v101, v109
	v_add_f32_e32 v102, v102, v110
	v_add_f32_e32 v103, v103, v111
	v_add_f32_e32 v104, v104, v112
	v_add_f32_e32 v105, v105, v113
	v_add_f32_e32 v106, v106, v114
	v_add_f32_e32 v107, v107, v115
	v_mul_f32_e32 v238, 0x3a800000, v100
	v_mul_f32_e32 v116, 0x3a800000, v101
	v_fma_f32 v116, -v238, v238, v116
	v_max_f32_e32 v116, 0, v116
	v_add_f32_e32 v116, 0x3727c5ac, v116
	v_mul_f32_e32 v240, 0x3a800000, v102
	v_mul_f32_e32 v118, 0x3a800000, v103
	v_fma_f32 v118, -v240, v240, v118
	v_max_f32_e32 v118, 0, v118
	v_add_f32_e32 v118, 0x3727c5ac, v118
	v_mul_f32_e32 v242, 0x3a800000, v104
	v_mul_f32_e32 v120, 0x3a800000, v105
	v_fma_f32 v120, -v242, v242, v120
	v_max_f32_e32 v120, 0, v120
	v_add_f32_e32 v120, 0x3727c5ac, v120
	v_mul_f32_e32 v244, 0x3a800000, v106
	v_mul_f32_e32 v122, 0x3a800000, v107
	v_fma_f32 v122, -v244, v244, v122
	v_max_f32_e32 v122, 0, v122
	v_add_f32_e32 v122, 0x3727c5ac, v122
	v_rsq_f32_e32 v117, v116
	v_rsq_f32_e32 v119, v118
	v_rsq_f32_e32 v121, v120
	v_rsq_f32_e32 v123, v122
	s_nop 0
	v_mul_f32_e32 v124, v116, v117
	v_mul_f32_e32 v124, v124, v117
	v_fmaak_f32 v124, -0.5, v124, 0x3fc00000
	v_mul_f32_e32 v239, v117, v124
	v_mul_f32_e32 v125, v118, v119
	v_mul_f32_e32 v125, v125, v119
	v_fmaak_f32 v125, -0.5, v125, 0x3fc00000
	v_mul_f32_e32 v241, v119, v125
	v_mul_f32_e32 v126, v120, v121
	v_mul_f32_e32 v126, v126, v121
	v_fmaak_f32 v126, -0.5, v126, 0x3fc00000
	v_mul_f32_e32 v243, v121, v126
	v_mul_f32_e32 v127, v122, v123
	v_mul_f32_e32 v127, v127, v123
	v_fmaak_f32 v127, -0.5, v127, 0x3fc00000
	v_mul_f32_e32 v245, v123, v127
	v_pk_add_f32 v[156:157], v[156:157], v[238:239] op_sel_hi:[1,0] neg_lo:[0,1] neg_hi:[0,1]
	v_pk_add_f32 v[158:159], v[158:159], v[238:239] op_sel_hi:[1,0] neg_lo:[0,1] neg_hi:[0,1]
	v_pk_add_f32 v[160:161], v[160:161], v[238:239] op_sel_hi:[1,0] neg_lo:[0,1] neg_hi:[0,1]
	v_pk_add_f32 v[162:163], v[162:163], v[238:239] op_sel_hi:[1,0] neg_lo:[0,1] neg_hi:[0,1]
	v_pk_add_f32 v[164:165], v[164:165], v[238:239] op_sel_hi:[1,0] neg_lo:[0,1] neg_hi:[0,1]
	v_pk_add_f32 v[166:167], v[166:167], v[238:239] op_sel_hi:[1,0] neg_lo:[0,1] neg_hi:[0,1]
	v_pk_add_f32 v[168:169], v[168:169], v[238:239] op_sel_hi:[1,0] neg_lo:[0,1] neg_hi:[0,1]
	v_pk_add_f32 v[170:171], v[170:171], v[238:239] op_sel_hi:[1,0] neg_lo:[0,1] neg_hi:[0,1]
	v_pk_mul_f32 v[156:157], v[156:157], v[238:239] op_sel:[0,1] op_sel_hi:[1,1]
	v_pk_mul_f32 v[158:159], v[158:159], v[238:239] op_sel:[0,1] op_sel_hi:[1,1]
	v_pk_mul_f32 v[160:161], v[160:161], v[238:239] op_sel:[0,1] op_sel_hi:[1,1]
	v_pk_mul_f32 v[162:163], v[162:163], v[238:239] op_sel:[0,1] op_sel_hi:[1,1]
	v_pk_mul_f32 v[164:165], v[164:165], v[238:239] op_sel:[0,1] op_sel_hi:[1,1]
	v_pk_mul_f32 v[166:167], v[166:167], v[238:239] op_sel:[0,1] op_sel_hi:[1,1]
	v_pk_mul_f32 v[168:169], v[168:169], v[238:239] op_sel:[0,1] op_sel_hi:[1,1]
	v_pk_mul_f32 v[170:171], v[170:171], v[238:239] op_sel:[0,1] op_sel_hi:[1,1]
	v_pk_fma_f32 v[156:157], v[4:5], v[156:157], v[20:21]
	v_pk_fma_f32 v[158:159], v[6:7], v[158:159], v[22:23]
	v_pk_fma_f32 v[160:161], v[8:9], v[160:161], v[24:25]
	v_pk_fma_f32 v[162:163], v[10:11], v[162:163], v[26:27]
	v_pk_fma_f32 v[164:165], v[12:13], v[164:165], v[28:29]
	v_pk_fma_f32 v[166:167], v[14:15], v[166:167], v[30:31]
	v_pk_fma_f32 v[168:169], v[16:17], v[168:169], v[32:33]
	v_pk_fma_f32 v[170:171], v[18:19], v[170:171], v[34:35]
	v_cvt_pk_bf16_f32 v156, v156, v157
	v_cvt_pk_bf16_f32 v157, v158, v159
	v_cvt_pk_bf16_f32 v158, v160, v161
	v_cvt_pk_bf16_f32 v159, v162, v163
	v_cvt_pk_bf16_f32 v164, v164, v165
	v_cvt_pk_bf16_f32 v165, v166, v167
	v_cvt_pk_bf16_f32 v166, v168, v169
	v_cvt_pk_bf16_f32 v167, v170, v171
	v_lshl_add_u32 v3, s40, 11, v2
	global_store_dwordx4 v3, v[156:159], s[96:97] sc1
	global_store_dwordx4 v3, v[164:167], s[96:97] offset:1024 sc1
	v_pk_add_f32 v[172:173], v[172:173], v[240:241] op_sel_hi:[1,0] neg_lo:[0,1] neg_hi:[0,1]
	v_pk_add_f32 v[174:175], v[174:175], v[240:241] op_sel_hi:[1,0] neg_lo:[0,1] neg_hi:[0,1]
	v_pk_add_f32 v[176:177], v[176:177], v[240:241] op_sel_hi:[1,0] neg_lo:[0,1] neg_hi:[0,1]
	v_pk_add_f32 v[178:179], v[178:179], v[240:241] op_sel_hi:[1,0] neg_lo:[0,1] neg_hi:[0,1]
	v_pk_add_f32 v[180:181], v[180:181], v[240:241] op_sel_hi:[1,0] neg_lo:[0,1] neg_hi:[0,1]
	v_pk_add_f32 v[182:183], v[182:183], v[240:241] op_sel_hi:[1,0] neg_lo:[0,1] neg_hi:[0,1]
	v_pk_add_f32 v[184:185], v[184:185], v[240:241] op_sel_hi:[1,0] neg_lo:[0,1] neg_hi:[0,1]
	v_pk_add_f32 v[186:187], v[186:187], v[240:241] op_sel_hi:[1,0] neg_lo:[0,1] neg_hi:[0,1]
	v_pk_mul_f32 v[172:173], v[172:173], v[240:241] op_sel:[0,1] op_sel_hi:[1,1]
	v_pk_mul_f32 v[174:175], v[174:175], v[240:241] op_sel:[0,1] op_sel_hi:[1,1]
	v_pk_mul_f32 v[176:177], v[176:177], v[240:241] op_sel:[0,1] op_sel_hi:[1,1]
	v_pk_mul_f32 v[178:179], v[178:179], v[240:241] op_sel:[0,1] op_sel_hi:[1,1]
	v_pk_mul_f32 v[180:181], v[180:181], v[240:241] op_sel:[0,1] op_sel_hi:[1,1]
	v_pk_mul_f32 v[182:183], v[182:183], v[240:241] op_sel:[0,1] op_sel_hi:[1,1]
	v_pk_mul_f32 v[184:185], v[184:185], v[240:241] op_sel:[0,1] op_sel_hi:[1,1]
	v_pk_mul_f32 v[186:187], v[186:187], v[240:241] op_sel:[0,1] op_sel_hi:[1,1]
	v_pk_fma_f32 v[172:173], v[4:5], v[172:173], v[20:21]
	v_pk_fma_f32 v[174:175], v[6:7], v[174:175], v[22:23]
	v_pk_fma_f32 v[176:177], v[8:9], v[176:177], v[24:25]
	v_pk_fma_f32 v[178:179], v[10:11], v[178:179], v[26:27]
	v_pk_fma_f32 v[180:181], v[12:13], v[180:181], v[28:29]
	v_pk_fma_f32 v[182:183], v[14:15], v[182:183], v[30:31]
	v_pk_fma_f32 v[184:185], v[16:17], v[184:185], v[32:33]
	v_pk_fma_f32 v[186:187], v[18:19], v[186:187], v[34:35]
	v_cvt_pk_bf16_f32 v172, v172, v173
	v_cvt_pk_bf16_f32 v173, v174, v175
	v_cvt_pk_bf16_f32 v174, v176, v177
	v_cvt_pk_bf16_f32 v175, v178, v179
	v_cvt_pk_bf16_f32 v180, v180, v181
	v_cvt_pk_bf16_f32 v181, v182, v183
	v_cvt_pk_bf16_f32 v182, v184, v185
	v_cvt_pk_bf16_f32 v183, v186, v187
	v_lshl_add_u32 v3, s41, 11, v2
	global_store_dwordx4 v3, v[172:175], s[96:97] sc1
	global_store_dwordx4 v3, v[180:183], s[96:97] offset:1024 sc1
	v_pk_add_f32 v[188:189], v[188:189], v[242:243] op_sel_hi:[1,0] neg_lo:[0,1] neg_hi:[0,1]
	v_pk_add_f32 v[190:191], v[190:191], v[242:243] op_sel_hi:[1,0] neg_lo:[0,1] neg_hi:[0,1]
	v_pk_add_f32 v[192:193], v[192:193], v[242:243] op_sel_hi:[1,0] neg_lo:[0,1] neg_hi:[0,1]
	v_pk_add_f32 v[194:195], v[194:195], v[242:243] op_sel_hi:[1,0] neg_lo:[0,1] neg_hi:[0,1]
	v_pk_add_f32 v[196:197], v[196:197], v[242:243] op_sel_hi:[1,0] neg_lo:[0,1] neg_hi:[0,1]
	v_pk_add_f32 v[198:199], v[198:199], v[242:243] op_sel_hi:[1,0] neg_lo:[0,1] neg_hi:[0,1]
	v_pk_add_f32 v[200:201], v[200:201], v[242:243] op_sel_hi:[1,0] neg_lo:[0,1] neg_hi:[0,1]
	v_pk_add_f32 v[202:203], v[202:203], v[242:243] op_sel_hi:[1,0] neg_lo:[0,1] neg_hi:[0,1]
	v_pk_mul_f32 v[188:189], v[188:189], v[242:243] op_sel:[0,1] op_sel_hi:[1,1]
	v_pk_mul_f32 v[190:191], v[190:191], v[242:243] op_sel:[0,1] op_sel_hi:[1,1]
	v_pk_mul_f32 v[192:193], v[192:193], v[242:243] op_sel:[0,1] op_sel_hi:[1,1]
	v_pk_mul_f32 v[194:195], v[194:195], v[242:243] op_sel:[0,1] op_sel_hi:[1,1]
	v_pk_mul_f32 v[196:197], v[196:197], v[242:243] op_sel:[0,1] op_sel_hi:[1,1]
	v_pk_mul_f32 v[198:199], v[198:199], v[242:243] op_sel:[0,1] op_sel_hi:[1,1]
	v_pk_mul_f32 v[200:201], v[200:201], v[242:243] op_sel:[0,1] op_sel_hi:[1,1]
	v_pk_mul_f32 v[202:203], v[202:203], v[242:243] op_sel:[0,1] op_sel_hi:[1,1]
	v_pk_fma_f32 v[188:189], v[4:5], v[188:189], v[20:21]
	v_pk_fma_f32 v[190:191], v[6:7], v[190:191], v[22:23]
	v_pk_fma_f32 v[192:193], v[8:9], v[192:193], v[24:25]
	v_pk_fma_f32 v[194:195], v[10:11], v[194:195], v[26:27]
	v_pk_fma_f32 v[196:197], v[12:13], v[196:197], v[28:29]
	v_pk_fma_f32 v[198:199], v[14:15], v[198:199], v[30:31]
	v_pk_fma_f32 v[200:201], v[16:17], v[200:201], v[32:33]
	v_pk_fma_f32 v[202:203], v[18:19], v[202:203], v[34:35]
	v_cvt_pk_bf16_f32 v188, v188, v189
	v_cvt_pk_bf16_f32 v189, v190, v191
	v_cvt_pk_bf16_f32 v190, v192, v193
	v_cvt_pk_bf16_f32 v191, v194, v195
	v_cvt_pk_bf16_f32 v196, v196, v197
	v_cvt_pk_bf16_f32 v197, v198, v199
	v_cvt_pk_bf16_f32 v198, v200, v201
	v_cvt_pk_bf16_f32 v199, v202, v203
	v_lshl_add_u32 v3, s42, 11, v2
	global_store_dwordx4 v3, v[188:191], s[96:97] sc1
	global_store_dwordx4 v3, v[196:199], s[96:97] offset:1024 sc1
	v_pk_add_f32 v[204:205], v[204:205], v[244:245] op_sel_hi:[1,0] neg_lo:[0,1] neg_hi:[0,1]
	v_pk_add_f32 v[206:207], v[206:207], v[244:245] op_sel_hi:[1,0] neg_lo:[0,1] neg_hi:[0,1]
	v_pk_add_f32 v[208:209], v[208:209], v[244:245] op_sel_hi:[1,0] neg_lo:[0,1] neg_hi:[0,1]
	v_pk_add_f32 v[210:211], v[210:211], v[244:245] op_sel_hi:[1,0] neg_lo:[0,1] neg_hi:[0,1]
	v_pk_add_f32 v[212:213], v[212:213], v[244:245] op_sel_hi:[1,0] neg_lo:[0,1] neg_hi:[0,1]
	v_pk_add_f32 v[214:215], v[214:215], v[244:245] op_sel_hi:[1,0] neg_lo:[0,1] neg_hi:[0,1]
	v_pk_add_f32 v[216:217], v[216:217], v[244:245] op_sel_hi:[1,0] neg_lo:[0,1] neg_hi:[0,1]
	v_pk_add_f32 v[218:219], v[218:219], v[244:245] op_sel_hi:[1,0] neg_lo:[0,1] neg_hi:[0,1]
	v_pk_mul_f32 v[204:205], v[204:205], v[244:245] op_sel:[0,1] op_sel_hi:[1,1]
	v_pk_mul_f32 v[206:207], v[206:207], v[244:245] op_sel:[0,1] op_sel_hi:[1,1]
	v_pk_mul_f32 v[208:209], v[208:209], v[244:245] op_sel:[0,1] op_sel_hi:[1,1]
	v_pk_mul_f32 v[210:211], v[210:211], v[244:245] op_sel:[0,1] op_sel_hi:[1,1]
	v_pk_mul_f32 v[212:213], v[212:213], v[244:245] op_sel:[0,1] op_sel_hi:[1,1]
	v_pk_mul_f32 v[214:215], v[214:215], v[244:245] op_sel:[0,1] op_sel_hi:[1,1]
	v_pk_mul_f32 v[216:217], v[216:217], v[244:245] op_sel:[0,1] op_sel_hi:[1,1]
	v_pk_mul_f32 v[218:219], v[218:219], v[244:245] op_sel:[0,1] op_sel_hi:[1,1]
	v_pk_fma_f32 v[204:205], v[4:5], v[204:205], v[20:21]
	v_pk_fma_f32 v[206:207], v[6:7], v[206:207], v[22:23]
	v_pk_fma_f32 v[208:209], v[8:9], v[208:209], v[24:25]
	v_pk_fma_f32 v[210:211], v[10:11], v[210:211], v[26:27]
	v_pk_fma_f32 v[212:213], v[12:13], v[212:213], v[28:29]
	v_pk_fma_f32 v[214:215], v[14:15], v[214:215], v[30:31]
	v_pk_fma_f32 v[216:217], v[16:17], v[216:217], v[32:33]
	v_pk_fma_f32 v[218:219], v[18:19], v[218:219], v[34:35]
	v_cvt_pk_bf16_f32 v204, v204, v205
	v_cvt_pk_bf16_f32 v205, v206, v207
	v_cvt_pk_bf16_f32 v206, v208, v209
	v_cvt_pk_bf16_f32 v207, v210, v211
	v_cvt_pk_bf16_f32 v212, v212, v213
	v_cvt_pk_bf16_f32 v213, v214, v215
	v_cvt_pk_bf16_f32 v214, v216, v217
	v_cvt_pk_bf16_f32 v215, v218, v219
	v_lshl_add_u32 v3, s43, 11, v2
	global_store_dwordx4 v3, v[204:207], s[96:97] sc1
	global_store_dwordx4 v3, v[212:215], s[96:97] offset:1024 sc1
	s_mov_b64 s[52:53], exec
	s_mov_b64 exec, 1
	v_mov_b32_e32 v3, s40
	v_lshlrev_b32_e32 v3, 3, v3
	global_store_dwordx2 v3, v[238:239], s[92:93] sc1
	v_mov_b32_e32 v3, s41
	v_lshlrev_b32_e32 v3, 3, v3
	global_store_dwordx2 v3, v[240:241], s[92:93] sc1
	v_mov_b32_e32 v3, s42
	v_lshlrev_b32_e32 v3, 3, v3
	global_store_dwordx2 v3, v[242:243], s[92:93] sc1
	v_mov_b32_e32 v3, s43
	v_lshlrev_b32_e32 v3, 3, v3
	global_store_dwordx2 v3, v[244:245], s[92:93] sc1
	s_mov_b64 exec, s[52:53]
	s_cmp_gt_u32 s46, 15
	s_cbranch_scc1 .Lln2_done
	v_lshl_add_u32 v128, s46, 12, v1
	global_load_dwordx4 v[36:39], v128, s[30:31]
	global_load_dwordx4 v[40:43], v128, s[30:31] offset:16
	global_load_dwordx4 v[44:47], v128, s[30:31] offset:2048
	global_load_dwordx4 v[48:51], v128, s[30:31] offset:2064
	s_add_u32 s36, s46, 0x8000
	s_waitcnt vmcnt(0)
	v_pk_add_f32 v[108:109], v[36:37], v[38:39]
	v_pk_add_f32 v[110:111], v[40:41], v[42:43]
	v_pk_add_f32 v[112:113], v[44:45], v[46:47]
	v_pk_add_f32 v[114:115], v[48:49], v[50:51]
	v_pk_mul_f32 v[116:117], v[36:37], v[36:37]
	v_pk_fma_f32 v[116:117], v[38:39], v[38:39], v[116:117]
	v_pk_fma_f32 v[116:117], v[40:41], v[40:41], v[116:117]
	v_pk_fma_f32 v[116:117], v[42:43], v[42:43], v[116:117]
	v_pk_fma_f32 v[116:117], v[44:45], v[44:45], v[116:117]
	v_pk_fma_f32 v[116:117], v[46:47], v[46:47], v[116:117]
	v_pk_fma_f32 v[116:117], v[48:49], v[48:49], v[116:117]
	v_pk_fma_f32 v[116:117], v[50:51], v[50:51], v[116:117]
	v_pk_add_f32 v[108:109], v[108:109], v[110:111]
	v_pk_add_f32 v[112:113], v[112:113], v[114:115]
	v_pk_add_f32 v[108:109], v[108:109], v[112:113]
	v_add_f32_e32 v100, v108, v109
	v_add_f32_e32 v101, v116, v117
	s_nop 1
	v_add_f32_dpp v100, v100, v100 quad_perm:[1,0,3,2] row_mask:0xf bank_mask:0xf
	v_add_f32_dpp v101, v101, v101 quad_perm:[1,0,3,2] row_mask:0xf bank_mask:0xf
	s_nop 1
	v_add_f32_dpp v100, v100, v100 quad_perm:[2,3,0,1] row_mask:0xf bank_mask:0xf
	v_add_f32_dpp v101, v101, v101 quad_perm:[2,3,0,1] row_mask:0xf bank_mask:0xf
	s_nop 1
	v_add_f32_dpp v100, v100, v100 row_half_mirror row_mask:0xf bank_mask:0xf
	v_add_f32_dpp v101, v101, v101 row_half_mirror row_mask:0xf bank_mask:0xf
	s_nop 1
	v_add_f32_dpp v100, v100, v100 row_mirror row_mask:0xf bank_mask:0xf
	v_add_f32_dpp v101, v101, v101 row_mirror row_mask:0xf bank_mask:0xf
	s_nop 1
	v_mov_b32_e32 v108, v100
	v_mov_b32_e32 v109, v101
	s_nop 1
	v_permlane16_swap_b32_e32 v108, v100
	v_permlane16_swap_b32_e32 v109, v101
	v_add_f32_e32 v100, v100, v108
	v_add_f32_e32 v101, v101, v109
	v_mov_b32_e32 v108, v100
	v_mov_b32_e32 v109, v101
	s_nop 1
	v_permlane32_swap_b32_e32 v108, v100
	v_permlane32_swap_b32_e32 v109, v101
	v_add_f32_e32 v100, v100, v108
	v_add_f32_e32 v101, v101, v109
	v_mul_f32_e32 v230, 0x3a800000, v100
	v_mul_f32_e32 v116, 0x3a800000, v101
	v_fma_f32 v116, -v230, v230, v116
	v_max_f32_e32 v116, 0, v116
	v_add_f32_e32 v116, 0x3727c5ac, v116
	v_rsq_f32_e32 v117, v116
	s_nop 0
	v_mul_f32_e32 v124, v116, v117
	v_mul_f32_e32 v124, v124, v117
	v_fmaak_f32 v124, -0.5, v124, 0x3fc00000
	v_mul_f32_e32 v231, v117, v124
	v_pk_add_f32 v[36:37], v[36:37], v[230:231] op_sel_hi:[1,0] neg_lo:[0,1] neg_hi:[0,1]
	v_pk_add_f32 v[38:39], v[38:39], v[230:231] op_sel_hi:[1,0] neg_lo:[0,1] neg_hi:[0,1]
	v_pk_add_f32 v[40:41], v[40:41], v[230:231] op_sel_hi:[1,0] neg_lo:[0,1] neg_hi:[0,1]
	v_pk_add_f32 v[42:43], v[42:43], v[230:231] op_sel_hi:[1,0] neg_lo:[0,1] neg_hi:[0,1]
	v_pk_add_f32 v[44:45], v[44:45], v[230:231] op_sel_hi:[1,0] neg_lo:[0,1] neg_hi:[0,1]
	v_pk_add_f32 v[46:47], v[46:47], v[230:231] op_sel_hi:[1,0] neg_lo:[0,1] neg_hi:[0,1]
	v_pk_add_f32 v[48:49], v[48:49], v[230:231] op_sel_hi:[1,0] neg_lo:[0,1] neg_hi:[0,1]
	v_pk_add_f32 v[50:51], v[50:51], v[230:231] op_sel_hi:[1,0] neg_lo:[0,1] neg_hi:[0,1]
	v_pk_mul_f32 v[36:37], v[36:37], v[230:231] op_sel:[0,1] op_sel_hi:[1,1]
	v_pk_mul_f32 v[38:39], v[38:39], v[230:231] op_sel:[0,1] op_sel_hi:[1,1]
	v_pk_mul_f32 v[40:41], v[40:41], v[230:231] op_sel:[0,1] op_sel_hi:[1,1]
	v_pk_mul_f32 v[42:43], v[42:43], v[230:231] op_sel:[0,1] op_sel_hi:[1,1]
	v_pk_mul_f32 v[44:45], v[44:45], v[230:231] op_sel:[0,1] op_sel_hi:[1,1]
	v_pk_mul_f32 v[46:47], v[46:47], v[230:231] op_sel:[0,1] op_sel_hi:[1,1]
	v_pk_mul_f32 v[48:49], v[48:49], v[230:231] op_sel:[0,1] op_sel_hi:[1,1]
	v_pk_mul_f32 v[50:51], v[50:51], v[230:231] op_sel:[0,1] op_sel_hi:[1,1]
	v_pk_fma_f32 v[36:37], v[4:5], v[36:37], v[20:21]
	v_pk_fma_f32 v[38:39], v[6:7], v[38:39], v[22:23]
	v_pk_fma_f32 v[40:41], v[8:9], v[40:41], v[24:25]
	v_pk_fma_f32 v[42:43], v[10:11], v[42:43], v[26:27]
	v_pk_fma_f32 v[44:45], v[12:13], v[44:45], v[28:29]
	v_pk_fma_f32 v[46:47], v[14:15], v[46:47], v[30:31]
	v_pk_fma_f32 v[48:49], v[16:17], v[48:49], v[32:33]
	v_pk_fma_f32 v[50:51], v[18:19], v[50:51], v[34:35]
	v_cvt_pk_bf16_f32 v36, v36, v37
	v_cvt_pk_bf16_f32 v37, v38, v39
	v_cvt_pk_bf16_f32 v38, v40, v41
	v_cvt_pk_bf16_f32 v39, v42, v43
	v_cvt_pk_bf16_f32 v44, v44, v45
	v_cvt_pk_bf16_f32 v45, v46, v47
	v_cvt_pk_bf16_f32 v46, v48, v49
	v_cvt_pk_bf16_f32 v47, v50, v51
	v_lshl_add_u32 v3, s36, 11, v2
	global_store_dwordx4 v3, v[36:39], s[96:97] sc1
	global_store_dwordx4 v3, v[44:47], s[96:97] offset:1024 sc1
	s_mov_b64 s[52:53], exec
	s_mov_b64 exec, 1
	v_mov_b32_e32 v3, s36
	v_lshlrev_b32_e32 v3, 3, v3
	global_store_dwordx2 v3, v[230:231], s[92:93] sc1
	s_mov_b64 exec, s[52:53]
